# accumulate-chain MFMA order + snake through the 4x4 accumulator grid with alternate pairs issuing k1 before k0, so MFMAs across a pair boundary share one operand register (f32 summation order of those
# speedup vs baseline: 1.0293x; 1.0153x over previous
; #define PG8_STAGE(bufoff, gbase, voff) do { _Pragma("unroll") for (int _i = 0; _i < 2; ++_i) \
;         __builtin_amdgcn_global_load_lds((const unsigned*)((const char*)(gbase) + (voff)[_i]), (PG8_LAS unsigned*)(lds + (bufoff) + ldsw + _i * 8192), 16, 0, 0); } while (0)
; #define PG8_LDA(dst, b, h) do { _Pragma("unroll") for (int m = 0; m < 4; ++m) _Pragma("unroll") for (int k = 0; k < 2; ++k) dst[m][k] = *(const PG8_LAS bf16x8*)(lds + PG8_SA(b, h) + aoff + m * 2048 + k * 1024); } while (0)
; #define PG8_LDB(dst, b, h) do { _Pragma("unroll") for (int n = 0; n < 2; ++n) _Pragma("unroll") for (int k = 0; k < 2; ++k) dst[n][k] = *(const PG8_LAS bf16x8*)(lds + PG8_SB(b, h) + boff + n * 2048 + k * 1024); } while (0)
; #define PG8_MMA(ai, bj, At, Bt) do { __builtin_amdgcn_s_setprio(1); _Pragma("unroll") for (int m = 0; m < 4; ++m) _Pragma("unroll") for (int n = 0; n < 2; ++n) _Pragma("unroll") for (int k = 0; k < 2; ++k) \
;         acc[ai][bj][m][n] = __builtin_amdgcn_mfma_f32_16x16x32_bf16(Bt[n][k], At[m][k], acc[ai][bj][m][n], 0, 0, 0); __builtin_amdgcn_s_setprio(0); } while (0)
; #define PG8_WAIT_V(n) asm volatile("s_waitcnt vmcnt(" #n ")" ::: "memory")
; #define PG8_BAR __builtin_amdgcn_s_barrier()
; template <class Epi, class Sched, bool ALIGN_EPI = false, bool SP2 = false>
; __device__ __forceinline__ void gemm_phase(PG8_LAS unsigned char* lds, const Gemm g, const Sched& S, const Epi& E) {
;     ...
;         for (int t = 0; t < nt; t += 2) {
;             const bool last = (t == nt - 2);
;             const char* a1 = cA + (size_t)(t + 1) * kstep;
;             const char* a2 = last ? nA : cA + (size_t)(t + 2) * kstep; const char* b2 = last ? nB : cB + (size_t)(t + 2) * kstep;
;             const char* a3 = a2 + kstep; const char* b3 = b2 + kstep;
;             if (last && has_next) S.a_ready(nxt);
;             if constexpr (SP2) {
;             PG8_LDB(B0, 0, 0); PG8_LDB(B1, 0, 1); PG8_SCHED; PG8_LDA(At, 0, 0); PG8_STAGE(PG8_SA(1, 1), a1 + hstep, voffA);
;             PG8_WAIT_V(8); PG8_WAIT_L(0); PG8_BAR; PG8_MMA(0, 0, At, B0); PG8_MMA(0, 1, At, B1); PG8_BAR; PG8_SCHED;
;             PG8_LDA(At, 0, 1); PG8_STAGE(PG8_SB(0, 0), b2, voffB); PG8_STAGE(PG8_SB(0, 1), b2 + hstep, voffB); PG8_STAGE(PG8_SA(0, 0), a2, voffA);
;             PG8_WAIT_V(8); PG8_WAIT_L(0); PG8_BAR; PG8_MMA(1, 0, At, B0); PG8_MMA(1, 1, At, B1); PG8_BAR; PG8_SCHED;
.LBB0_673:
	ds_read_b128 v[148:151], v241 offset:0
	ds_read_b128 v[156:159], v241 offset:1024
	ds_read_b128 v[166:169], v241 offset:2048
	ds_read_b128 v[170:173], v241 offset:3072
	ds_read_b128 v[174:177], v241 offset:16384
	ds_read_b128 v[178:181], v241 offset:17408
	ds_read_b128 v[182:185], v241 offset:18432
	ds_read_b128 v[186:189], v241 offset:19456
	s_add_u32 s20, s22, 0xfff00080
	s_addc_u32 s21, s23, -1
	s_cmp_eq_u32 s35, 60
	s_cselect_b32 s25, s11, s21
	s_cselect_b32 s24, s52, s20
	s_cselect_b32 s21, s13, s34
	s_cselect_b32 s20, s53, s62
	s_add_i32 m0, s19, 0xc000
	ds_read_b128 v[190:193], v161
	ds_read_b128 v[194:197], v161 offset:1024
	ds_read_b128 v[198:201], v161 offset:2048
	ds_read_b128 v[202:205], v161 offset:3072
	ds_read_b128 v[206:209], v161 offset:4096
	ds_read_b128 v[210:213], v161 offset:5120
	ds_read_b128 v[214:217], v161 offset:6144
	ds_read_b128 v[218:221], v161 offset:7168
	global_load_lds_dwordx4 v138, s[22:23]
	s_add_i32 m0, s19, 0xe000
	s_nop 0
	global_load_lds_dwordx4 v140, s[22:23]
	s_waitcnt vmcnt(8)
	s_waitcnt lgkmcnt(0)
	s_barrier
	s_waitcnt lgkmcnt(0)
	v_mfma_f32_16x16x32_bf16 v[118:121], v[148:151], v[190:193], v[118:121]
	v_mfma_f32_16x16x32_bf16 v[118:121], v[156:159], v[194:197], v[118:121]
	v_mfma_f32_16x16x32_bf16 v[102:105], v[156:159], v[202:205], v[102:105]
	v_mfma_f32_16x16x32_bf16 v[102:105], v[148:151], v[198:201], v[102:105]
	v_mfma_f32_16x16x32_bf16 v[86:89], v[148:151], v[206:209], v[86:89]
	v_mfma_f32_16x16x32_bf16 v[86:89], v[156:159], v[210:213], v[86:89]
	v_mfma_f32_16x16x32_bf16 v[70:73], v[156:159], v[218:221], v[70:73]
	v_mfma_f32_16x16x32_bf16 v[70:73], v[148:151], v[214:217], v[70:73]
	v_mfma_f32_16x16x32_bf16 v[66:69], v[166:169], v[214:217], v[66:69]
	v_mfma_f32_16x16x32_bf16 v[66:69], v[170:173], v[218:221], v[66:69]
	v_mfma_f32_16x16x32_bf16 v[82:85], v[170:173], v[210:213], v[82:85]
	v_mfma_f32_16x16x32_bf16 v[82:85], v[166:169], v[206:209], v[82:85]
	v_mfma_f32_16x16x32_bf16 v[98:101], v[166:169], v[198:201], v[98:101]
	v_mfma_f32_16x16x32_bf16 v[98:101], v[170:173], v[202:205], v[98:101]
	v_mfma_f32_16x16x32_bf16 v[114:117], v[170:173], v[194:197], v[114:117]
	v_mfma_f32_16x16x32_bf16 v[114:117], v[166:169], v[190:193], v[114:117]
	v_mfma_f32_16x16x32_bf16 v[126:129], v[174:177], v[190:193], v[126:129]
	v_mfma_f32_16x16x32_bf16 v[126:129], v[178:181], v[194:197], v[126:129]
	v_mfma_f32_16x16x32_bf16 v[110:113], v[178:181], v[202:205], v[110:113]
	v_mfma_f32_16x16x32_bf16 v[110:113], v[174:177], v[198:201], v[110:113]
	v_mfma_f32_16x16x32_bf16 v[94:97], v[174:177], v[206:209], v[94:97]
	v_mfma_f32_16x16x32_bf16 v[94:97], v[178:181], v[210:213], v[94:97]
	v_mfma_f32_16x16x32_bf16 v[78:81], v[178:181], v[218:221], v[78:81]
	v_mfma_f32_16x16x32_bf16 v[78:81], v[174:177], v[214:217], v[78:81]
	v_mfma_f32_16x16x32_bf16 v[74:77], v[182:185], v[214:217], v[74:77]
	v_mfma_f32_16x16x32_bf16 v[74:77], v[186:189], v[218:221], v[74:77]
	v_mfma_f32_16x16x32_bf16 v[90:93], v[186:189], v[210:213], v[90:93]
	v_mfma_f32_16x16x32_bf16 v[90:93], v[182:185], v[206:209], v[90:93]
	v_mfma_f32_16x16x32_bf16 v[106:109], v[182:185], v[198:201], v[106:109]
	v_mfma_f32_16x16x32_bf16 v[106:109], v[186:189], v[202:205], v[106:109]
	v_mfma_f32_16x16x32_bf16 v[122:125], v[186:189], v[194:197], v[122:125]
	v_mfma_f32_16x16x32_bf16 v[122:125], v[182:185], v[190:193], v[122:125]
	s_barrier
	s_add_i32 s63, s43, s26
	s_mov_b32 m0, s63
	ds_read_b128 v[190:193], v161 offset:16384
	ds_read_b128 v[194:197], v161 offset:17408
	ds_read_b128 v[198:201], v161 offset:18432
	ds_read_b128 v[202:205], v161 offset:19456
	ds_read_b128 v[206:209], v161 offset:20480
	ds_read_b128 v[210:213], v161 offset:21504
	ds_read_b128 v[214:217], v161 offset:22528
	ds_read_b128 v[218:221], v161 offset:23552
	global_load_lds_dwordx4 v132, s[20:21]
	s_add_i32 m0, s63, 0x2000
	s_add_u32 s64, s20, 0x100000
	s_addc_u32 s65, s21, 0
	s_add_i32 s63, s46, s26
	global_load_lds_dwordx4 v136, s[20:21]
	s_mov_b32 m0, s63
	s_add_u32 s100, s24, 0x80
	s_addc_u32 s101, s25, 0
	global_load_lds_dwordx4 v132, s[64:65]
	s_add_i32 m0, s63, 0x2000
	s_nop 0
	global_load_lds_dwordx4 v136, s[64:65]
	s_mov_b32 m0, s19
	s_nop 0
	global_load_lds_dwordx4 v130, s[24:25]
	s_mov_b32 m0, s29
	s_nop 0
	global_load_lds_dwordx4 v134, s[24:25]
	s_waitcnt vmcnt(8)
	s_waitcnt lgkmcnt(0)
	s_barrier
	s_waitcnt lgkmcnt(0)
	v_mfma_f32_16x16x32_bf16 v[54:57], v[148:151], v[190:193], v[54:57]
	v_mfma_f32_16x16x32_bf16 v[54:57], v[156:159], v[194:197], v[54:57]
	v_mfma_f32_16x16x32_bf16 v[38:41], v[156:159], v[202:205], v[38:41]
	v_mfma_f32_16x16x32_bf16 v[38:41], v[148:151], v[198:201], v[38:41]
	v_mfma_f32_16x16x32_bf16 v[22:25], v[148:151], v[206:209], v[22:25]
	v_mfma_f32_16x16x32_bf16 v[22:25], v[156:159], v[210:213], v[22:25]
	v_mfma_f32_16x16x32_bf16 v[6:9], v[156:159], v[218:221], v[6:9]
	v_mfma_f32_16x16x32_bf16 v[6:9], v[148:151], v[214:217], v[6:9]
	v_mfma_f32_16x16x32_bf16 v[2:5], v[166:169], v[214:217], v[2:5]
	v_mfma_f32_16x16x32_bf16 v[2:5], v[170:173], v[218:221], v[2:5]
	v_mfma_f32_16x16x32_bf16 v[18:21], v[170:173], v[210:213], v[18:21]
	v_mfma_f32_16x16x32_bf16 v[18:21], v[166:169], v[206:209], v[18:21]
	v_mfma_f32_16x16x32_bf16 v[34:37], v[166:169], v[198:201], v[34:37]
	v_mfma_f32_16x16x32_bf16 v[34:37], v[170:173], v[202:205], v[34:37]
	v_mfma_f32_16x16x32_bf16 v[50:53], v[170:173], v[194:197], v[50:53]
	v_mfma_f32_16x16x32_bf16 v[50:53], v[166:169], v[190:193], v[50:53]
	v_mfma_f32_16x16x32_bf16 v[62:65], v[174:177], v[190:193], v[62:65]
	v_mfma_f32_16x16x32_bf16 v[62:65], v[178:181], v[194:197], v[62:65]
	v_mfma_f32_16x16x32_bf16 v[46:49], v[178:181], v[202:205], v[46:49]
	v_mfma_f32_16x16x32_bf16 v[46:49], v[174:177], v[198:201], v[46:49]
	v_mfma_f32_16x16x32_bf16 v[30:33], v[174:177], v[206:209], v[30:33]
	v_mfma_f32_16x16x32_bf16 v[30:33], v[178:181], v[210:213], v[30:33]
	v_mfma_f32_16x16x32_bf16 v[10:13], v[178:181], v[218:221], v[10:13]
	v_mfma_f32_16x16x32_bf16 v[10:13], v[174:177], v[214:217], v[10:13]
	v_mfma_f32_16x16x32_bf16 v[14:17], v[182:185], v[214:217], v[14:17]
	v_mfma_f32_16x16x32_bf16 v[14:17], v[186:189], v[218:221], v[14:17]
	v_mfma_f32_16x16x32_bf16 v[26:29], v[186:189], v[210:213], v[26:29]
	v_mfma_f32_16x16x32_bf16 v[26:29], v[182:185], v[206:209], v[26:29]
	v_mfma_f32_16x16x32_bf16 v[42:45], v[182:185], v[198:201], v[42:45]
	v_mfma_f32_16x16x32_bf16 v[42:45], v[186:189], v[202:205], v[42:45]
	v_mfma_f32_16x16x32_bf16 v[58:61], v[186:189], v[194:197], v[58:61]
	v_mfma_f32_16x16x32_bf16 v[58:61], v[182:185], v[190:193], v[58:61]
	s_barrier
; #define PG8_STAGE(bufoff, gbase, voff) do { _Pragma("unroll") for (int _i = 0; _i < 2; ++_i) \
;         __builtin_amdgcn_global_load_lds((const unsigned*)((const char*)(gbase) + (voff)[_i]), (PG8_LAS unsigned*)(lds + (bufoff) + ldsw + _i * 8192), 16, 0, 0); } while (0)
; #define PG8_LDA(dst, b, h) do { _Pragma("unroll") for (int m = 0; m < 4; ++m) _Pragma("unroll") for (int k = 0; k < 2; ++k) dst[m][k] = *(const PG8_LAS bf16x8*)(lds + PG8_SA(b, h) + aoff + m * 2048 + k * 1024); } while (0)
; #define PG8_LDB(dst, b, h) do { _Pragma("unroll") for (int n = 0; n < 2; ++n) _Pragma("unroll") for (int k = 0; k < 2; ++k) dst[n][k] = *(const PG8_LAS bf16x8*)(lds + PG8_SB(b, h) + boff + n * 2048 + k * 1024); } while (0)
; #define PG8_MMA(ai, bj, At, Bt) do { __builtin_amdgcn_s_setprio(1); _Pragma("unroll") for (int m = 0; m < 4; ++m) _Pragma("unroll") for (int n = 0; n < 2; ++n) _Pragma("unroll") for (int k = 0; k < 2; ++k) \
;         acc[ai][bj][m][n] = __builtin_amdgcn_mfma_f32_16x16x32_bf16(Bt[n][k], At[m][k], acc[ai][bj][m][n], 0, 0, 0); __builtin_amdgcn_s_setprio(0); } while (0)
; #define PG8_WAIT_V(n) asm volatile("s_waitcnt vmcnt(" #n ")" ::: "memory")
; #define PG8_WAIT_L(n) asm volatile("s_waitcnt lgkmcnt(" #n ")" ::: "memory")
; #define PG8_BAR __builtin_amdgcn_s_barrier()
; #define PG8_SCHED __builtin_amdgcn_sched_barrier(0)
; template <class Epi, class Sched, bool ALIGN_EPI = false, bool SP2 = false>
; __device__ __forceinline__ void gemm_phase(PG8_LAS unsigned char* lds, const Gemm g, const Sched& S, const Epi& E) {
;     ...
;             PG8_LDB(B0, 1, 0); PG8_LDB(B1, 1, 1); PG8_SCHED; PG8_LDA(At, 1, 0); PG8_STAGE(PG8_SA(0, 1), a2 + hstep, voffA);
;             PG8_WAIT_V(8); PG8_WAIT_L(0); PG8_BAR; PG8_MMA(0, 0, At, B0); PG8_MMA(0, 1, At, B1); PG8_BAR; PG8_SCHED;
;             PG8_LDA(At, 1, 1); PG8_STAGE(PG8_SB(1, 0), b3, voffB); PG8_STAGE(PG8_SB(1, 1), b3 + hstep, voffB); PG8_STAGE(PG8_SA(1, 0), a3, voffA);
;             PG8_WAIT_V(8); PG8_WAIT_L(0); PG8_BAR; PG8_MMA(1, 0, At, B0); PG8_MMA(1, 1, At, B1); PG8_BAR; PG8_SCHED;
	s_add_i32 s63, 0, 0x18000
	s_add_i32 s64, 0, 0x1c000
	ds_read_b128 v[148:151], v241 offset:32768
	ds_read_b128 v[156:159], v241 offset:33792
	ds_read_b128 v[166:169], v241 offset:34816
	ds_read_b128 v[170:173], v241 offset:35840
	ds_read_b128 v[174:177], v241 offset:49152
	ds_read_b128 v[178:181], v241 offset:50176
	ds_read_b128 v[182:185], v241 offset:51200
	ds_read_b128 v[186:189], v241 offset:52224
	s_add_u32 s24, s24, 0x100000
	s_addc_u32 s25, s25, 0
	s_mov_b32 m0, s30
	ds_read_b128 v[190:193], v161 offset:32768
	ds_read_b128 v[194:197], v161 offset:33792
	ds_read_b128 v[198:201], v161 offset:34816
	ds_read_b128 v[202:205], v161 offset:35840
	ds_read_b128 v[206:209], v161 offset:36864
	ds_read_b128 v[210:213], v161 offset:37888
	ds_read_b128 v[214:217], v161 offset:38912
	ds_read_b128 v[218:221], v161 offset:39936
	global_load_lds_dwordx4 v130, s[24:25]
	s_mov_b32 m0, s31
	s_nop 0
	global_load_lds_dwordx4 v134, s[24:25]
	s_waitcnt vmcnt(8)
	s_waitcnt lgkmcnt(0)
	s_barrier
	s_waitcnt lgkmcnt(0)
	v_mfma_f32_16x16x32_bf16 v[118:121], v[148:151], v[190:193], v[118:121]
	v_mfma_f32_16x16x32_bf16 v[118:121], v[156:159], v[194:197], v[118:121]
	v_mfma_f32_16x16x32_bf16 v[102:105], v[156:159], v[202:205], v[102:105]
	v_mfma_f32_16x16x32_bf16 v[102:105], v[148:151], v[198:201], v[102:105]
	v_mfma_f32_16x16x32_bf16 v[86:89], v[148:151], v[206:209], v[86:89]
	v_mfma_f32_16x16x32_bf16 v[86:89], v[156:159], v[210:213], v[86:89]
	v_mfma_f32_16x16x32_bf16 v[70:73], v[156:159], v[218:221], v[70:73]
	v_mfma_f32_16x16x32_bf16 v[70:73], v[148:151], v[214:217], v[70:73]
	v_mfma_f32_16x16x32_bf16 v[66:69], v[166:169], v[214:217], v[66:69]
	v_mfma_f32_16x16x32_bf16 v[66:69], v[170:173], v[218:221], v[66:69]
	v_mfma_f32_16x16x32_bf16 v[82:85], v[170:173], v[210:213], v[82:85]
	v_mfma_f32_16x16x32_bf16 v[82:85], v[166:169], v[206:209], v[82:85]
	v_mfma_f32_16x16x32_bf16 v[98:101], v[166:169], v[198:201], v[98:101]
	v_mfma_f32_16x16x32_bf16 v[98:101], v[170:173], v[202:205], v[98:101]
	v_mfma_f32_16x16x32_bf16 v[114:117], v[170:173], v[194:197], v[114:117]
	v_mfma_f32_16x16x32_bf16 v[114:117], v[166:169], v[190:193], v[114:117]
	v_mfma_f32_16x16x32_bf16 v[126:129], v[174:177], v[190:193], v[126:129]
	v_mfma_f32_16x16x32_bf16 v[126:129], v[178:181], v[194:197], v[126:129]
	v_mfma_f32_16x16x32_bf16 v[110:113], v[178:181], v[202:205], v[110:113]
	v_mfma_f32_16x16x32_bf16 v[110:113], v[174:177], v[198:201], v[110:113]
	v_mfma_f32_16x16x32_bf16 v[94:97], v[174:177], v[206:209], v[94:97]
	v_mfma_f32_16x16x32_bf16 v[94:97], v[178:181], v[210:213], v[94:97]
	v_mfma_f32_16x16x32_bf16 v[78:81], v[178:181], v[218:221], v[78:81]
	v_mfma_f32_16x16x32_bf16 v[78:81], v[174:177], v[214:217], v[78:81]
	v_mfma_f32_16x16x32_bf16 v[74:77], v[182:185], v[214:217], v[74:77]
	v_mfma_f32_16x16x32_bf16 v[74:77], v[186:189], v[218:221], v[74:77]
	v_mfma_f32_16x16x32_bf16 v[90:93], v[186:189], v[210:213], v[90:93]
	v_mfma_f32_16x16x32_bf16 v[90:93], v[182:185], v[206:209], v[90:93]
	v_mfma_f32_16x16x32_bf16 v[106:109], v[182:185], v[198:201], v[106:109]
	v_mfma_f32_16x16x32_bf16 v[106:109], v[186:189], v[202:205], v[106:109]
	v_mfma_f32_16x16x32_bf16 v[122:125], v[186:189], v[194:197], v[122:125]
	v_mfma_f32_16x16x32_bf16 v[122:125], v[182:185], v[190:193], v[122:125]
	s_barrier
	s_add_i32 s24, s63, s26
	s_add_i32 m0, s24, 0xffffff80
	ds_read_b128 v[190:193], v161 offset:49152
	ds_read_b128 v[194:197], v161 offset:50176
	ds_read_b128 v[198:201], v161 offset:51200
	ds_read_b128 v[202:205], v161 offset:52224
	ds_read_b128 v[206:209], v161 offset:53248
	ds_read_b128 v[210:213], v161 offset:54272
	ds_read_b128 v[214:217], v161 offset:55296
	ds_read_b128 v[218:221], v161 offset:56320
	global_load_lds_dwordx4 v132, s[20:21] offset:128
	s_add_i32 m0, s24, 0x1f80
	s_add_i32 s24, s64, s26
	global_load_lds_dwordx4 v136, s[20:21] offset:128
	s_add_u32 s20, s20, 0x100080
	s_addc_u32 s21, s21, 0
	s_mov_b32 m0, s24
	s_nop 0
	global_load_lds_dwordx4 v132, s[20:21]
	s_add_i32 m0, s24, 0x2000
	s_nop 0
	global_load_lds_dwordx4 v136, s[20:21]
	s_mov_b32 m0, s40
	s_nop 0
	global_load_lds_dwordx4 v130, s[100:101]
	s_mov_b32 m0, s41
	s_nop 0
	global_load_lds_dwordx4 v134, s[100:101]
	s_waitcnt vmcnt(8)
	s_waitcnt lgkmcnt(0)
	s_barrier
	s_waitcnt lgkmcnt(0)
	v_mfma_f32_16x16x32_bf16 v[54:57], v[148:151], v[190:193], v[54:57]
	v_mfma_f32_16x16x32_bf16 v[54:57], v[156:159], v[194:197], v[54:57]
	v_mfma_f32_16x16x32_bf16 v[38:41], v[156:159], v[202:205], v[38:41]
	v_mfma_f32_16x16x32_bf16 v[38:41], v[148:151], v[198:201], v[38:41]
	v_mfma_f32_16x16x32_bf16 v[22:25], v[148:151], v[206:209], v[22:25]
	v_mfma_f32_16x16x32_bf16 v[22:25], v[156:159], v[210:213], v[22:25]
	v_mfma_f32_16x16x32_bf16 v[6:9], v[156:159], v[218:221], v[6:9]
	v_mfma_f32_16x16x32_bf16 v[6:9], v[148:151], v[214:217], v[6:9]
	v_mfma_f32_16x16x32_bf16 v[2:5], v[166:169], v[214:217], v[2:5]
	v_mfma_f32_16x16x32_bf16 v[2:5], v[170:173], v[218:221], v[2:5]
	v_mfma_f32_16x16x32_bf16 v[18:21], v[170:173], v[210:213], v[18:21]
	v_mfma_f32_16x16x32_bf16 v[18:21], v[166:169], v[206:209], v[18:21]
	v_mfma_f32_16x16x32_bf16 v[34:37], v[166:169], v[198:201], v[34:37]
	v_mfma_f32_16x16x32_bf16 v[34:37], v[170:173], v[202:205], v[34:37]
	v_mfma_f32_16x16x32_bf16 v[50:53], v[170:173], v[194:197], v[50:53]
	v_mfma_f32_16x16x32_bf16 v[50:53], v[166:169], v[190:193], v[50:53]
	v_mfma_f32_16x16x32_bf16 v[62:65], v[174:177], v[190:193], v[62:65]
	v_mfma_f32_16x16x32_bf16 v[62:65], v[178:181], v[194:197], v[62:65]
	v_mfma_f32_16x16x32_bf16 v[46:49], v[178:181], v[202:205], v[46:49]
	v_mfma_f32_16x16x32_bf16 v[46:49], v[174:177], v[198:201], v[46:49]
	v_mfma_f32_16x16x32_bf16 v[30:33], v[174:177], v[206:209], v[30:33]
	v_mfma_f32_16x16x32_bf16 v[30:33], v[178:181], v[210:213], v[30:33]
	v_mfma_f32_16x16x32_bf16 v[10:13], v[178:181], v[218:221], v[10:13]
	v_mfma_f32_16x16x32_bf16 v[10:13], v[174:177], v[214:217], v[10:13]
	v_mfma_f32_16x16x32_bf16 v[14:17], v[182:185], v[214:217], v[14:17]
	v_mfma_f32_16x16x32_bf16 v[14:17], v[186:189], v[218:221], v[14:17]
	v_mfma_f32_16x16x32_bf16 v[26:29], v[186:189], v[210:213], v[26:29]
	v_mfma_f32_16x16x32_bf16 v[26:29], v[182:185], v[206:209], v[26:29]
	v_mfma_f32_16x16x32_bf16 v[42:45], v[182:185], v[198:201], v[42:45]
	v_mfma_f32_16x16x32_bf16 v[42:45], v[186:189], v[202:205], v[42:45]
	v_mfma_f32_16x16x32_bf16 v[58:61], v[186:189], v[194:197], v[58:61]
	v_mfma_f32_16x16x32_bf16 v[58:61], v[182:185], v[190:193], v[58:61]
	s_barrier
	s_add_i32 s35, s35, 2
	s_add_u32 s22, s22, 0x100
	s_addc_u32 s23, s23, 0
	s_add_u32 s62, s62, 0x100
	s_addc_u32 s34, s34, 0
	s_cmp_gt_u32 s35, 61
	s_cbranch_scc0 .LBB0_673
	s_and_b64 vcc, exec, s[8:9]
	s_cbranch_vccz .LBB0_676
	s_barrier

; #define PG8_STAGE(bufoff, gbase, voff) do { _Pragma("unroll") for (int _i = 0; _i < 2; ++_i) \
;         __builtin_amdgcn_global_load_lds((const unsigned*)((const char*)(gbase) + (voff)[_i]), (PG8_LAS unsigned*)(lds + (bufoff) + ldsw + _i * 8192), 16, 0, 0); } while (0)
; #define PG8_LDA(dst, b, h) do { _Pragma("unroll") for (int m = 0; m < 4; ++m) _Pragma("unroll") for (int k = 0; k < 2; ++k) dst[m][k] = *(const PG8_LAS bf16x8*)(lds + PG8_SA(b, h) + aoff + m * 2048 + k * 1024); } while (0)
; #define PG8_LDB(dst, b, h) do { _Pragma("unroll") for (int n = 0; n < 2; ++n) _Pragma("unroll") for (int k = 0; k < 2; ++k) dst[n][k] = *(const PG8_LAS bf16x8*)(lds + PG8_SB(b, h) + boff + n * 2048 + k * 1024); } while (0)
; #define PG8_MMA(ai, bj, At, Bt) do { __builtin_amdgcn_s_setprio(1); _Pragma("unroll") for (int m = 0; m < 4; ++m) _Pragma("unroll") for (int n = 0; n < 2; ++n) _Pragma("unroll") for (int k = 0; k < 2; ++k) \
;         acc[ai][bj][m][n] = __builtin_amdgcn_mfma_f32_16x16x32_bf16(Bt[n][k], At[m][k], acc[ai][bj][m][n], 0, 0, 0); __builtin_amdgcn_s_setprio(0); } while (0)
; #define PG8_WAIT_V(n) asm volatile("s_waitcnt vmcnt(" #n ")" ::: "memory")
; #define PG8_BAR __builtin_amdgcn_s_barrier()
; template <class Epi, class Sched, bool ALIGN_EPI = false, bool SP2 = false>
; __device__ __forceinline__ void gemm_phase(PG8_LAS unsigned char* lds, const Gemm g, const Sched& S, const Epi& E) {
;     ...
;         for (int t = 0; t < nt; t += 2) {
;             const bool last = (t == nt - 2);
;             const char* a1 = cA + (size_t)(t + 1) * kstep;
;             const char* a2 = last ? nA : cA + (size_t)(t + 2) * kstep; const char* b2 = last ? nB : cB + (size_t)(t + 2) * kstep;
;             const char* a3 = a2 + kstep; const char* b3 = b2 + kstep;
;             if (last && has_next) S.a_ready(nxt);
;             if constexpr (SP2) {
;             PG8_LDB(B0, 0, 0); PG8_LDB(B1, 0, 1); PG8_SCHED; PG8_LDA(At, 0, 0); PG8_STAGE(PG8_SA(1, 1), a1 + hstep, voffA);
;             PG8_WAIT_V(8); PG8_WAIT_L(0); PG8_BAR; PG8_MMA(0, 0, At, B0); PG8_MMA(0, 1, At, B1); PG8_BAR; PG8_SCHED;
;             PG8_LDA(At, 0, 1); PG8_STAGE(PG8_SB(0, 0), b2, voffB); PG8_STAGE(PG8_SB(0, 1), b2 + hstep, voffB); PG8_STAGE(PG8_SA(0, 0), a2, voffA);
;             PG8_WAIT_V(8); PG8_WAIT_L(0); PG8_BAR; PG8_MMA(1, 0, At, B0); PG8_MMA(1, 1, At, B1); PG8_BAR; PG8_SCHED;
.LBB0_1039:
	ds_read_b128 v[130:133], v241 offset:0
	ds_read_b128 v[134:137], v241 offset:1024
	ds_read_b128 v[138:141], v241 offset:2048
	ds_read_b128 v[142:145], v241 offset:3072
	ds_read_b128 v[146:149], v241 offset:16384
	ds_read_b128 v[150:153], v241 offset:17408
	ds_read_b128 v[172:175], v241 offset:18432
	ds_read_b128 v[176:179], v241 offset:19456
	s_add_u32 s24, s26, 0xfff00080
	s_addc_u32 s25, s27, -1
	s_cmp_eq_u32 s68, 60
	s_cselect_b32 s29, s15, s25
	s_cselect_b32 s28, s21, s24
	s_cselect_b32 s25, s13, s67
	s_cselect_b32 s24, s65, s66
	s_add_i32 m0, s23, 0xc000
	ds_read_b128 v[180:183], v185
	ds_read_b128 v[188:191], v185 offset:1024
	ds_read_b128 v[192:195], v185 offset:2048
	ds_read_b128 v[196:199], v185 offset:3072
	ds_read_b128 v[200:203], v185 offset:4096
	ds_read_b128 v[204:207], v185 offset:5120
	ds_read_b128 v[208:211], v185 offset:6144
	ds_read_b128 v[212:215], v185 offset:7168
	global_load_lds_dwordx4 v162, s[26:27]
	s_add_i32 m0, s23, 0xe000
	s_nop 0
	global_load_lds_dwordx4 v166, s[26:27]
	s_waitcnt vmcnt(8)
	s_waitcnt lgkmcnt(0)
	s_barrier
	s_waitcnt lgkmcnt(0)
	v_mfma_f32_16x16x32_bf16 v[114:117], v[130:133], v[180:183], v[114:117]
	v_mfma_f32_16x16x32_bf16 v[114:117], v[134:137], v[188:191], v[114:117]
	v_mfma_f32_16x16x32_bf16 v[106:109], v[134:137], v[196:199], v[106:109]
	v_mfma_f32_16x16x32_bf16 v[106:109], v[130:133], v[192:195], v[106:109]
	v_mfma_f32_16x16x32_bf16 v[90:93], v[130:133], v[200:203], v[90:93]
	v_mfma_f32_16x16x32_bf16 v[90:93], v[134:137], v[204:207], v[90:93]
	v_mfma_f32_16x16x32_bf16 v[74:77], v[134:137], v[212:215], v[74:77]
	v_mfma_f32_16x16x32_bf16 v[74:77], v[130:133], v[208:211], v[74:77]
	v_mfma_f32_16x16x32_bf16 v[66:69], v[138:141], v[208:211], v[66:69]
	v_mfma_f32_16x16x32_bf16 v[66:69], v[142:145], v[212:215], v[66:69]
	v_mfma_f32_16x16x32_bf16 v[82:85], v[142:145], v[204:207], v[82:85]
	v_mfma_f32_16x16x32_bf16 v[82:85], v[138:141], v[200:203], v[82:85]
	v_mfma_f32_16x16x32_bf16 v[98:101], v[138:141], v[192:195], v[98:101]
	v_mfma_f32_16x16x32_bf16 v[98:101], v[142:145], v[196:199], v[98:101]
	v_mfma_f32_16x16x32_bf16 v[118:121], v[142:145], v[188:191], v[118:121]
	v_mfma_f32_16x16x32_bf16 v[118:121], v[138:141], v[180:183], v[118:121]
	v_mfma_f32_16x16x32_bf16 v[122:125], v[146:149], v[180:183], v[122:125]
	v_mfma_f32_16x16x32_bf16 v[122:125], v[150:153], v[188:191], v[122:125]
	v_mfma_f32_16x16x32_bf16 v[110:113], v[150:153], v[196:199], v[110:113]
	v_mfma_f32_16x16x32_bf16 v[110:113], v[146:149], v[192:195], v[110:113]
	v_mfma_f32_16x16x32_bf16 v[94:97], v[146:149], v[200:203], v[94:97]
	v_mfma_f32_16x16x32_bf16 v[94:97], v[150:153], v[204:207], v[94:97]
	v_mfma_f32_16x16x32_bf16 v[78:81], v[150:153], v[212:215], v[78:81]
	v_mfma_f32_16x16x32_bf16 v[78:81], v[146:149], v[208:211], v[78:81]
	v_mfma_f32_16x16x32_bf16 v[70:73], v[172:175], v[208:211], v[70:73]
	v_mfma_f32_16x16x32_bf16 v[70:73], v[176:179], v[212:215], v[70:73]
	v_mfma_f32_16x16x32_bf16 v[86:89], v[176:179], v[204:207], v[86:89]
	v_mfma_f32_16x16x32_bf16 v[86:89], v[172:175], v[200:203], v[86:89]
	v_mfma_f32_16x16x32_bf16 v[102:105], v[172:175], v[192:195], v[102:105]
	v_mfma_f32_16x16x32_bf16 v[102:105], v[176:179], v[196:199], v[102:105]
	v_mfma_f32_16x16x32_bf16 v[126:129], v[176:179], v[188:191], v[126:129]
	v_mfma_f32_16x16x32_bf16 v[126:129], v[172:175], v[180:183], v[126:129]
	s_barrier
	s_add_i32 s33, s62, s36
	s_mov_b32 m0, s33
	ds_read_b128 v[180:183], v185 offset:16384
	ds_read_b128 v[188:191], v185 offset:17408
	ds_read_b128 v[192:195], v185 offset:18432
	ds_read_b128 v[196:199], v185 offset:19456
	ds_read_b128 v[200:203], v185 offset:20480
	ds_read_b128 v[204:207], v185 offset:21504
	ds_read_b128 v[208:211], v185 offset:22528
	ds_read_b128 v[212:215], v185 offset:23552
	global_load_lds_dwordx4 v156, s[24:25]
	s_add_i32 m0, s33, 0x2000
	s_add_u32 s72, s24, 0x100000
	s_addc_u32 s73, s25, 0
	s_add_i32 s33, s63, s36
	global_load_lds_dwordx4 v160, s[24:25]
	s_mov_b32 m0, s33
	s_add_u32 s100, s28, 0x80
	s_addc_u32 s101, s29, 0
	global_load_lds_dwordx4 v156, s[72:73]
	s_add_i32 m0, s33, 0x2000
	s_nop 0
	global_load_lds_dwordx4 v160, s[72:73]
	s_mov_b32 m0, s23
	s_nop 0
	global_load_lds_dwordx4 v154, s[28:29]
	s_mov_b32 m0, s37
	s_nop 0
	global_load_lds_dwordx4 v158, s[28:29]
	s_waitcnt vmcnt(8)
	s_waitcnt lgkmcnt(0)
	s_barrier
	s_waitcnt lgkmcnt(0)
	v_mfma_f32_16x16x32_bf16 v[58:61], v[130:133], v[180:183], v[58:61]
	v_mfma_f32_16x16x32_bf16 v[58:61], v[134:137], v[188:191], v[58:61]
	v_mfma_f32_16x16x32_bf16 v[42:45], v[134:137], v[196:199], v[42:45]
	v_mfma_f32_16x16x32_bf16 v[42:45], v[130:133], v[192:195], v[42:45]
	v_mfma_f32_16x16x32_bf16 v[26:29], v[130:133], v[200:203], v[26:29]
	v_mfma_f32_16x16x32_bf16 v[26:29], v[134:137], v[204:207], v[26:29]
	v_mfma_f32_16x16x32_bf16 v[6:9], v[134:137], v[212:215], v[6:9]
	v_mfma_f32_16x16x32_bf16 v[6:9], v[130:133], v[208:211], v[6:9]
	v_mfma_f32_16x16x32_bf16 v[2:5], v[138:141], v[208:211], v[2:5]
	v_mfma_f32_16x16x32_bf16 v[2:5], v[142:145], v[212:215], v[2:5]
	v_mfma_f32_16x16x32_bf16 v[18:21], v[142:145], v[204:207], v[18:21]
	v_mfma_f32_16x16x32_bf16 v[18:21], v[138:141], v[200:203], v[18:21]
	v_mfma_f32_16x16x32_bf16 v[34:37], v[138:141], v[192:195], v[34:37]
	v_mfma_f32_16x16x32_bf16 v[34:37], v[142:145], v[196:199], v[34:37]
	v_mfma_f32_16x16x32_bf16 v[54:57], v[142:145], v[188:191], v[54:57]
	v_mfma_f32_16x16x32_bf16 v[54:57], v[138:141], v[180:183], v[54:57]
	v_mfma_f32_16x16x32_bf16 v[62:65], v[146:149], v[180:183], v[62:65]
	v_mfma_f32_16x16x32_bf16 v[62:65], v[150:153], v[188:191], v[62:65]
	v_mfma_f32_16x16x32_bf16 v[46:49], v[150:153], v[196:199], v[46:49]
	v_mfma_f32_16x16x32_bf16 v[46:49], v[146:149], v[192:195], v[46:49]
	v_mfma_f32_16x16x32_bf16 v[30:33], v[146:149], v[200:203], v[30:33]
	v_mfma_f32_16x16x32_bf16 v[30:33], v[150:153], v[204:207], v[30:33]
	v_mfma_f32_16x16x32_bf16 v[10:13], v[150:153], v[212:215], v[10:13]
	v_mfma_f32_16x16x32_bf16 v[10:13], v[146:149], v[208:211], v[10:13]
	v_mfma_f32_16x16x32_bf16 v[14:17], v[172:175], v[208:211], v[14:17]
	v_mfma_f32_16x16x32_bf16 v[14:17], v[176:179], v[212:215], v[14:17]
	v_mfma_f32_16x16x32_bf16 v[22:25], v[176:179], v[204:207], v[22:25]
	v_mfma_f32_16x16x32_bf16 v[22:25], v[172:175], v[200:203], v[22:25]
	v_mfma_f32_16x16x32_bf16 v[38:41], v[172:175], v[192:195], v[38:41]
	v_mfma_f32_16x16x32_bf16 v[38:41], v[176:179], v[196:199], v[38:41]
	v_mfma_f32_16x16x32_bf16 v[50:53], v[176:179], v[188:191], v[50:53]
	v_mfma_f32_16x16x32_bf16 v[50:53], v[172:175], v[180:183], v[50:53]
	s_barrier
; #define PG8_STAGE(bufoff, gbase, voff) do { _Pragma("unroll") for (int _i = 0; _i < 2; ++_i) \
;         __builtin_amdgcn_global_load_lds((const unsigned*)((const char*)(gbase) + (voff)[_i]), (PG8_LAS unsigned*)(lds + (bufoff) + ldsw + _i * 8192), 16, 0, 0); } while (0)
; #define PG8_LDA(dst, b, h) do { _Pragma("unroll") for (int m = 0; m < 4; ++m) _Pragma("unroll") for (int k = 0; k < 2; ++k) dst[m][k] = *(const PG8_LAS bf16x8*)(lds + PG8_SA(b, h) + aoff + m * 2048 + k * 1024); } while (0)
; #define PG8_LDB(dst, b, h) do { _Pragma("unroll") for (int n = 0; n < 2; ++n) _Pragma("unroll") for (int k = 0; k < 2; ++k) dst[n][k] = *(const PG8_LAS bf16x8*)(lds + PG8_SB(b, h) + boff + n * 2048 + k * 1024); } while (0)
; #define PG8_MMA(ai, bj, At, Bt) do { __builtin_amdgcn_s_setprio(1); _Pragma("unroll") for (int m = 0; m < 4; ++m) _Pragma("unroll") for (int n = 0; n < 2; ++n) _Pragma("unroll") for (int k = 0; k < 2; ++k) \
;         acc[ai][bj][m][n] = __builtin_amdgcn_mfma_f32_16x16x32_bf16(Bt[n][k], At[m][k], acc[ai][bj][m][n], 0, 0, 0); __builtin_amdgcn_s_setprio(0); } while (0)
; #define PG8_WAIT_V(n) asm volatile("s_waitcnt vmcnt(" #n ")" ::: "memory")
; #define PG8_WAIT_L(n) asm volatile("s_waitcnt lgkmcnt(" #n ")" ::: "memory")
; #define PG8_BAR __builtin_amdgcn_s_barrier()
; #define PG8_SCHED __builtin_amdgcn_sched_barrier(0)
; template <class Epi, class Sched, bool ALIGN_EPI = false, bool SP2 = false>
; __device__ __forceinline__ void gemm_phase(PG8_LAS unsigned char* lds, const Gemm g, const Sched& S, const Epi& E) {
;     ...
;             PG8_LDB(B0, 1, 0); PG8_LDB(B1, 1, 1); PG8_SCHED; PG8_LDA(At, 1, 0); PG8_STAGE(PG8_SA(0, 1), a2 + hstep, voffA);
;             PG8_WAIT_V(8); PG8_WAIT_L(0); PG8_BAR; PG8_MMA(0, 0, At, B0); PG8_MMA(0, 1, At, B1); PG8_BAR; PG8_SCHED;
;             PG8_LDA(At, 1, 1); PG8_STAGE(PG8_SB(1, 0), b3, voffB); PG8_STAGE(PG8_SB(1, 1), b3 + hstep, voffB); PG8_STAGE(PG8_SA(1, 0), a3, voffA);
;             PG8_WAIT_V(8); PG8_WAIT_L(0); PG8_BAR; PG8_MMA(1, 0, At, B0); PG8_MMA(1, 1, At, B1); PG8_BAR; PG8_SCHED;
	s_add_i32 s33, 0, 0x18000
	s_add_i32 s42, 0, 0x1c000
	ds_read_b128 v[130:133], v241 offset:32768
	ds_read_b128 v[134:137], v241 offset:33792
	ds_read_b128 v[138:141], v241 offset:34816
	ds_read_b128 v[142:145], v241 offset:35840
	ds_read_b128 v[146:149], v241 offset:49152
	ds_read_b128 v[150:153], v241 offset:50176
	ds_read_b128 v[172:175], v241 offset:51200
	ds_read_b128 v[176:179], v241 offset:52224
	s_add_u32 s28, s28, 0x100000
	s_addc_u32 s29, s29, 0
	s_mov_b32 m0, s40
	ds_read_b128 v[180:183], v185 offset:32768
	ds_read_b128 v[188:191], v185 offset:33792
	ds_read_b128 v[192:195], v185 offset:34816
	ds_read_b128 v[196:199], v185 offset:35840
	ds_read_b128 v[200:203], v185 offset:36864
	ds_read_b128 v[204:207], v185 offset:37888
	ds_read_b128 v[208:211], v185 offset:38912
	ds_read_b128 v[212:215], v185 offset:39936
	global_load_lds_dwordx4 v154, s[28:29]
	s_mov_b32 m0, s41
	s_nop 0
	global_load_lds_dwordx4 v158, s[28:29]
	s_waitcnt vmcnt(8)
	s_waitcnt lgkmcnt(0)
	s_barrier
	s_waitcnt lgkmcnt(0)
	v_mfma_f32_16x16x32_bf16 v[114:117], v[130:133], v[180:183], v[114:117]
	v_mfma_f32_16x16x32_bf16 v[114:117], v[134:137], v[188:191], v[114:117]
	v_mfma_f32_16x16x32_bf16 v[106:109], v[134:137], v[196:199], v[106:109]
	v_mfma_f32_16x16x32_bf16 v[106:109], v[130:133], v[192:195], v[106:109]
	v_mfma_f32_16x16x32_bf16 v[90:93], v[130:133], v[200:203], v[90:93]
	v_mfma_f32_16x16x32_bf16 v[90:93], v[134:137], v[204:207], v[90:93]
	v_mfma_f32_16x16x32_bf16 v[74:77], v[134:137], v[212:215], v[74:77]
	v_mfma_f32_16x16x32_bf16 v[74:77], v[130:133], v[208:211], v[74:77]
	v_mfma_f32_16x16x32_bf16 v[66:69], v[138:141], v[208:211], v[66:69]
	v_mfma_f32_16x16x32_bf16 v[66:69], v[142:145], v[212:215], v[66:69]
	v_mfma_f32_16x16x32_bf16 v[82:85], v[142:145], v[204:207], v[82:85]
	v_mfma_f32_16x16x32_bf16 v[82:85], v[138:141], v[200:203], v[82:85]
	v_mfma_f32_16x16x32_bf16 v[98:101], v[138:141], v[192:195], v[98:101]
	v_mfma_f32_16x16x32_bf16 v[98:101], v[142:145], v[196:199], v[98:101]
	v_mfma_f32_16x16x32_bf16 v[118:121], v[142:145], v[188:191], v[118:121]
	v_mfma_f32_16x16x32_bf16 v[118:121], v[138:141], v[180:183], v[118:121]
	v_mfma_f32_16x16x32_bf16 v[122:125], v[146:149], v[180:183], v[122:125]
	v_mfma_f32_16x16x32_bf16 v[122:125], v[150:153], v[188:191], v[122:125]
	v_mfma_f32_16x16x32_bf16 v[110:113], v[150:153], v[196:199], v[110:113]
	v_mfma_f32_16x16x32_bf16 v[110:113], v[146:149], v[192:195], v[110:113]
	v_mfma_f32_16x16x32_bf16 v[94:97], v[146:149], v[200:203], v[94:97]
	v_mfma_f32_16x16x32_bf16 v[94:97], v[150:153], v[204:207], v[94:97]
	v_mfma_f32_16x16x32_bf16 v[78:81], v[150:153], v[212:215], v[78:81]
	v_mfma_f32_16x16x32_bf16 v[78:81], v[146:149], v[208:211], v[78:81]
	v_mfma_f32_16x16x32_bf16 v[70:73], v[172:175], v[208:211], v[70:73]
	v_mfma_f32_16x16x32_bf16 v[70:73], v[176:179], v[212:215], v[70:73]
	v_mfma_f32_16x16x32_bf16 v[86:89], v[176:179], v[204:207], v[86:89]
	v_mfma_f32_16x16x32_bf16 v[86:89], v[172:175], v[200:203], v[86:89]
	v_mfma_f32_16x16x32_bf16 v[102:105], v[172:175], v[192:195], v[102:105]
	v_mfma_f32_16x16x32_bf16 v[102:105], v[176:179], v[196:199], v[102:105]
	v_mfma_f32_16x16x32_bf16 v[126:129], v[176:179], v[188:191], v[126:129]
	v_mfma_f32_16x16x32_bf16 v[126:129], v[172:175], v[180:183], v[126:129]
	s_barrier
	s_add_i32 s28, s33, s36
	s_add_i32 m0, s28, 0xffffff80
	ds_read_b128 v[180:183], v185 offset:49152
	ds_read_b128 v[188:191], v185 offset:50176
	ds_read_b128 v[192:195], v185 offset:51200
	ds_read_b128 v[196:199], v185 offset:52224
	ds_read_b128 v[200:203], v185 offset:53248
	ds_read_b128 v[204:207], v185 offset:54272
	ds_read_b128 v[208:211], v185 offset:55296
	ds_read_b128 v[212:215], v185 offset:56320
	global_load_lds_dwordx4 v156, s[24:25] offset:128
	s_add_i32 m0, s28, 0x1f80
	s_add_i32 s28, s42, s36
	global_load_lds_dwordx4 v160, s[24:25] offset:128
	s_add_u32 s24, s24, 0x100080
	s_addc_u32 s25, s25, 0
	s_mov_b32 m0, s28
	s_nop 0
	global_load_lds_dwordx4 v156, s[24:25]
	s_add_i32 m0, s28, 0x2000
	s_nop 0
	global_load_lds_dwordx4 v160, s[24:25]
	s_mov_b32 m0, s46
	s_nop 0
	global_load_lds_dwordx4 v154, s[100:101]
	s_mov_b32 m0, s47
	s_nop 0
	global_load_lds_dwordx4 v158, s[100:101]
	s_waitcnt vmcnt(8)
	s_waitcnt lgkmcnt(0)
	s_barrier
	s_waitcnt lgkmcnt(0)
	v_mfma_f32_16x16x32_bf16 v[58:61], v[130:133], v[180:183], v[58:61]
	v_mfma_f32_16x16x32_bf16 v[58:61], v[134:137], v[188:191], v[58:61]
	v_mfma_f32_16x16x32_bf16 v[42:45], v[134:137], v[196:199], v[42:45]
	v_mfma_f32_16x16x32_bf16 v[42:45], v[130:133], v[192:195], v[42:45]
	v_mfma_f32_16x16x32_bf16 v[26:29], v[130:133], v[200:203], v[26:29]
	v_mfma_f32_16x16x32_bf16 v[26:29], v[134:137], v[204:207], v[26:29]
	v_mfma_f32_16x16x32_bf16 v[6:9], v[134:137], v[212:215], v[6:9]
	v_mfma_f32_16x16x32_bf16 v[6:9], v[130:133], v[208:211], v[6:9]
	v_mfma_f32_16x16x32_bf16 v[2:5], v[138:141], v[208:211], v[2:5]
	v_mfma_f32_16x16x32_bf16 v[2:5], v[142:145], v[212:215], v[2:5]
	v_mfma_f32_16x16x32_bf16 v[18:21], v[142:145], v[204:207], v[18:21]
	v_mfma_f32_16x16x32_bf16 v[18:21], v[138:141], v[200:203], v[18:21]
	v_mfma_f32_16x16x32_bf16 v[34:37], v[138:141], v[192:195], v[34:37]
	v_mfma_f32_16x16x32_bf16 v[34:37], v[142:145], v[196:199], v[34:37]
	v_mfma_f32_16x16x32_bf16 v[54:57], v[142:145], v[188:191], v[54:57]
	v_mfma_f32_16x16x32_bf16 v[54:57], v[138:141], v[180:183], v[54:57]
	v_mfma_f32_16x16x32_bf16 v[62:65], v[146:149], v[180:183], v[62:65]
	v_mfma_f32_16x16x32_bf16 v[62:65], v[150:153], v[188:191], v[62:65]
	v_mfma_f32_16x16x32_bf16 v[46:49], v[150:153], v[196:199], v[46:49]
	v_mfma_f32_16x16x32_bf16 v[46:49], v[146:149], v[192:195], v[46:49]
	v_mfma_f32_16x16x32_bf16 v[30:33], v[146:149], v[200:203], v[30:33]
	v_mfma_f32_16x16x32_bf16 v[30:33], v[150:153], v[204:207], v[30:33]
	v_mfma_f32_16x16x32_bf16 v[10:13], v[150:153], v[212:215], v[10:13]
	v_mfma_f32_16x16x32_bf16 v[10:13], v[146:149], v[208:211], v[10:13]
	v_mfma_f32_16x16x32_bf16 v[14:17], v[172:175], v[208:211], v[14:17]
	v_mfma_f32_16x16x32_bf16 v[14:17], v[176:179], v[212:215], v[14:17]
	v_mfma_f32_16x16x32_bf16 v[22:25], v[176:179], v[204:207], v[22:25]
	v_mfma_f32_16x16x32_bf16 v[22:25], v[172:175], v[200:203], v[22:25]
	v_mfma_f32_16x16x32_bf16 v[38:41], v[172:175], v[192:195], v[38:41]
	v_mfma_f32_16x16x32_bf16 v[38:41], v[176:179], v[196:199], v[38:41]
	v_mfma_f32_16x16x32_bf16 v[50:53], v[176:179], v[188:191], v[50:53]
	v_mfma_f32_16x16x32_bf16 v[50:53], v[172:175], v[180:183], v[50:53]
	s_barrier
	s_add_i32 s68, s68, 2
	s_add_u32 s26, s26, 0x100
	s_addc_u32 s27, s27, 0
	s_add_u32 s66, s66, 0x100
	s_addc_u32 s67, s67, 0
	s_cmp_gt_u32 s68, 61
	s_cbranch_scc0 .LBB0_1039
	s_and_b64 vcc, exec, s[10:11]
	s_cbranch_vccz .LBB0_1042
	s_barrier

; #define PG8_STAGE(bufoff, gbase, voff) do { _Pragma("unroll") for (int _i = 0; _i < 2; ++_i) \
;         __builtin_amdgcn_global_load_lds((const unsigned*)((const char*)(gbase) + (voff)[_i]), (PG8_LAS unsigned*)(lds + (bufoff) + ldsw + _i * 8192), 16, 0, 0); } while (0)
; #define PG8_LDA(dst, b, h) do { _Pragma("unroll") for (int m = 0; m < 4; ++m) _Pragma("unroll") for (int k = 0; k < 2; ++k) dst[m][k] = *(const PG8_LAS bf16x8*)(lds + PG8_SA(b, h) + aoff + m * 2048 + k * 1024); } while (0)
; #define PG8_LDB(dst, b, h) do { _Pragma("unroll") for (int n = 0; n < 2; ++n) _Pragma("unroll") for (int k = 0; k < 2; ++k) dst[n][k] = *(const PG8_LAS bf16x8*)(lds + PG8_SB(b, h) + boff + n * 2048 + k * 1024); } while (0)
; #define PG8_MMA(ai, bj, At, Bt) do { __builtin_amdgcn_s_setprio(1); _Pragma("unroll") for (int m = 0; m < 4; ++m) _Pragma("unroll") for (int n = 0; n < 2; ++n) _Pragma("unroll") for (int k = 0; k < 2; ++k) \
;         acc[ai][bj][m][n] = __builtin_amdgcn_mfma_f32_16x16x32_bf16(Bt[n][k], At[m][k], acc[ai][bj][m][n], 0, 0, 0); __builtin_amdgcn_s_setprio(0); } while (0)
; #define PG8_WAIT_V(n) asm volatile("s_waitcnt vmcnt(" #n ")" ::: "memory")
; #define PG8_WAIT_L(n) asm volatile("s_waitcnt lgkmcnt(" #n ")" ::: "memory")
; #define PG8_BAR __builtin_amdgcn_s_barrier()
; #define PG8_SCHED __builtin_amdgcn_sched_barrier(0)
; template <class Epi, class Sched, bool ALIGN_EPI = false, bool SP2 = false>
; __device__ __forceinline__ void gemm_phase(PG8_LAS unsigned char* lds, const Gemm g, const Sched& S, const Epi& E) {
;     ...
;             PG8_LDB(B0, 0, 0); PG8_LDB(B1, 0, 1); PG8_SCHED; PG8_LDA(At, 0, 0); PG8_STAGE(PG8_SA(1, 1), a1 + hstep, voffA);
;             PG8_WAIT_V(8); PG8_WAIT_L(0); PG8_BAR; PG8_MMA(0, 0, At, B0); PG8_MMA(0, 1, At, B1); PG8_BAR; PG8_SCHED;
;             PG8_LDA(At, 0, 1); PG8_STAGE(PG8_SB(0, 0), b2, voffB); PG8_STAGE(PG8_SB(0, 1), b2 + hstep, voffB); PG8_STAGE(PG8_SA(0, 0), a2, voffA);
;             PG8_WAIT_V(8); PG8_WAIT_L(0); PG8_BAR; PG8_MMA(1, 0, At, B0); PG8_MMA(1, 1, At, B1); PG8_BAR; PG8_SCHED;
.LBB0_1126:
	ds_read_b128 v[160:163], v241 offset:0
	ds_read_b128 v[166:169], v241 offset:1024
	ds_read_b128 v[170:173], v241 offset:2048
	ds_read_b128 v[174:177], v241 offset:3072
	ds_read_b128 v[178:181], v241 offset:16384
	ds_read_b128 v[182:185], v241 offset:17408
	ds_read_b128 v[186:189], v241 offset:18432
	ds_read_b128 v[190:193], v241 offset:19456
	s_add_u32 s22, s24, 0xfff00080
	s_addc_u32 s23, s25, -1
	s_cmp_eq_u32 s68, 60
	s_cselect_b32 s27, s15, s23
	s_cselect_b32 s26, s64, s22
	s_cselect_b32 s23, s13, s67
	s_cselect_b32 s22, s65, s66
	s_add_i32 m0, s21, 0xc000
	ds_read_b128 v[194:197], v155
	ds_read_b128 v[198:201], v155 offset:1024
	ds_read_b128 v[202:205], v155 offset:2048
	ds_read_b128 v[206:209], v155 offset:3072
	ds_read_b128 v[210:213], v155 offset:4096
	ds_read_b128 v[214:217], v155 offset:5120
	ds_read_b128 v[218:221], v155 offset:6144
	ds_read_b128 v[222:225], v155 offset:7168
	global_load_lds_dwordx4 v138, s[24:25]
	s_add_i32 m0, s21, 0xe000
	s_nop 0
	global_load_lds_dwordx4 v140, s[24:25]
	s_waitcnt vmcnt(8)
	s_waitcnt lgkmcnt(0)
	s_barrier
	s_waitcnt lgkmcnt(0)
	v_mfma_f32_16x16x32_bf16 v[122:125], v[160:163], v[194:197], v[122:125]
	v_mfma_f32_16x16x32_bf16 v[122:125], v[166:169], v[198:201], v[122:125]
	v_mfma_f32_16x16x32_bf16 v[106:109], v[166:169], v[206:209], v[106:109]
	v_mfma_f32_16x16x32_bf16 v[106:109], v[160:163], v[202:205], v[106:109]
	v_mfma_f32_16x16x32_bf16 v[90:93], v[160:163], v[210:213], v[90:93]
	v_mfma_f32_16x16x32_bf16 v[90:93], v[166:169], v[214:217], v[90:93]
	v_mfma_f32_16x16x32_bf16 v[74:77], v[166:169], v[222:225], v[74:77]
	v_mfma_f32_16x16x32_bf16 v[74:77], v[160:163], v[218:221], v[74:77]
	v_mfma_f32_16x16x32_bf16 v[62:65], v[170:173], v[218:221], v[62:65]
	v_mfma_f32_16x16x32_bf16 v[62:65], v[174:177], v[222:225], v[62:65]
	v_mfma_f32_16x16x32_bf16 v[82:85], v[174:177], v[214:217], v[82:85]
	v_mfma_f32_16x16x32_bf16 v[82:85], v[170:173], v[210:213], v[82:85]
	v_mfma_f32_16x16x32_bf16 v[98:101], v[170:173], v[202:205], v[98:101]
	v_mfma_f32_16x16x32_bf16 v[98:101], v[174:177], v[206:209], v[98:101]
	v_mfma_f32_16x16x32_bf16 v[114:117], v[174:177], v[198:201], v[114:117]
	v_mfma_f32_16x16x32_bf16 v[114:117], v[170:173], v[194:197], v[114:117]
	v_mfma_f32_16x16x32_bf16 v[126:129], v[178:181], v[194:197], v[126:129]
	v_mfma_f32_16x16x32_bf16 v[126:129], v[182:185], v[198:201], v[126:129]
	v_mfma_f32_16x16x32_bf16 v[110:113], v[182:185], v[206:209], v[110:113]
	v_mfma_f32_16x16x32_bf16 v[110:113], v[178:181], v[202:205], v[110:113]
	v_mfma_f32_16x16x32_bf16 v[94:97], v[178:181], v[210:213], v[94:97]
	v_mfma_f32_16x16x32_bf16 v[94:97], v[182:185], v[214:217], v[94:97]
	v_mfma_f32_16x16x32_bf16 v[78:81], v[182:185], v[222:225], v[78:81]
	v_mfma_f32_16x16x32_bf16 v[78:81], v[178:181], v[218:221], v[78:81]
	v_mfma_f32_16x16x32_bf16 v[70:73], v[186:189], v[218:221], v[70:73]
	v_mfma_f32_16x16x32_bf16 v[70:73], v[190:193], v[222:225], v[70:73]
	v_mfma_f32_16x16x32_bf16 v[86:89], v[190:193], v[214:217], v[86:89]
	v_mfma_f32_16x16x32_bf16 v[86:89], v[186:189], v[210:213], v[86:89]
	v_mfma_f32_16x16x32_bf16 v[102:105], v[186:189], v[202:205], v[102:105]
	v_mfma_f32_16x16x32_bf16 v[102:105], v[190:193], v[206:209], v[102:105]
	v_mfma_f32_16x16x32_bf16 v[118:121], v[190:193], v[198:201], v[118:121]
	v_mfma_f32_16x16x32_bf16 v[118:121], v[186:189], v[194:197], v[118:121]
	s_barrier
	s_add_i32 s33, s52, s29
	s_mov_b32 m0, s33
	ds_read_b128 v[194:197], v155 offset:16384
	ds_read_b128 v[198:201], v155 offset:17408
	ds_read_b128 v[202:205], v155 offset:18432
	ds_read_b128 v[206:209], v155 offset:19456
	ds_read_b128 v[210:213], v155 offset:20480
	ds_read_b128 v[214:217], v155 offset:21504
	ds_read_b128 v[218:221], v155 offset:22528
	ds_read_b128 v[222:225], v155 offset:23552
	global_load_lds_dwordx4 v132, s[22:23]
	s_add_i32 m0, s33, 0x2000
	s_add_u32 s72, s22, 0x100000
	s_addc_u32 s73, s23, 0
	s_add_i32 s33, s53, s29
	global_load_lds_dwordx4 v136, s[22:23]
	s_mov_b32 m0, s33
	s_add_u32 s100, s26, 0x80
	s_addc_u32 s101, s27, 0
	global_load_lds_dwordx4 v132, s[72:73]
	s_add_i32 m0, s33, 0x2000
	s_nop 0
	global_load_lds_dwordx4 v136, s[72:73]
	s_mov_b32 m0, s21
	s_nop 0
	global_load_lds_dwordx4 v130, s[26:27]
	s_mov_b32 m0, s36
	s_nop 0
	global_load_lds_dwordx4 v134, s[26:27]
	s_waitcnt vmcnt(8)
	s_waitcnt lgkmcnt(0)
	s_barrier
	s_waitcnt lgkmcnt(0)
	v_mfma_f32_16x16x32_bf16 v[58:61], v[160:163], v[194:197], v[58:61]
	v_mfma_f32_16x16x32_bf16 v[58:61], v[166:169], v[198:201], v[58:61]
	v_mfma_f32_16x16x32_bf16 v[42:45], v[166:169], v[206:209], v[42:45]
	v_mfma_f32_16x16x32_bf16 v[42:45], v[160:163], v[202:205], v[42:45]
	v_mfma_f32_16x16x32_bf16 v[26:29], v[160:163], v[210:213], v[26:29]
	v_mfma_f32_16x16x32_bf16 v[26:29], v[166:169], v[214:217], v[26:29]
	v_mfma_f32_16x16x32_bf16 v[10:13], v[166:169], v[222:225], v[10:13]
	v_mfma_f32_16x16x32_bf16 v[10:13], v[160:163], v[218:221], v[10:13]
	v_mfma_f32_16x16x32_bf16 v[2:5], v[170:173], v[218:221], v[2:5]
	v_mfma_f32_16x16x32_bf16 v[2:5], v[174:177], v[222:225], v[2:5]
	v_mfma_f32_16x16x32_bf16 v[18:21], v[174:177], v[214:217], v[18:21]
	v_mfma_f32_16x16x32_bf16 v[18:21], v[170:173], v[210:213], v[18:21]
	v_mfma_f32_16x16x32_bf16 v[34:37], v[170:173], v[202:205], v[34:37]
	v_mfma_f32_16x16x32_bf16 v[34:37], v[174:177], v[206:209], v[34:37]
	v_mfma_f32_16x16x32_bf16 v[50:53], v[174:177], v[198:201], v[50:53]
	v_mfma_f32_16x16x32_bf16 v[50:53], v[170:173], v[194:197], v[50:53]
	v_mfma_f32_16x16x32_bf16 v[66:69], v[178:181], v[194:197], v[66:69]
	v_mfma_f32_16x16x32_bf16 v[66:69], v[182:185], v[198:201], v[66:69]
	v_mfma_f32_16x16x32_bf16 v[46:49], v[182:185], v[206:209], v[46:49]
	v_mfma_f32_16x16x32_bf16 v[46:49], v[178:181], v[202:205], v[46:49]
	v_mfma_f32_16x16x32_bf16 v[30:33], v[178:181], v[210:213], v[30:33]
	v_mfma_f32_16x16x32_bf16 v[30:33], v[182:185], v[214:217], v[30:33]
	v_mfma_f32_16x16x32_bf16 v[14:17], v[182:185], v[222:225], v[14:17]
	v_mfma_f32_16x16x32_bf16 v[14:17], v[178:181], v[218:221], v[14:17]
	v_mfma_f32_16x16x32_bf16 v[6:9], v[186:189], v[218:221], v[6:9]
	v_mfma_f32_16x16x32_bf16 v[6:9], v[190:193], v[222:225], v[6:9]
	v_mfma_f32_16x16x32_bf16 v[22:25], v[190:193], v[214:217], v[22:25]
	v_mfma_f32_16x16x32_bf16 v[22:25], v[186:189], v[210:213], v[22:25]
	v_mfma_f32_16x16x32_bf16 v[38:41], v[186:189], v[202:205], v[38:41]
	v_mfma_f32_16x16x32_bf16 v[38:41], v[190:193], v[206:209], v[38:41]
	v_mfma_f32_16x16x32_bf16 v[54:57], v[190:193], v[198:201], v[54:57]
	v_mfma_f32_16x16x32_bf16 v[54:57], v[186:189], v[194:197], v[54:57]
	s_barrier
; #define PG8_STAGE(bufoff, gbase, voff) do { _Pragma("unroll") for (int _i = 0; _i < 2; ++_i) \
;         __builtin_amdgcn_global_load_lds((const unsigned*)((const char*)(gbase) + (voff)[_i]), (PG8_LAS unsigned*)(lds + (bufoff) + ldsw + _i * 8192), 16, 0, 0); } while (0)
; #define PG8_LDA(dst, b, h) do { _Pragma("unroll") for (int m = 0; m < 4; ++m) _Pragma("unroll") for (int k = 0; k < 2; ++k) dst[m][k] = *(const PG8_LAS bf16x8*)(lds + PG8_SA(b, h) + aoff + m * 2048 + k * 1024); } while (0)
; #define PG8_LDB(dst, b, h) do { _Pragma("unroll") for (int n = 0; n < 2; ++n) _Pragma("unroll") for (int k = 0; k < 2; ++k) dst[n][k] = *(const PG8_LAS bf16x8*)(lds + PG8_SB(b, h) + boff + n * 2048 + k * 1024); } while (0)
; #define PG8_MMA(ai, bj, At, Bt) do { __builtin_amdgcn_s_setprio(1); _Pragma("unroll") for (int m = 0; m < 4; ++m) _Pragma("unroll") for (int n = 0; n < 2; ++n) _Pragma("unroll") for (int k = 0; k < 2; ++k) \
;         acc[ai][bj][m][n] = __builtin_amdgcn_mfma_f32_16x16x32_bf16(Bt[n][k], At[m][k], acc[ai][bj][m][n], 0, 0, 0); __builtin_amdgcn_s_setprio(0); } while (0)
; #define PG8_WAIT_V(n) asm volatile("s_waitcnt vmcnt(" #n ")" ::: "memory")
; #define PG8_WAIT_L(n) asm volatile("s_waitcnt lgkmcnt(" #n ")" ::: "memory")
; #define PG8_BAR __builtin_amdgcn_s_barrier()
; template <class Epi, class Sched, bool ALIGN_EPI = false, bool SP2 = false>
; __device__ __forceinline__ void gemm_phase(PG8_LAS unsigned char* lds, const Gemm g, const Sched& S, const Epi& E) {
;     ...
;         for (int t = 0; t < nt; t += 2) {
;             const bool last = (t == nt - 2);
;             const char* a1 = cA + (size_t)(t + 1) * kstep;
;             const char* a2 = last ? nA : cA + (size_t)(t + 2) * kstep; const char* b2 = last ? nB : cB + (size_t)(t + 2) * kstep;
;             const char* a3 = a2 + kstep; const char* b3 = b2 + kstep;
;     ...
;             PG8_LDB(B0, 1, 0); PG8_LDB(B1, 1, 1); PG8_SCHED; PG8_LDA(At, 1, 0); PG8_STAGE(PG8_SA(0, 1), a2 + hstep, voffA);
;             PG8_WAIT_V(8); PG8_WAIT_L(0); PG8_BAR; PG8_MMA(0, 0, At, B0); PG8_MMA(0, 1, At, B1); PG8_BAR; PG8_SCHED;
;             PG8_LDA(At, 1, 1); PG8_STAGE(PG8_SB(1, 0), b3, voffB); PG8_STAGE(PG8_SB(1, 1), b3 + hstep, voffB); PG8_STAGE(PG8_SA(1, 0), a3, voffA);
;             PG8_WAIT_V(8); PG8_WAIT_L(0); PG8_BAR; PG8_MMA(1, 0, At, B0); PG8_MMA(1, 1, At, B1); PG8_BAR; PG8_SCHED;
	s_add_i32 s33, 0, 0x18000
	s_add_i32 s42, 0, 0x1c000
	ds_read_b128 v[160:163], v241 offset:32768
	ds_read_b128 v[166:169], v241 offset:33792
	ds_read_b128 v[170:173], v241 offset:34816
	ds_read_b128 v[174:177], v241 offset:35840
	ds_read_b128 v[178:181], v241 offset:49152
	ds_read_b128 v[182:185], v241 offset:50176
	ds_read_b128 v[186:189], v241 offset:51200
	ds_read_b128 v[190:193], v241 offset:52224
	s_add_u32 s26, s26, 0x100000
	s_addc_u32 s27, s27, 0
	s_mov_b32 m0, s37
	ds_read_b128 v[194:197], v155 offset:32768
	ds_read_b128 v[198:201], v155 offset:33792
	ds_read_b128 v[202:205], v155 offset:34816
	ds_read_b128 v[206:209], v155 offset:35840
	ds_read_b128 v[210:213], v155 offset:36864
	ds_read_b128 v[214:217], v155 offset:37888
	ds_read_b128 v[218:221], v155 offset:38912
	ds_read_b128 v[222:225], v155 offset:39936
	global_load_lds_dwordx4 v130, s[26:27]
	s_mov_b32 m0, s40
	s_nop 0
	global_load_lds_dwordx4 v134, s[26:27]
	s_waitcnt vmcnt(8)
	s_waitcnt lgkmcnt(0)
	s_barrier
	s_waitcnt lgkmcnt(0)
	v_mfma_f32_16x16x32_bf16 v[122:125], v[160:163], v[194:197], v[122:125]
	v_mfma_f32_16x16x32_bf16 v[122:125], v[166:169], v[198:201], v[122:125]
	v_mfma_f32_16x16x32_bf16 v[106:109], v[166:169], v[206:209], v[106:109]
	v_mfma_f32_16x16x32_bf16 v[106:109], v[160:163], v[202:205], v[106:109]
	v_mfma_f32_16x16x32_bf16 v[90:93], v[160:163], v[210:213], v[90:93]
	v_mfma_f32_16x16x32_bf16 v[90:93], v[166:169], v[214:217], v[90:93]
	v_mfma_f32_16x16x32_bf16 v[74:77], v[166:169], v[222:225], v[74:77]
	v_mfma_f32_16x16x32_bf16 v[74:77], v[160:163], v[218:221], v[74:77]
	v_mfma_f32_16x16x32_bf16 v[62:65], v[170:173], v[218:221], v[62:65]
	v_mfma_f32_16x16x32_bf16 v[62:65], v[174:177], v[222:225], v[62:65]
	v_mfma_f32_16x16x32_bf16 v[82:85], v[174:177], v[214:217], v[82:85]
	v_mfma_f32_16x16x32_bf16 v[82:85], v[170:173], v[210:213], v[82:85]
	v_mfma_f32_16x16x32_bf16 v[98:101], v[170:173], v[202:205], v[98:101]
	v_mfma_f32_16x16x32_bf16 v[98:101], v[174:177], v[206:209], v[98:101]
	v_mfma_f32_16x16x32_bf16 v[114:117], v[174:177], v[198:201], v[114:117]
	v_mfma_f32_16x16x32_bf16 v[114:117], v[170:173], v[194:197], v[114:117]
	v_mfma_f32_16x16x32_bf16 v[126:129], v[178:181], v[194:197], v[126:129]
	v_mfma_f32_16x16x32_bf16 v[126:129], v[182:185], v[198:201], v[126:129]
	v_mfma_f32_16x16x32_bf16 v[110:113], v[182:185], v[206:209], v[110:113]
	v_mfma_f32_16x16x32_bf16 v[110:113], v[178:181], v[202:205], v[110:113]
	v_mfma_f32_16x16x32_bf16 v[94:97], v[178:181], v[210:213], v[94:97]
	v_mfma_f32_16x16x32_bf16 v[94:97], v[182:185], v[214:217], v[94:97]
	v_mfma_f32_16x16x32_bf16 v[78:81], v[182:185], v[222:225], v[78:81]
	v_mfma_f32_16x16x32_bf16 v[78:81], v[178:181], v[218:221], v[78:81]
	v_mfma_f32_16x16x32_bf16 v[70:73], v[186:189], v[218:221], v[70:73]
	v_mfma_f32_16x16x32_bf16 v[70:73], v[190:193], v[222:225], v[70:73]
	v_mfma_f32_16x16x32_bf16 v[86:89], v[190:193], v[214:217], v[86:89]
	v_mfma_f32_16x16x32_bf16 v[86:89], v[186:189], v[210:213], v[86:89]
	v_mfma_f32_16x16x32_bf16 v[102:105], v[186:189], v[202:205], v[102:105]
	v_mfma_f32_16x16x32_bf16 v[102:105], v[190:193], v[206:209], v[102:105]
	v_mfma_f32_16x16x32_bf16 v[118:121], v[190:193], v[198:201], v[118:121]
	v_mfma_f32_16x16x32_bf16 v[118:121], v[186:189], v[194:197], v[118:121]
	s_barrier
	s_add_i32 s26, s33, s29
	s_add_i32 m0, s26, 0xffffff80
	ds_read_b128 v[194:197], v155 offset:49152
	ds_read_b128 v[198:201], v155 offset:50176
	ds_read_b128 v[202:205], v155 offset:51200
	ds_read_b128 v[206:209], v155 offset:52224
	ds_read_b128 v[210:213], v155 offset:53248
	ds_read_b128 v[214:217], v155 offset:54272
	ds_read_b128 v[218:221], v155 offset:55296
	ds_read_b128 v[222:225], v155 offset:56320
	global_load_lds_dwordx4 v132, s[22:23] offset:128
	s_add_i32 m0, s26, 0x1f80
	s_add_i32 s26, s42, s29
	global_load_lds_dwordx4 v136, s[22:23] offset:128
	s_add_u32 s22, s22, 0x100080
	s_addc_u32 s23, s23, 0
	s_mov_b32 m0, s26
	s_nop 0
	global_load_lds_dwordx4 v132, s[22:23]
	s_add_i32 m0, s26, 0x2000
	s_nop 0
	global_load_lds_dwordx4 v136, s[22:23]
	s_mov_b32 m0, s46
	s_nop 0
	global_load_lds_dwordx4 v130, s[100:101]
	s_mov_b32 m0, s47
	s_nop 0
	global_load_lds_dwordx4 v134, s[100:101]
	s_waitcnt vmcnt(8)
	s_waitcnt lgkmcnt(0)
	s_barrier
	s_waitcnt lgkmcnt(0)
	v_mfma_f32_16x16x32_bf16 v[58:61], v[160:163], v[194:197], v[58:61]
	v_mfma_f32_16x16x32_bf16 v[58:61], v[166:169], v[198:201], v[58:61]
	v_mfma_f32_16x16x32_bf16 v[42:45], v[166:169], v[206:209], v[42:45]
	v_mfma_f32_16x16x32_bf16 v[42:45], v[160:163], v[202:205], v[42:45]
	v_mfma_f32_16x16x32_bf16 v[26:29], v[160:163], v[210:213], v[26:29]
	v_mfma_f32_16x16x32_bf16 v[26:29], v[166:169], v[214:217], v[26:29]
	v_mfma_f32_16x16x32_bf16 v[10:13], v[166:169], v[222:225], v[10:13]
	v_mfma_f32_16x16x32_bf16 v[10:13], v[160:163], v[218:221], v[10:13]
	v_mfma_f32_16x16x32_bf16 v[2:5], v[170:173], v[218:221], v[2:5]
	v_mfma_f32_16x16x32_bf16 v[2:5], v[174:177], v[222:225], v[2:5]
	v_mfma_f32_16x16x32_bf16 v[18:21], v[174:177], v[214:217], v[18:21]
	v_mfma_f32_16x16x32_bf16 v[18:21], v[170:173], v[210:213], v[18:21]
	v_mfma_f32_16x16x32_bf16 v[34:37], v[170:173], v[202:205], v[34:37]
	v_mfma_f32_16x16x32_bf16 v[34:37], v[174:177], v[206:209], v[34:37]
	v_mfma_f32_16x16x32_bf16 v[50:53], v[174:177], v[198:201], v[50:53]
	v_mfma_f32_16x16x32_bf16 v[50:53], v[170:173], v[194:197], v[50:53]
	v_mfma_f32_16x16x32_bf16 v[66:69], v[178:181], v[194:197], v[66:69]
	v_mfma_f32_16x16x32_bf16 v[66:69], v[182:185], v[198:201], v[66:69]
	v_mfma_f32_16x16x32_bf16 v[46:49], v[182:185], v[206:209], v[46:49]
	v_mfma_f32_16x16x32_bf16 v[46:49], v[178:181], v[202:205], v[46:49]
	v_mfma_f32_16x16x32_bf16 v[30:33], v[178:181], v[210:213], v[30:33]
	v_mfma_f32_16x16x32_bf16 v[30:33], v[182:185], v[214:217], v[30:33]
	v_mfma_f32_16x16x32_bf16 v[14:17], v[182:185], v[222:225], v[14:17]
	v_mfma_f32_16x16x32_bf16 v[14:17], v[178:181], v[218:221], v[14:17]
	v_mfma_f32_16x16x32_bf16 v[6:9], v[186:189], v[218:221], v[6:9]
	v_mfma_f32_16x16x32_bf16 v[6:9], v[190:193], v[222:225], v[6:9]
	v_mfma_f32_16x16x32_bf16 v[22:25], v[190:193], v[214:217], v[22:25]
	v_mfma_f32_16x16x32_bf16 v[22:25], v[186:189], v[210:213], v[22:25]
	v_mfma_f32_16x16x32_bf16 v[38:41], v[186:189], v[202:205], v[38:41]
	v_mfma_f32_16x16x32_bf16 v[38:41], v[190:193], v[206:209], v[38:41]
	v_mfma_f32_16x16x32_bf16 v[54:57], v[190:193], v[198:201], v[54:57]
	v_mfma_f32_16x16x32_bf16 v[54:57], v[186:189], v[194:197], v[54:57]
	s_barrier
	s_add_i32 s68, s68, 2
	s_add_u32 s24, s24, 0x100
	s_addc_u32 s25, s25, 0
	s_add_u32 s66, s66, 0x100
	s_addc_u32 s67, s67, 0
	s_cmp_gt_u32 s68, 61
	s_cbranch_scc0 .LBB0_1126
	s_and_b64 vcc, exec, s[8:9]
	s_cbranch_vccz .LBB0_1129
	s_barrier

; #define PG8_STAGE(bufoff, gbase, voff) do { _Pragma("unroll") for (int _i = 0; _i < 2; ++_i) \
;         __builtin_amdgcn_global_load_lds((const unsigned*)((const char*)(gbase) + (voff)[_i]), (PG8_LAS unsigned*)(lds + (bufoff) + ldsw + _i * 8192), 16, 0, 0); } while (0)
; #define PG8_LDA(dst, b, h) do { _Pragma("unroll") for (int m = 0; m < 4; ++m) _Pragma("unroll") for (int k = 0; k < 2; ++k) dst[m][k] = *(const PG8_LAS bf16x8*)(lds + PG8_SA(b, h) + aoff + m * 2048 + k * 1024); } while (0)
; #define PG8_LDB(dst, b, h) do { _Pragma("unroll") for (int n = 0; n < 2; ++n) _Pragma("unroll") for (int k = 0; k < 2; ++k) dst[n][k] = *(const PG8_LAS bf16x8*)(lds + PG8_SB(b, h) + boff + n * 2048 + k * 1024); } while (0)
; #define PG8_MMA(ai, bj, At, Bt) do { __builtin_amdgcn_s_setprio(1); _Pragma("unroll") for (int m = 0; m < 4; ++m) _Pragma("unroll") for (int n = 0; n < 2; ++n) _Pragma("unroll") for (int k = 0; k < 2; ++k) \
;         acc[ai][bj][m][n] = __builtin_amdgcn_mfma_f32_16x16x32_bf16(Bt[n][k], At[m][k], acc[ai][bj][m][n], 0, 0, 0); __builtin_amdgcn_s_setprio(0); } while (0)
; #define PG8_WAIT_V(n) asm volatile("s_waitcnt vmcnt(" #n ")" ::: "memory")
; #define PG8_WAIT_L(n) asm volatile("s_waitcnt lgkmcnt(" #n ")" ::: "memory")
; #define PG8_BAR __builtin_amdgcn_s_barrier()
; #define PG8_SCHED __builtin_amdgcn_sched_barrier(0)
; template <class Epi, class Sched, bool ALIGN_EPI = false, bool SP2 = false>
; __device__ __forceinline__ void gemm_phase(PG8_LAS unsigned char* lds, const Gemm g, const Sched& S, const Epi& E) {
;     ...
;             PG8_LDB(B0, 0, 0); PG8_LDB(B1, 0, 1); PG8_SCHED; PG8_LDA(At, 0, 0); PG8_STAGE(PG8_SA(1, 1), a1 + hstep, voffA);
;             PG8_WAIT_V(8); PG8_WAIT_L(0); PG8_BAR; PG8_MMA(0, 0, At, B0); PG8_MMA(0, 1, At, B1); PG8_BAR; PG8_SCHED;
;             PG8_LDA(At, 0, 1); PG8_STAGE(PG8_SB(0, 0), b2, voffB); PG8_STAGE(PG8_SB(0, 1), b2 + hstep, voffB); PG8_STAGE(PG8_SA(0, 0), a2, voffA);
;             PG8_WAIT_V(8); PG8_WAIT_L(0); PG8_BAR; PG8_MMA(1, 0, At, B0); PG8_MMA(1, 1, At, B1); PG8_BAR; PG8_SCHED;
.LBB0_1245:
	ds_read_b128 v[130:133], v241 offset:0
	ds_read_b128 v[134:137], v241 offset:1024
	ds_read_b128 v[138:141], v241 offset:2048
	ds_read_b128 v[142:145], v241 offset:3072
	ds_read_b128 v[146:149], v241 offset:16384
	ds_read_b128 v[150:153], v241 offset:17408
	ds_read_b128 v[172:175], v241 offset:18432
	ds_read_b128 v[176:179], v241 offset:19456
	s_add_u32 s16, s18, 0xffd50080
	s_addc_u32 s17, s19, -1
	s_cmpk_eq_i32 s64, 0xa8
	s_cselect_b32 s21, s5, s17
	s_cselect_b32 s20, s4, s16
	s_cselect_b32 s17, s15, s63
	s_cselect_b32 s16, s14, s62
	s_add_i32 m0, s25, 0xc000
	ds_read_b128 v[180:183], v185
	ds_read_b128 v[188:191], v185 offset:1024
	ds_read_b128 v[192:195], v185 offset:2048
	ds_read_b128 v[196:199], v185 offset:3072
	ds_read_b128 v[200:203], v185 offset:4096
	ds_read_b128 v[204:207], v185 offset:5120
	ds_read_b128 v[208:211], v185 offset:6144
	ds_read_b128 v[212:215], v185 offset:7168
	global_load_lds_dwordx4 v162, s[18:19]
	s_add_i32 m0, s25, 0xe000
	s_nop 0
	global_load_lds_dwordx4 v166, s[18:19]
	s_waitcnt vmcnt(8)
	s_waitcnt lgkmcnt(0)
	s_barrier
	s_waitcnt lgkmcnt(0)
	v_mfma_f32_16x16x32_bf16 v[114:117], v[130:133], v[180:183], v[114:117]
	v_mfma_f32_16x16x32_bf16 v[114:117], v[134:137], v[188:191], v[114:117]
	v_mfma_f32_16x16x32_bf16 v[106:109], v[134:137], v[196:199], v[106:109]
	v_mfma_f32_16x16x32_bf16 v[106:109], v[130:133], v[192:195], v[106:109]
	v_mfma_f32_16x16x32_bf16 v[90:93], v[130:133], v[200:203], v[90:93]
	v_mfma_f32_16x16x32_bf16 v[90:93], v[134:137], v[204:207], v[90:93]
	v_mfma_f32_16x16x32_bf16 v[74:77], v[134:137], v[212:215], v[74:77]
	v_mfma_f32_16x16x32_bf16 v[74:77], v[130:133], v[208:211], v[74:77]
	v_mfma_f32_16x16x32_bf16 v[66:69], v[138:141], v[208:211], v[66:69]
	v_mfma_f32_16x16x32_bf16 v[66:69], v[142:145], v[212:215], v[66:69]
	v_mfma_f32_16x16x32_bf16 v[82:85], v[142:145], v[204:207], v[82:85]
	v_mfma_f32_16x16x32_bf16 v[82:85], v[138:141], v[200:203], v[82:85]
	v_mfma_f32_16x16x32_bf16 v[98:101], v[138:141], v[192:195], v[98:101]
	v_mfma_f32_16x16x32_bf16 v[98:101], v[142:145], v[196:199], v[98:101]
	v_mfma_f32_16x16x32_bf16 v[118:121], v[142:145], v[188:191], v[118:121]
	v_mfma_f32_16x16x32_bf16 v[118:121], v[138:141], v[180:183], v[118:121]
	v_mfma_f32_16x16x32_bf16 v[122:125], v[146:149], v[180:183], v[122:125]
	v_mfma_f32_16x16x32_bf16 v[122:125], v[150:153], v[188:191], v[122:125]
	v_mfma_f32_16x16x32_bf16 v[110:113], v[150:153], v[196:199], v[110:113]
	v_mfma_f32_16x16x32_bf16 v[110:113], v[146:149], v[192:195], v[110:113]
	v_mfma_f32_16x16x32_bf16 v[94:97], v[146:149], v[200:203], v[94:97]
	v_mfma_f32_16x16x32_bf16 v[94:97], v[150:153], v[204:207], v[94:97]
	v_mfma_f32_16x16x32_bf16 v[78:81], v[150:153], v[212:215], v[78:81]
	v_mfma_f32_16x16x32_bf16 v[78:81], v[146:149], v[208:211], v[78:81]
	v_mfma_f32_16x16x32_bf16 v[70:73], v[172:175], v[208:211], v[70:73]
	v_mfma_f32_16x16x32_bf16 v[70:73], v[176:179], v[212:215], v[70:73]
	v_mfma_f32_16x16x32_bf16 v[86:89], v[176:179], v[204:207], v[86:89]
	v_mfma_f32_16x16x32_bf16 v[86:89], v[172:175], v[200:203], v[86:89]
	v_mfma_f32_16x16x32_bf16 v[102:105], v[172:175], v[192:195], v[102:105]
	v_mfma_f32_16x16x32_bf16 v[102:105], v[176:179], v[196:199], v[102:105]
	v_mfma_f32_16x16x32_bf16 v[126:129], v[176:179], v[188:191], v[126:129]
	v_mfma_f32_16x16x32_bf16 v[126:129], v[172:175], v[180:183], v[126:129]
	s_barrier
	s_add_i32 s33, s40, s24
	s_mov_b32 m0, s33
	ds_read_b128 v[180:183], v185 offset:16384
	ds_read_b128 v[188:191], v185 offset:17408
	ds_read_b128 v[192:195], v185 offset:18432
	ds_read_b128 v[196:199], v185 offset:19456
	ds_read_b128 v[200:203], v185 offset:20480
	ds_read_b128 v[204:207], v185 offset:21504
	ds_read_b128 v[208:211], v185 offset:22528
	ds_read_b128 v[212:215], v185 offset:23552
	global_load_lds_dwordx4 v156, s[16:17]
	s_add_i32 m0, s33, 0x2000
	s_add_u32 s66, s16, 0x2b0000
	s_addc_u32 s67, s17, 0
	s_add_i32 s33, s41, s24
	global_load_lds_dwordx4 v160, s[16:17]
	s_mov_b32 m0, s33
	s_add_u32 s100, s20, 0x80
	s_addc_u32 s101, s21, 0
	global_load_lds_dwordx4 v156, s[66:67]
	s_add_i32 m0, s33, 0x2000
	s_nop 0
	global_load_lds_dwordx4 v160, s[66:67]
	s_mov_b32 m0, s25
	s_nop 0
	global_load_lds_dwordx4 v154, s[20:21]
	s_mov_b32 m0, s26
	s_nop 0
	global_load_lds_dwordx4 v158, s[20:21]
	s_waitcnt vmcnt(8)
	s_waitcnt lgkmcnt(0)
	s_barrier
	s_waitcnt lgkmcnt(0)
	v_mfma_f32_16x16x32_bf16 v[58:61], v[130:133], v[180:183], v[58:61]
	v_mfma_f32_16x16x32_bf16 v[58:61], v[134:137], v[188:191], v[58:61]
	v_mfma_f32_16x16x32_bf16 v[42:45], v[134:137], v[196:199], v[42:45]
	v_mfma_f32_16x16x32_bf16 v[42:45], v[130:133], v[192:195], v[42:45]
	v_mfma_f32_16x16x32_bf16 v[26:29], v[130:133], v[200:203], v[26:29]
	v_mfma_f32_16x16x32_bf16 v[26:29], v[134:137], v[204:207], v[26:29]
	v_mfma_f32_16x16x32_bf16 v[6:9], v[134:137], v[212:215], v[6:9]
	v_mfma_f32_16x16x32_bf16 v[6:9], v[130:133], v[208:211], v[6:9]
	v_mfma_f32_16x16x32_bf16 v[2:5], v[138:141], v[208:211], v[2:5]
	v_mfma_f32_16x16x32_bf16 v[2:5], v[142:145], v[212:215], v[2:5]
	v_mfma_f32_16x16x32_bf16 v[18:21], v[142:145], v[204:207], v[18:21]
	v_mfma_f32_16x16x32_bf16 v[18:21], v[138:141], v[200:203], v[18:21]
	v_mfma_f32_16x16x32_bf16 v[34:37], v[138:141], v[192:195], v[34:37]
	v_mfma_f32_16x16x32_bf16 v[34:37], v[142:145], v[196:199], v[34:37]
	v_mfma_f32_16x16x32_bf16 v[54:57], v[142:145], v[188:191], v[54:57]
	v_mfma_f32_16x16x32_bf16 v[54:57], v[138:141], v[180:183], v[54:57]
	v_mfma_f32_16x16x32_bf16 v[62:65], v[146:149], v[180:183], v[62:65]
	v_mfma_f32_16x16x32_bf16 v[62:65], v[150:153], v[188:191], v[62:65]
	v_mfma_f32_16x16x32_bf16 v[46:49], v[150:153], v[196:199], v[46:49]
	v_mfma_f32_16x16x32_bf16 v[46:49], v[146:149], v[192:195], v[46:49]
	v_mfma_f32_16x16x32_bf16 v[30:33], v[146:149], v[200:203], v[30:33]
	v_mfma_f32_16x16x32_bf16 v[30:33], v[150:153], v[204:207], v[30:33]
	v_mfma_f32_16x16x32_bf16 v[10:13], v[150:153], v[212:215], v[10:13]
	v_mfma_f32_16x16x32_bf16 v[10:13], v[146:149], v[208:211], v[10:13]
	v_mfma_f32_16x16x32_bf16 v[14:17], v[172:175], v[208:211], v[14:17]
	v_mfma_f32_16x16x32_bf16 v[14:17], v[176:179], v[212:215], v[14:17]
	v_mfma_f32_16x16x32_bf16 v[22:25], v[176:179], v[204:207], v[22:25]
	v_mfma_f32_16x16x32_bf16 v[22:25], v[172:175], v[200:203], v[22:25]
	v_mfma_f32_16x16x32_bf16 v[38:41], v[172:175], v[192:195], v[38:41]
	v_mfma_f32_16x16x32_bf16 v[38:41], v[176:179], v[196:199], v[38:41]
	v_mfma_f32_16x16x32_bf16 v[50:53], v[176:179], v[188:191], v[50:53]
	v_mfma_f32_16x16x32_bf16 v[50:53], v[172:175], v[180:183], v[50:53]
	s_barrier
; #define PG8_STAGE(bufoff, gbase, voff) do { _Pragma("unroll") for (int _i = 0; _i < 2; ++_i) \
;         __builtin_amdgcn_global_load_lds((const unsigned*)((const char*)(gbase) + (voff)[_i]), (PG8_LAS unsigned*)(lds + (bufoff) + ldsw + _i * 8192), 16, 0, 0); } while (0)
; #define PG8_LDA(dst, b, h) do { _Pragma("unroll") for (int m = 0; m < 4; ++m) _Pragma("unroll") for (int k = 0; k < 2; ++k) dst[m][k] = *(const PG8_LAS bf16x8*)(lds + PG8_SA(b, h) + aoff + m * 2048 + k * 1024); } while (0)
; #define PG8_LDB(dst, b, h) do { _Pragma("unroll") for (int n = 0; n < 2; ++n) _Pragma("unroll") for (int k = 0; k < 2; ++k) dst[n][k] = *(const PG8_LAS bf16x8*)(lds + PG8_SB(b, h) + boff + n * 2048 + k * 1024); } while (0)
; #define PG8_MMA(ai, bj, At, Bt) do { __builtin_amdgcn_s_setprio(1); _Pragma("unroll") for (int m = 0; m < 4; ++m) _Pragma("unroll") for (int n = 0; n < 2; ++n) _Pragma("unroll") for (int k = 0; k < 2; ++k) \
;         acc[ai][bj][m][n] = __builtin_amdgcn_mfma_f32_16x16x32_bf16(Bt[n][k], At[m][k], acc[ai][bj][m][n], 0, 0, 0); __builtin_amdgcn_s_setprio(0); } while (0)
; #define PG8_WAIT_V(n) asm volatile("s_waitcnt vmcnt(" #n ")" ::: "memory")
; #define PG8_WAIT_L(n) asm volatile("s_waitcnt lgkmcnt(" #n ")" ::: "memory")
; #define PG8_BAR __builtin_amdgcn_s_barrier()
; template <class Epi, class Sched, bool ALIGN_EPI = false, bool SP2 = false>
; __device__ __forceinline__ void gemm_phase(PG8_LAS unsigned char* lds, const Gemm g, const Sched& S, const Epi& E) {
;     ...
;         for (int t = 0; t < nt; t += 2) {
;             const bool last = (t == nt - 2);
;             const char* a1 = cA + (size_t)(t + 1) * kstep;
;             const char* a2 = last ? nA : cA + (size_t)(t + 2) * kstep; const char* b2 = last ? nB : cB + (size_t)(t + 2) * kstep;
;             const char* a3 = a2 + kstep; const char* b3 = b2 + kstep;
;     ...
;             PG8_LDB(B0, 1, 0); PG8_LDB(B1, 1, 1); PG8_SCHED; PG8_LDA(At, 1, 0); PG8_STAGE(PG8_SA(0, 1), a2 + hstep, voffA);
;             PG8_WAIT_V(8); PG8_WAIT_L(0); PG8_BAR; PG8_MMA(0, 0, At, B0); PG8_MMA(0, 1, At, B1); PG8_BAR; PG8_SCHED;
;             PG8_LDA(At, 1, 1); PG8_STAGE(PG8_SB(1, 0), b3, voffB); PG8_STAGE(PG8_SB(1, 1), b3 + hstep, voffB); PG8_STAGE(PG8_SA(1, 0), a3, voffA);
;             PG8_WAIT_V(8); PG8_WAIT_L(0); PG8_BAR; PG8_MMA(1, 0, At, B0); PG8_MMA(1, 1, At, B1); PG8_BAR; PG8_SCHED;
	s_add_i32 s33, 0, 0x18000
	s_add_i32 s42, 0, 0x1c000
	ds_read_b128 v[130:133], v241 offset:32768
	ds_read_b128 v[134:137], v241 offset:33792
	ds_read_b128 v[138:141], v241 offset:34816
	ds_read_b128 v[142:145], v241 offset:35840
	ds_read_b128 v[146:149], v241 offset:49152
	ds_read_b128 v[150:153], v241 offset:50176
	ds_read_b128 v[172:175], v241 offset:51200
	ds_read_b128 v[176:179], v241 offset:52224
	s_add_u32 s20, s20, 0x2b0000
	s_addc_u32 s21, s21, 0
	s_mov_b32 m0, s27
	ds_read_b128 v[180:183], v185 offset:32768
	ds_read_b128 v[188:191], v185 offset:33792
	ds_read_b128 v[192:195], v185 offset:34816
	ds_read_b128 v[196:199], v185 offset:35840
	ds_read_b128 v[200:203], v185 offset:36864
	ds_read_b128 v[204:207], v185 offset:37888
	ds_read_b128 v[208:211], v185 offset:38912
	ds_read_b128 v[212:215], v185 offset:39936
	global_load_lds_dwordx4 v154, s[20:21]
	s_mov_b32 m0, s28
	s_nop 0
	global_load_lds_dwordx4 v158, s[20:21]
	s_waitcnt vmcnt(8)
	s_waitcnt lgkmcnt(0)
	s_barrier
	s_waitcnt lgkmcnt(0)
	v_mfma_f32_16x16x32_bf16 v[114:117], v[130:133], v[180:183], v[114:117]
	v_mfma_f32_16x16x32_bf16 v[114:117], v[134:137], v[188:191], v[114:117]
	v_mfma_f32_16x16x32_bf16 v[106:109], v[134:137], v[196:199], v[106:109]
	v_mfma_f32_16x16x32_bf16 v[106:109], v[130:133], v[192:195], v[106:109]
	v_mfma_f32_16x16x32_bf16 v[90:93], v[130:133], v[200:203], v[90:93]
	v_mfma_f32_16x16x32_bf16 v[90:93], v[134:137], v[204:207], v[90:93]
	v_mfma_f32_16x16x32_bf16 v[74:77], v[134:137], v[212:215], v[74:77]
	v_mfma_f32_16x16x32_bf16 v[74:77], v[130:133], v[208:211], v[74:77]
	v_mfma_f32_16x16x32_bf16 v[66:69], v[138:141], v[208:211], v[66:69]
	v_mfma_f32_16x16x32_bf16 v[66:69], v[142:145], v[212:215], v[66:69]
	v_mfma_f32_16x16x32_bf16 v[82:85], v[142:145], v[204:207], v[82:85]
	v_mfma_f32_16x16x32_bf16 v[82:85], v[138:141], v[200:203], v[82:85]
	v_mfma_f32_16x16x32_bf16 v[98:101], v[138:141], v[192:195], v[98:101]
	v_mfma_f32_16x16x32_bf16 v[98:101], v[142:145], v[196:199], v[98:101]
	v_mfma_f32_16x16x32_bf16 v[118:121], v[142:145], v[188:191], v[118:121]
	v_mfma_f32_16x16x32_bf16 v[118:121], v[138:141], v[180:183], v[118:121]
	v_mfma_f32_16x16x32_bf16 v[122:125], v[146:149], v[180:183], v[122:125]
	v_mfma_f32_16x16x32_bf16 v[122:125], v[150:153], v[188:191], v[122:125]
	v_mfma_f32_16x16x32_bf16 v[110:113], v[150:153], v[196:199], v[110:113]
	v_mfma_f32_16x16x32_bf16 v[110:113], v[146:149], v[192:195], v[110:113]
	v_mfma_f32_16x16x32_bf16 v[94:97], v[146:149], v[200:203], v[94:97]
	v_mfma_f32_16x16x32_bf16 v[94:97], v[150:153], v[204:207], v[94:97]
	v_mfma_f32_16x16x32_bf16 v[78:81], v[150:153], v[212:215], v[78:81]
	v_mfma_f32_16x16x32_bf16 v[78:81], v[146:149], v[208:211], v[78:81]
	v_mfma_f32_16x16x32_bf16 v[70:73], v[172:175], v[208:211], v[70:73]
	v_mfma_f32_16x16x32_bf16 v[70:73], v[176:179], v[212:215], v[70:73]
	v_mfma_f32_16x16x32_bf16 v[86:89], v[176:179], v[204:207], v[86:89]
	v_mfma_f32_16x16x32_bf16 v[86:89], v[172:175], v[200:203], v[86:89]
	v_mfma_f32_16x16x32_bf16 v[102:105], v[172:175], v[192:195], v[102:105]
	v_mfma_f32_16x16x32_bf16 v[102:105], v[176:179], v[196:199], v[102:105]
	v_mfma_f32_16x16x32_bf16 v[126:129], v[176:179], v[188:191], v[126:129]
	v_mfma_f32_16x16x32_bf16 v[126:129], v[172:175], v[180:183], v[126:129]
	s_barrier
	s_add_i32 s20, s33, s24
	s_add_i32 m0, s20, 0xffffff80
	ds_read_b128 v[180:183], v185 offset:49152
	ds_read_b128 v[188:191], v185 offset:50176
	ds_read_b128 v[192:195], v185 offset:51200
	ds_read_b128 v[196:199], v185 offset:52224
	ds_read_b128 v[200:203], v185 offset:53248
	ds_read_b128 v[204:207], v185 offset:54272
	ds_read_b128 v[208:211], v185 offset:55296
	ds_read_b128 v[212:215], v185 offset:56320
	global_load_lds_dwordx4 v156, s[16:17] offset:128
	s_add_i32 m0, s20, 0x1f80
	s_add_i32 s20, s42, s24
	global_load_lds_dwordx4 v160, s[16:17] offset:128
	s_add_u32 s16, s16, 0x2b0080
	s_addc_u32 s17, s17, 0
	s_mov_b32 m0, s20
	s_nop 0
	global_load_lds_dwordx4 v156, s[16:17]
	s_add_i32 m0, s20, 0x2000
	s_nop 0
	global_load_lds_dwordx4 v160, s[16:17]
	s_mov_b32 m0, s34
	s_nop 0
	global_load_lds_dwordx4 v154, s[100:101]
	s_mov_b32 m0, s35
	s_nop 0
	global_load_lds_dwordx4 v158, s[100:101]
	s_waitcnt vmcnt(8)
	s_waitcnt lgkmcnt(0)
	s_barrier
	s_waitcnt lgkmcnt(0)
	v_mfma_f32_16x16x32_bf16 v[58:61], v[130:133], v[180:183], v[58:61]
	v_mfma_f32_16x16x32_bf16 v[58:61], v[134:137], v[188:191], v[58:61]
	v_mfma_f32_16x16x32_bf16 v[42:45], v[134:137], v[196:199], v[42:45]
	v_mfma_f32_16x16x32_bf16 v[42:45], v[130:133], v[192:195], v[42:45]
	v_mfma_f32_16x16x32_bf16 v[26:29], v[130:133], v[200:203], v[26:29]
	v_mfma_f32_16x16x32_bf16 v[26:29], v[134:137], v[204:207], v[26:29]
	v_mfma_f32_16x16x32_bf16 v[6:9], v[134:137], v[212:215], v[6:9]
	v_mfma_f32_16x16x32_bf16 v[6:9], v[130:133], v[208:211], v[6:9]
	v_mfma_f32_16x16x32_bf16 v[2:5], v[138:141], v[208:211], v[2:5]
	v_mfma_f32_16x16x32_bf16 v[2:5], v[142:145], v[212:215], v[2:5]
	v_mfma_f32_16x16x32_bf16 v[18:21], v[142:145], v[204:207], v[18:21]
	v_mfma_f32_16x16x32_bf16 v[18:21], v[138:141], v[200:203], v[18:21]
	v_mfma_f32_16x16x32_bf16 v[34:37], v[138:141], v[192:195], v[34:37]
	v_mfma_f32_16x16x32_bf16 v[34:37], v[142:145], v[196:199], v[34:37]
	v_mfma_f32_16x16x32_bf16 v[54:57], v[142:145], v[188:191], v[54:57]
	v_mfma_f32_16x16x32_bf16 v[54:57], v[138:141], v[180:183], v[54:57]
	v_mfma_f32_16x16x32_bf16 v[62:65], v[146:149], v[180:183], v[62:65]
	v_mfma_f32_16x16x32_bf16 v[62:65], v[150:153], v[188:191], v[62:65]
	v_mfma_f32_16x16x32_bf16 v[46:49], v[150:153], v[196:199], v[46:49]
	v_mfma_f32_16x16x32_bf16 v[46:49], v[146:149], v[192:195], v[46:49]
	v_mfma_f32_16x16x32_bf16 v[30:33], v[146:149], v[200:203], v[30:33]
	v_mfma_f32_16x16x32_bf16 v[30:33], v[150:153], v[204:207], v[30:33]
	v_mfma_f32_16x16x32_bf16 v[10:13], v[150:153], v[212:215], v[10:13]
	v_mfma_f32_16x16x32_bf16 v[10:13], v[146:149], v[208:211], v[10:13]
	v_mfma_f32_16x16x32_bf16 v[14:17], v[172:175], v[208:211], v[14:17]
	v_mfma_f32_16x16x32_bf16 v[14:17], v[176:179], v[212:215], v[14:17]
	v_mfma_f32_16x16x32_bf16 v[22:25], v[176:179], v[204:207], v[22:25]
	v_mfma_f32_16x16x32_bf16 v[22:25], v[172:175], v[200:203], v[22:25]
	v_mfma_f32_16x16x32_bf16 v[38:41], v[172:175], v[192:195], v[38:41]
	v_mfma_f32_16x16x32_bf16 v[38:41], v[176:179], v[196:199], v[38:41]
	v_mfma_f32_16x16x32_bf16 v[50:53], v[176:179], v[188:191], v[50:53]
	v_mfma_f32_16x16x32_bf16 v[50:53], v[172:175], v[180:183], v[50:53]
	s_barrier
	s_add_i32 s64, s64, 2
	s_add_u32 s18, s18, 0x100
	s_addc_u32 s19, s19, 0
	s_add_u32 s62, s62, 0x100
	s_addc_u32 s63, s63, 0
	s_cmpk_gt_u32 s64, 0xa9
	s_cbranch_scc0 .LBB0_1245
	s_and_b64 vcc, exec, s[12:13]
	s_cbranch_vccz .LBB0_1248
	s_barrier

; #define PG8_STAGE(bufoff, gbase, voff) do { _Pragma("unroll") for (int _i = 0; _i < 2; ++_i) \
;         __builtin_amdgcn_global_load_lds((const unsigned*)((const char*)(gbase) + (voff)[_i]), (PG8_LAS unsigned*)(lds + (bufoff) + ldsw + _i * 8192), 16, 0, 0); } while (0)
; #define PG8_LDA(dst, b, h) do { _Pragma("unroll") for (int m = 0; m < 4; ++m) _Pragma("unroll") for (int k = 0; k < 2; ++k) dst[m][k] = *(const PG8_LAS bf16x8*)(lds + PG8_SA(b, h) + aoff + m * 2048 + k * 1024); } while (0)
; #define PG8_LDB(dst, b, h) do { _Pragma("unroll") for (int n = 0; n < 2; ++n) _Pragma("unroll") for (int k = 0; k < 2; ++k) dst[n][k] = *(const PG8_LAS bf16x8*)(lds + PG8_SB(b, h) + boff + n * 2048 + k * 1024); } while (0)
; #define PG8_MMA(ai, bj, At, Bt) do { __builtin_amdgcn_s_setprio(1); _Pragma("unroll") for (int m = 0; m < 4; ++m) _Pragma("unroll") for (int n = 0; n < 2; ++n) _Pragma("unroll") for (int k = 0; k < 2; ++k) \
;         acc[ai][bj][m][n] = __builtin_amdgcn_mfma_f32_16x16x32_bf16(Bt[n][k], At[m][k], acc[ai][bj][m][n], 0, 0, 0); __builtin_amdgcn_s_setprio(0); } while (0)
; #define PG8_WAIT_V(n) asm volatile("s_waitcnt vmcnt(" #n ")" ::: "memory")
; #define PG8_WAIT_L(n) asm volatile("s_waitcnt lgkmcnt(" #n ")" ::: "memory")
; #define PG8_BAR __builtin_amdgcn_s_barrier()
; #define PG8_SCHED __builtin_amdgcn_sched_barrier(0)
; template <class Epi, class Sched, bool ALIGN_EPI = false, bool SP2 = false>
; __device__ __forceinline__ void gemm_phase(PG8_LAS unsigned char* lds, const Gemm g, const Sched& S, const Epi& E) {
;     ...
;             PG8_LDB(B0, 0, 0); PG8_LDB(B1, 0, 1); PG8_SCHED; PG8_LDA(At, 0, 0); PG8_STAGE(PG8_SA(1, 1), a1 + hstep, voffA);
;             PG8_WAIT_V(8); PG8_WAIT_L(0); PG8_BAR; PG8_MMA(0, 0, At, B0); PG8_MMA(0, 1, At, B1); PG8_BAR; PG8_SCHED;
;             PG8_LDA(At, 0, 1); PG8_STAGE(PG8_SB(0, 0), b2, voffB); PG8_STAGE(PG8_SB(0, 1), b2 + hstep, voffB); PG8_STAGE(PG8_SA(0, 0), a2, voffA);
;             PG8_WAIT_V(8); PG8_WAIT_L(0); PG8_BAR; PG8_MMA(1, 0, At, B0); PG8_MMA(1, 1, At, B1); PG8_BAR; PG8_SCHED;
.LBB0_1332:
	ds_read_b128 v[148:151], v241 offset:0
	ds_read_b128 v[156:159], v241 offset:1024
	ds_read_b128 v[166:169], v241 offset:2048
	ds_read_b128 v[170:173], v241 offset:3072
	ds_read_b128 v[174:177], v241 offset:16384
	ds_read_b128 v[178:181], v241 offset:17408
	ds_read_b128 v[182:185], v241 offset:18432
	ds_read_b128 v[186:189], v241 offset:19456
	s_add_u32 s20, s22, 0xfff00080
	s_addc_u32 s21, s23, -1
	s_cmp_eq_u32 s67, 60
	s_cselect_b32 s25, s13, s21
	s_cselect_b32 s24, s63, s20
	s_cselect_b32 s21, s11, s66
	s_cselect_b32 s20, s64, s65
	s_add_i32 m0, s19, 0xc000
	ds_read_b128 v[190:193], v155
	ds_read_b128 v[194:197], v155 offset:1024
	ds_read_b128 v[198:201], v155 offset:2048
	ds_read_b128 v[202:205], v155 offset:3072
	ds_read_b128 v[206:209], v155 offset:4096
	ds_read_b128 v[210:213], v155 offset:5120
	ds_read_b128 v[214:217], v155 offset:6144
	ds_read_b128 v[218:221], v155 offset:7168
	global_load_lds_dwordx4 v138, s[22:23]
	s_add_i32 m0, s19, 0xe000
	s_nop 0
	global_load_lds_dwordx4 v140, s[22:23]
	s_waitcnt vmcnt(8)
	s_waitcnt lgkmcnt(0)
	s_barrier
	s_waitcnt lgkmcnt(0)
	v_mfma_f32_16x16x32_bf16 v[118:121], v[148:151], v[190:193], v[118:121]
	v_mfma_f32_16x16x32_bf16 v[118:121], v[156:159], v[194:197], v[118:121]
	v_mfma_f32_16x16x32_bf16 v[102:105], v[156:159], v[202:205], v[102:105]
	v_mfma_f32_16x16x32_bf16 v[102:105], v[148:151], v[198:201], v[102:105]
	v_mfma_f32_16x16x32_bf16 v[86:89], v[148:151], v[206:209], v[86:89]
	v_mfma_f32_16x16x32_bf16 v[86:89], v[156:159], v[210:213], v[86:89]
	v_mfma_f32_16x16x32_bf16 v[70:73], v[156:159], v[218:221], v[70:73]
	v_mfma_f32_16x16x32_bf16 v[70:73], v[148:151], v[214:217], v[70:73]
	v_mfma_f32_16x16x32_bf16 v[66:69], v[166:169], v[214:217], v[66:69]
	v_mfma_f32_16x16x32_bf16 v[66:69], v[170:173], v[218:221], v[66:69]
	v_mfma_f32_16x16x32_bf16 v[82:85], v[170:173], v[210:213], v[82:85]
	v_mfma_f32_16x16x32_bf16 v[82:85], v[166:169], v[206:209], v[82:85]
	v_mfma_f32_16x16x32_bf16 v[98:101], v[166:169], v[198:201], v[98:101]
	v_mfma_f32_16x16x32_bf16 v[98:101], v[170:173], v[202:205], v[98:101]
	v_mfma_f32_16x16x32_bf16 v[114:117], v[170:173], v[194:197], v[114:117]
	v_mfma_f32_16x16x32_bf16 v[114:117], v[166:169], v[190:193], v[114:117]
	v_mfma_f32_16x16x32_bf16 v[126:129], v[174:177], v[190:193], v[126:129]
	v_mfma_f32_16x16x32_bf16 v[126:129], v[178:181], v[194:197], v[126:129]
	v_mfma_f32_16x16x32_bf16 v[110:113], v[178:181], v[202:205], v[110:113]
	v_mfma_f32_16x16x32_bf16 v[110:113], v[174:177], v[198:201], v[110:113]
	v_mfma_f32_16x16x32_bf16 v[94:97], v[174:177], v[206:209], v[94:97]
	v_mfma_f32_16x16x32_bf16 v[94:97], v[178:181], v[210:213], v[94:97]
	v_mfma_f32_16x16x32_bf16 v[78:81], v[178:181], v[218:221], v[78:81]
	v_mfma_f32_16x16x32_bf16 v[78:81], v[174:177], v[214:217], v[78:81]
	v_mfma_f32_16x16x32_bf16 v[74:77], v[182:185], v[214:217], v[74:77]
	v_mfma_f32_16x16x32_bf16 v[74:77], v[186:189], v[218:221], v[74:77]
	v_mfma_f32_16x16x32_bf16 v[90:93], v[186:189], v[210:213], v[90:93]
	v_mfma_f32_16x16x32_bf16 v[90:93], v[182:185], v[206:209], v[90:93]
	v_mfma_f32_16x16x32_bf16 v[106:109], v[182:185], v[198:201], v[106:109]
	v_mfma_f32_16x16x32_bf16 v[106:109], v[186:189], v[202:205], v[106:109]
	v_mfma_f32_16x16x32_bf16 v[122:125], v[186:189], v[194:197], v[122:125]
	v_mfma_f32_16x16x32_bf16 v[122:125], v[182:185], v[190:193], v[122:125]
	s_barrier
	s_add_i32 s33, s47, s28
	s_mov_b32 m0, s33
	ds_read_b128 v[190:193], v155 offset:16384
	ds_read_b128 v[194:197], v155 offset:17408
	ds_read_b128 v[198:201], v155 offset:18432
	ds_read_b128 v[202:205], v155 offset:19456
	ds_read_b128 v[206:209], v155 offset:20480
	ds_read_b128 v[210:213], v155 offset:21504
	ds_read_b128 v[214:217], v155 offset:22528
	ds_read_b128 v[218:221], v155 offset:23552
	global_load_lds_dwordx4 v132, s[20:21]
	s_add_i32 m0, s33, 0x2000
	s_add_u32 s68, s20, 0x100000
	s_addc_u32 s69, s21, 0
	s_add_i32 s33, s52, s28
	global_load_lds_dwordx4 v136, s[20:21]
	s_mov_b32 m0, s33
	s_add_u32 s100, s24, 0x80
	s_addc_u32 s101, s25, 0
	global_load_lds_dwordx4 v132, s[68:69]
	s_add_i32 m0, s33, 0x2000
	s_nop 0
	global_load_lds_dwordx4 v136, s[68:69]
	s_mov_b32 m0, s19
	s_nop 0
	global_load_lds_dwordx4 v130, s[24:25]
	s_mov_b32 m0, s35
	s_nop 0
	global_load_lds_dwordx4 v134, s[24:25]
	s_waitcnt vmcnt(8)
	s_waitcnt lgkmcnt(0)
	s_barrier
	s_waitcnt lgkmcnt(0)
	v_mfma_f32_16x16x32_bf16 v[54:57], v[148:151], v[190:193], v[54:57]
	v_mfma_f32_16x16x32_bf16 v[54:57], v[156:159], v[194:197], v[54:57]
	v_mfma_f32_16x16x32_bf16 v[38:41], v[156:159], v[202:205], v[38:41]
	v_mfma_f32_16x16x32_bf16 v[38:41], v[148:151], v[198:201], v[38:41]
	v_mfma_f32_16x16x32_bf16 v[22:25], v[148:151], v[206:209], v[22:25]
	v_mfma_f32_16x16x32_bf16 v[22:25], v[156:159], v[210:213], v[22:25]
	v_mfma_f32_16x16x32_bf16 v[6:9], v[156:159], v[218:221], v[6:9]
	v_mfma_f32_16x16x32_bf16 v[6:9], v[148:151], v[214:217], v[6:9]
	v_mfma_f32_16x16x32_bf16 v[2:5], v[166:169], v[214:217], v[2:5]
	v_mfma_f32_16x16x32_bf16 v[2:5], v[170:173], v[218:221], v[2:5]
	v_mfma_f32_16x16x32_bf16 v[18:21], v[170:173], v[210:213], v[18:21]
	v_mfma_f32_16x16x32_bf16 v[18:21], v[166:169], v[206:209], v[18:21]
	v_mfma_f32_16x16x32_bf16 v[34:37], v[166:169], v[198:201], v[34:37]
	v_mfma_f32_16x16x32_bf16 v[34:37], v[170:173], v[202:205], v[34:37]
	v_mfma_f32_16x16x32_bf16 v[50:53], v[170:173], v[194:197], v[50:53]
	v_mfma_f32_16x16x32_bf16 v[50:53], v[166:169], v[190:193], v[50:53]
	v_mfma_f32_16x16x32_bf16 v[62:65], v[174:177], v[190:193], v[62:65]
	v_mfma_f32_16x16x32_bf16 v[62:65], v[178:181], v[194:197], v[62:65]
	v_mfma_f32_16x16x32_bf16 v[46:49], v[178:181], v[202:205], v[46:49]
	v_mfma_f32_16x16x32_bf16 v[46:49], v[174:177], v[198:201], v[46:49]
	v_mfma_f32_16x16x32_bf16 v[30:33], v[174:177], v[206:209], v[30:33]
	v_mfma_f32_16x16x32_bf16 v[30:33], v[178:181], v[210:213], v[30:33]
	v_mfma_f32_16x16x32_bf16 v[10:13], v[178:181], v[218:221], v[10:13]
	v_mfma_f32_16x16x32_bf16 v[10:13], v[174:177], v[214:217], v[10:13]
	v_mfma_f32_16x16x32_bf16 v[14:17], v[182:185], v[214:217], v[14:17]
	v_mfma_f32_16x16x32_bf16 v[14:17], v[186:189], v[218:221], v[14:17]
	v_mfma_f32_16x16x32_bf16 v[26:29], v[186:189], v[210:213], v[26:29]
	v_mfma_f32_16x16x32_bf16 v[26:29], v[182:185], v[206:209], v[26:29]
	v_mfma_f32_16x16x32_bf16 v[42:45], v[182:185], v[198:201], v[42:45]
	v_mfma_f32_16x16x32_bf16 v[42:45], v[186:189], v[202:205], v[42:45]
	v_mfma_f32_16x16x32_bf16 v[58:61], v[186:189], v[194:197], v[58:61]
	v_mfma_f32_16x16x32_bf16 v[58:61], v[182:185], v[190:193], v[58:61]
	s_barrier
; #define PG8_STAGE(bufoff, gbase, voff) do { _Pragma("unroll") for (int _i = 0; _i < 2; ++_i) \
;         __builtin_amdgcn_global_load_lds((const unsigned*)((const char*)(gbase) + (voff)[_i]), (PG8_LAS unsigned*)(lds + (bufoff) + ldsw + _i * 8192), 16, 0, 0); } while (0)
; #define PG8_LDA(dst, b, h) do { _Pragma("unroll") for (int m = 0; m < 4; ++m) _Pragma("unroll") for (int k = 0; k < 2; ++k) dst[m][k] = *(const PG8_LAS bf16x8*)(lds + PG8_SA(b, h) + aoff + m * 2048 + k * 1024); } while (0)
; #define PG8_LDB(dst, b, h) do { _Pragma("unroll") for (int n = 0; n < 2; ++n) _Pragma("unroll") for (int k = 0; k < 2; ++k) dst[n][k] = *(const PG8_LAS bf16x8*)(lds + PG8_SB(b, h) + boff + n * 2048 + k * 1024); } while (0)
; #define PG8_MMA(ai, bj, At, Bt) do { __builtin_amdgcn_s_setprio(1); _Pragma("unroll") for (int m = 0; m < 4; ++m) _Pragma("unroll") for (int n = 0; n < 2; ++n) _Pragma("unroll") for (int k = 0; k < 2; ++k) \
;         acc[ai][bj][m][n] = __builtin_amdgcn_mfma_f32_16x16x32_bf16(Bt[n][k], At[m][k], acc[ai][bj][m][n], 0, 0, 0); __builtin_amdgcn_s_setprio(0); } while (0)
; #define PG8_WAIT_V(n) asm volatile("s_waitcnt vmcnt(" #n ")" ::: "memory")
; #define PG8_WAIT_L(n) asm volatile("s_waitcnt lgkmcnt(" #n ")" ::: "memory")
; #define PG8_BAR __builtin_amdgcn_s_barrier()
; template <class Epi, class Sched, bool ALIGN_EPI = false, bool SP2 = false>
; __device__ __forceinline__ void gemm_phase(PG8_LAS unsigned char* lds, const Gemm g, const Sched& S, const Epi& E) {
;     ...
;         for (int t = 0; t < nt; t += 2) {
;             const bool last = (t == nt - 2);
;             const char* a1 = cA + (size_t)(t + 1) * kstep;
;             const char* a2 = last ? nA : cA + (size_t)(t + 2) * kstep; const char* b2 = last ? nB : cB + (size_t)(t + 2) * kstep;
;             const char* a3 = a2 + kstep; const char* b3 = b2 + kstep;
;     ...
;             PG8_LDB(B0, 1, 0); PG8_LDB(B1, 1, 1); PG8_SCHED; PG8_LDA(At, 1, 0); PG8_STAGE(PG8_SA(0, 1), a2 + hstep, voffA);
;             PG8_WAIT_V(8); PG8_WAIT_L(0); PG8_BAR; PG8_MMA(0, 0, At, B0); PG8_MMA(0, 1, At, B1); PG8_BAR; PG8_SCHED;
;             PG8_LDA(At, 1, 1); PG8_STAGE(PG8_SB(1, 0), b3, voffB); PG8_STAGE(PG8_SB(1, 1), b3 + hstep, voffB); PG8_STAGE(PG8_SA(1, 0), a3, voffA);
;             PG8_WAIT_V(8); PG8_WAIT_L(0); PG8_BAR; PG8_MMA(1, 0, At, B0); PG8_MMA(1, 1, At, B1); PG8_BAR; PG8_SCHED;
	s_add_i32 s33, 0, 0x18000
	s_add_i32 s42, 0, 0x1c000
	ds_read_b128 v[148:151], v241 offset:32768
	ds_read_b128 v[156:159], v241 offset:33792
	ds_read_b128 v[166:169], v241 offset:34816
	ds_read_b128 v[170:173], v241 offset:35840
	ds_read_b128 v[174:177], v241 offset:49152
	ds_read_b128 v[178:181], v241 offset:50176
	ds_read_b128 v[182:185], v241 offset:51200
	ds_read_b128 v[186:189], v241 offset:52224
	s_add_u32 s24, s24, 0x100000
	s_addc_u32 s25, s25, 0
	s_mov_b32 m0, s36
	ds_read_b128 v[190:193], v155 offset:32768
	ds_read_b128 v[194:197], v155 offset:33792
	ds_read_b128 v[198:201], v155 offset:34816
	ds_read_b128 v[202:205], v155 offset:35840
	ds_read_b128 v[206:209], v155 offset:36864
	ds_read_b128 v[210:213], v155 offset:37888
	ds_read_b128 v[214:217], v155 offset:38912
	ds_read_b128 v[218:221], v155 offset:39936
	global_load_lds_dwordx4 v130, s[24:25]
	s_mov_b32 m0, s37
	s_nop 0
	global_load_lds_dwordx4 v134, s[24:25]
	s_waitcnt vmcnt(8)
	s_waitcnt lgkmcnt(0)
	s_barrier
	s_waitcnt lgkmcnt(0)
	v_mfma_f32_16x16x32_bf16 v[118:121], v[148:151], v[190:193], v[118:121]
	v_mfma_f32_16x16x32_bf16 v[118:121], v[156:159], v[194:197], v[118:121]
	v_mfma_f32_16x16x32_bf16 v[102:105], v[156:159], v[202:205], v[102:105]
	v_mfma_f32_16x16x32_bf16 v[102:105], v[148:151], v[198:201], v[102:105]
	v_mfma_f32_16x16x32_bf16 v[86:89], v[148:151], v[206:209], v[86:89]
	v_mfma_f32_16x16x32_bf16 v[86:89], v[156:159], v[210:213], v[86:89]
	v_mfma_f32_16x16x32_bf16 v[70:73], v[156:159], v[218:221], v[70:73]
	v_mfma_f32_16x16x32_bf16 v[70:73], v[148:151], v[214:217], v[70:73]
	v_mfma_f32_16x16x32_bf16 v[66:69], v[166:169], v[214:217], v[66:69]
	v_mfma_f32_16x16x32_bf16 v[66:69], v[170:173], v[218:221], v[66:69]
	v_mfma_f32_16x16x32_bf16 v[82:85], v[170:173], v[210:213], v[82:85]
	v_mfma_f32_16x16x32_bf16 v[82:85], v[166:169], v[206:209], v[82:85]
	v_mfma_f32_16x16x32_bf16 v[98:101], v[166:169], v[198:201], v[98:101]
	v_mfma_f32_16x16x32_bf16 v[98:101], v[170:173], v[202:205], v[98:101]
	v_mfma_f32_16x16x32_bf16 v[114:117], v[170:173], v[194:197], v[114:117]
	v_mfma_f32_16x16x32_bf16 v[114:117], v[166:169], v[190:193], v[114:117]
	v_mfma_f32_16x16x32_bf16 v[126:129], v[174:177], v[190:193], v[126:129]
	v_mfma_f32_16x16x32_bf16 v[126:129], v[178:181], v[194:197], v[126:129]
	v_mfma_f32_16x16x32_bf16 v[110:113], v[178:181], v[202:205], v[110:113]
	v_mfma_f32_16x16x32_bf16 v[110:113], v[174:177], v[198:201], v[110:113]
	v_mfma_f32_16x16x32_bf16 v[94:97], v[174:177], v[206:209], v[94:97]
	v_mfma_f32_16x16x32_bf16 v[94:97], v[178:181], v[210:213], v[94:97]
	v_mfma_f32_16x16x32_bf16 v[78:81], v[178:181], v[218:221], v[78:81]
	v_mfma_f32_16x16x32_bf16 v[78:81], v[174:177], v[214:217], v[78:81]
	v_mfma_f32_16x16x32_bf16 v[74:77], v[182:185], v[214:217], v[74:77]
	v_mfma_f32_16x16x32_bf16 v[74:77], v[186:189], v[218:221], v[74:77]
	v_mfma_f32_16x16x32_bf16 v[90:93], v[186:189], v[210:213], v[90:93]
	v_mfma_f32_16x16x32_bf16 v[90:93], v[182:185], v[206:209], v[90:93]
	v_mfma_f32_16x16x32_bf16 v[106:109], v[182:185], v[198:201], v[106:109]
	v_mfma_f32_16x16x32_bf16 v[106:109], v[186:189], v[202:205], v[106:109]
	v_mfma_f32_16x16x32_bf16 v[122:125], v[186:189], v[194:197], v[122:125]
	v_mfma_f32_16x16x32_bf16 v[122:125], v[182:185], v[190:193], v[122:125]
	s_barrier
	s_add_i32 s24, s33, s28
	s_add_i32 m0, s24, 0xffffff80
	ds_read_b128 v[190:193], v155 offset:49152
	ds_read_b128 v[194:197], v155 offset:50176
	ds_read_b128 v[198:201], v155 offset:51200
	ds_read_b128 v[202:205], v155 offset:52224
	ds_read_b128 v[206:209], v155 offset:53248
	ds_read_b128 v[210:213], v155 offset:54272
	ds_read_b128 v[214:217], v155 offset:55296
	ds_read_b128 v[218:221], v155 offset:56320
	global_load_lds_dwordx4 v132, s[20:21] offset:128
	s_add_i32 m0, s24, 0x1f80
	s_add_i32 s24, s42, s28
	global_load_lds_dwordx4 v136, s[20:21] offset:128
	s_add_u32 s20, s20, 0x100080
	s_addc_u32 s21, s21, 0
	s_mov_b32 m0, s24
	s_nop 0
	global_load_lds_dwordx4 v132, s[20:21]
	s_add_i32 m0, s24, 0x2000
	s_nop 0
	global_load_lds_dwordx4 v136, s[20:21]
	s_mov_b32 m0, s43
	s_nop 0
	global_load_lds_dwordx4 v130, s[100:101]
	s_mov_b32 m0, s46
	s_nop 0
	global_load_lds_dwordx4 v134, s[100:101]
	s_waitcnt vmcnt(8)
	s_waitcnt lgkmcnt(0)
	s_barrier
	s_waitcnt lgkmcnt(0)
	v_mfma_f32_16x16x32_bf16 v[54:57], v[148:151], v[190:193], v[54:57]
	v_mfma_f32_16x16x32_bf16 v[54:57], v[156:159], v[194:197], v[54:57]
	v_mfma_f32_16x16x32_bf16 v[38:41], v[156:159], v[202:205], v[38:41]
	v_mfma_f32_16x16x32_bf16 v[38:41], v[148:151], v[198:201], v[38:41]
	v_mfma_f32_16x16x32_bf16 v[22:25], v[148:151], v[206:209], v[22:25]
	v_mfma_f32_16x16x32_bf16 v[22:25], v[156:159], v[210:213], v[22:25]
	v_mfma_f32_16x16x32_bf16 v[6:9], v[156:159], v[218:221], v[6:9]
	v_mfma_f32_16x16x32_bf16 v[6:9], v[148:151], v[214:217], v[6:9]
	v_mfma_f32_16x16x32_bf16 v[2:5], v[166:169], v[214:217], v[2:5]
	v_mfma_f32_16x16x32_bf16 v[2:5], v[170:173], v[218:221], v[2:5]
	v_mfma_f32_16x16x32_bf16 v[18:21], v[170:173], v[210:213], v[18:21]
	v_mfma_f32_16x16x32_bf16 v[18:21], v[166:169], v[206:209], v[18:21]
	v_mfma_f32_16x16x32_bf16 v[34:37], v[166:169], v[198:201], v[34:37]
	v_mfma_f32_16x16x32_bf16 v[34:37], v[170:173], v[202:205], v[34:37]
	v_mfma_f32_16x16x32_bf16 v[50:53], v[170:173], v[194:197], v[50:53]
	v_mfma_f32_16x16x32_bf16 v[50:53], v[166:169], v[190:193], v[50:53]
	v_mfma_f32_16x16x32_bf16 v[62:65], v[174:177], v[190:193], v[62:65]
	v_mfma_f32_16x16x32_bf16 v[62:65], v[178:181], v[194:197], v[62:65]
	v_mfma_f32_16x16x32_bf16 v[46:49], v[178:181], v[202:205], v[46:49]
	v_mfma_f32_16x16x32_bf16 v[46:49], v[174:177], v[198:201], v[46:49]
	v_mfma_f32_16x16x32_bf16 v[30:33], v[174:177], v[206:209], v[30:33]
	v_mfma_f32_16x16x32_bf16 v[30:33], v[178:181], v[210:213], v[30:33]
	v_mfma_f32_16x16x32_bf16 v[10:13], v[178:181], v[218:221], v[10:13]
	v_mfma_f32_16x16x32_bf16 v[10:13], v[174:177], v[214:217], v[10:13]
	v_mfma_f32_16x16x32_bf16 v[14:17], v[182:185], v[214:217], v[14:17]
	v_mfma_f32_16x16x32_bf16 v[14:17], v[186:189], v[218:221], v[14:17]
	v_mfma_f32_16x16x32_bf16 v[26:29], v[186:189], v[210:213], v[26:29]
	v_mfma_f32_16x16x32_bf16 v[26:29], v[182:185], v[206:209], v[26:29]
	v_mfma_f32_16x16x32_bf16 v[42:45], v[182:185], v[198:201], v[42:45]
	v_mfma_f32_16x16x32_bf16 v[42:45], v[186:189], v[202:205], v[42:45]
	v_mfma_f32_16x16x32_bf16 v[58:61], v[186:189], v[194:197], v[58:61]
	v_mfma_f32_16x16x32_bf16 v[58:61], v[182:185], v[190:193], v[58:61]
	s_barrier
	s_add_i32 s67, s67, 2
	s_add_u32 s22, s22, 0x100
	s_addc_u32 s23, s23, 0
	s_add_u32 s65, s65, 0x100
	s_addc_u32 s66, s66, 0
	s_cmp_gt_u32 s67, 61
	s_cbranch_scc0 .LBB0_1332
	s_and_b64 vcc, exec, s[8:9]
	s_cbranch_vccz .LBB0_1335
	s_barrier

; #define PG8_STAGE(bufoff, gbase, voff) do { _Pragma("unroll") for (int _i = 0; _i < 2; ++_i) \
;         __builtin_amdgcn_global_load_lds((const unsigned*)((const char*)(gbase) + (voff)[_i]), (PG8_LAS unsigned*)(lds + (bufoff) + ldsw + _i * 8192), 16, 0, 0); } while (0)
; #define PG8_LDA(dst, b, h) do { _Pragma("unroll") for (int m = 0; m < 4; ++m) _Pragma("unroll") for (int k = 0; k < 2; ++k) dst[m][k] = *(const PG8_LAS bf16x8*)(lds + PG8_SA(b, h) + aoff + m * 2048 + k * 1024); } while (0)
; #define PG8_LDB(dst, b, h) do { _Pragma("unroll") for (int n = 0; n < 2; ++n) _Pragma("unroll") for (int k = 0; k < 2; ++k) dst[n][k] = *(const PG8_LAS bf16x8*)(lds + PG8_SB(b, h) + boff + n * 2048 + k * 1024); } while (0)
; #define PG8_MMA(ai, bj, At, Bt) do { __builtin_amdgcn_s_setprio(1); _Pragma("unroll") for (int m = 0; m < 4; ++m) _Pragma("unroll") for (int n = 0; n < 2; ++n) _Pragma("unroll") for (int k = 0; k < 2; ++k) \
;         acc[ai][bj][m][n] = __builtin_amdgcn_mfma_f32_16x16x32_bf16(Bt[n][k], At[m][k], acc[ai][bj][m][n], 0, 0, 0); __builtin_amdgcn_s_setprio(0); } while (0)
; #define PG8_WAIT_V(n) asm volatile("s_waitcnt vmcnt(" #n ")" ::: "memory")
; #define PG8_WAIT_L(n) asm volatile("s_waitcnt lgkmcnt(" #n ")" ::: "memory")
; #define PG8_BAR __builtin_amdgcn_s_barrier()
; #define PG8_SCHED __builtin_amdgcn_sched_barrier(0)
; template <class Epi, class Sched, bool ALIGN_EPI = false, bool SP2 = false>
; __device__ __forceinline__ void gemm_phase(PG8_LAS unsigned char* lds, const Gemm g, const Sched& S, const Epi& E) {
;     ...
;             PG8_LDB(B0, 0, 0); PG8_LDB(B1, 0, 1); PG8_SCHED; PG8_LDA(At, 0, 0); PG8_STAGE(PG8_SA(1, 1), a1 + hstep, voffA);
;             PG8_WAIT_V(8); PG8_WAIT_L(0); PG8_BAR; PG8_MMA(0, 0, At, B0); PG8_MMA(0, 1, At, B1); PG8_BAR; PG8_SCHED;
;             PG8_LDA(At, 0, 1); PG8_STAGE(PG8_SB(0, 0), b2, voffB); PG8_STAGE(PG8_SB(0, 1), b2 + hstep, voffB); PG8_STAGE(PG8_SA(0, 0), a2, voffA);
;             PG8_WAIT_V(8); PG8_WAIT_L(0); PG8_BAR; PG8_MMA(1, 0, At, B0); PG8_MMA(1, 1, At, B1); PG8_BAR; PG8_SCHED;
.LBB0_1595:
	ds_read_b128 v[130:133], v241 offset:0
	ds_read_b128 v[134:137], v241 offset:1024
	ds_read_b128 v[138:141], v241 offset:2048
	ds_read_b128 v[142:145], v241 offset:3072
	ds_read_b128 v[146:149], v241 offset:16384
	ds_read_b128 v[150:153], v241 offset:17408
	ds_read_b128 v[172:175], v241 offset:18432
	ds_read_b128 v[176:179], v241 offset:19456
	s_add_u32 s24, s26, 0xfff00080
	s_addc_u32 s25, s27, -1
	s_cmp_eq_u32 s62, 60
	s_cselect_b32 s29, s15, s25
	s_cselect_b32 s28, s21, s24
	s_cselect_b32 s25, s13, s53
	s_cselect_b32 s24, s51, s52
	s_add_i32 m0, s23, 0xc000
	ds_read_b128 v[180:183], v185
	ds_read_b128 v[188:191], v185 offset:1024
	ds_read_b128 v[192:195], v185 offset:2048
	ds_read_b128 v[196:199], v185 offset:3072
	ds_read_b128 v[200:203], v185 offset:4096
	ds_read_b128 v[204:207], v185 offset:5120
	ds_read_b128 v[208:211], v185 offset:6144
	ds_read_b128 v[212:215], v185 offset:7168
	global_load_lds_dwordx4 v162, s[26:27]
	s_add_i32 m0, s23, 0xe000
	s_nop 0
	global_load_lds_dwordx4 v166, s[26:27]
	s_waitcnt vmcnt(8)
	s_waitcnt lgkmcnt(0)
	s_barrier
	s_waitcnt lgkmcnt(0)
	v_mfma_f32_16x16x32_bf16 v[114:117], v[130:133], v[180:183], v[114:117]
	v_mfma_f32_16x16x32_bf16 v[114:117], v[134:137], v[188:191], v[114:117]
	v_mfma_f32_16x16x32_bf16 v[106:109], v[134:137], v[196:199], v[106:109]
	v_mfma_f32_16x16x32_bf16 v[106:109], v[130:133], v[192:195], v[106:109]
	v_mfma_f32_16x16x32_bf16 v[90:93], v[130:133], v[200:203], v[90:93]
	v_mfma_f32_16x16x32_bf16 v[90:93], v[134:137], v[204:207], v[90:93]
	v_mfma_f32_16x16x32_bf16 v[74:77], v[134:137], v[212:215], v[74:77]
	v_mfma_f32_16x16x32_bf16 v[74:77], v[130:133], v[208:211], v[74:77]
	v_mfma_f32_16x16x32_bf16 v[66:69], v[138:141], v[208:211], v[66:69]
	v_mfma_f32_16x16x32_bf16 v[66:69], v[142:145], v[212:215], v[66:69]
	v_mfma_f32_16x16x32_bf16 v[82:85], v[142:145], v[204:207], v[82:85]
	v_mfma_f32_16x16x32_bf16 v[82:85], v[138:141], v[200:203], v[82:85]
	v_mfma_f32_16x16x32_bf16 v[98:101], v[138:141], v[192:195], v[98:101]
	v_mfma_f32_16x16x32_bf16 v[98:101], v[142:145], v[196:199], v[98:101]
	v_mfma_f32_16x16x32_bf16 v[118:121], v[142:145], v[188:191], v[118:121]
	v_mfma_f32_16x16x32_bf16 v[118:121], v[138:141], v[180:183], v[118:121]
	v_mfma_f32_16x16x32_bf16 v[122:125], v[146:149], v[180:183], v[122:125]
	v_mfma_f32_16x16x32_bf16 v[122:125], v[150:153], v[188:191], v[122:125]
	v_mfma_f32_16x16x32_bf16 v[110:113], v[150:153], v[196:199], v[110:113]
	v_mfma_f32_16x16x32_bf16 v[110:113], v[146:149], v[192:195], v[110:113]
	v_mfma_f32_16x16x32_bf16 v[94:97], v[146:149], v[200:203], v[94:97]
	v_mfma_f32_16x16x32_bf16 v[94:97], v[150:153], v[204:207], v[94:97]
	v_mfma_f32_16x16x32_bf16 v[78:81], v[150:153], v[212:215], v[78:81]
	v_mfma_f32_16x16x32_bf16 v[78:81], v[146:149], v[208:211], v[78:81]
	v_mfma_f32_16x16x32_bf16 v[70:73], v[172:175], v[208:211], v[70:73]
	v_mfma_f32_16x16x32_bf16 v[70:73], v[176:179], v[212:215], v[70:73]
	v_mfma_f32_16x16x32_bf16 v[86:89], v[176:179], v[204:207], v[86:89]
	v_mfma_f32_16x16x32_bf16 v[86:89], v[172:175], v[200:203], v[86:89]
	v_mfma_f32_16x16x32_bf16 v[102:105], v[172:175], v[192:195], v[102:105]
	v_mfma_f32_16x16x32_bf16 v[102:105], v[176:179], v[196:199], v[102:105]
	v_mfma_f32_16x16x32_bf16 v[126:129], v[176:179], v[188:191], v[126:129]
	v_mfma_f32_16x16x32_bf16 v[126:129], v[172:175], v[180:183], v[126:129]
	s_barrier
	s_add_i32 s33, s48, s36
	s_mov_b32 m0, s33
	ds_read_b128 v[180:183], v185 offset:16384
	ds_read_b128 v[188:191], v185 offset:17408
	ds_read_b128 v[192:195], v185 offset:18432
	ds_read_b128 v[196:199], v185 offset:19456
	ds_read_b128 v[200:203], v185 offset:20480
	ds_read_b128 v[204:207], v185 offset:21504
	ds_read_b128 v[208:211], v185 offset:22528
	ds_read_b128 v[212:215], v185 offset:23552
	global_load_lds_dwordx4 v156, s[24:25]
	s_add_i32 m0, s33, 0x2000
	s_add_u32 s64, s24, 0x100000
	s_addc_u32 s65, s25, 0
	s_add_i32 s33, s49, s36
	global_load_lds_dwordx4 v160, s[24:25]
	s_mov_b32 m0, s33
	s_add_u32 s100, s28, 0x80
	s_addc_u32 s101, s29, 0
	global_load_lds_dwordx4 v156, s[64:65]
	s_add_i32 m0, s33, 0x2000
	s_nop 0
	global_load_lds_dwordx4 v160, s[64:65]
	s_mov_b32 m0, s23
	s_nop 0
	global_load_lds_dwordx4 v154, s[28:29]
	s_mov_b32 m0, s37
	s_nop 0
	global_load_lds_dwordx4 v158, s[28:29]
	s_waitcnt vmcnt(8)
	s_waitcnt lgkmcnt(0)
	s_barrier
	s_waitcnt lgkmcnt(0)
	v_mfma_f32_16x16x32_bf16 v[58:61], v[130:133], v[180:183], v[58:61]
	v_mfma_f32_16x16x32_bf16 v[58:61], v[134:137], v[188:191], v[58:61]
	v_mfma_f32_16x16x32_bf16 v[42:45], v[134:137], v[196:199], v[42:45]
	v_mfma_f32_16x16x32_bf16 v[42:45], v[130:133], v[192:195], v[42:45]
	v_mfma_f32_16x16x32_bf16 v[26:29], v[130:133], v[200:203], v[26:29]
	v_mfma_f32_16x16x32_bf16 v[26:29], v[134:137], v[204:207], v[26:29]
	v_mfma_f32_16x16x32_bf16 v[6:9], v[134:137], v[212:215], v[6:9]
	v_mfma_f32_16x16x32_bf16 v[6:9], v[130:133], v[208:211], v[6:9]
	v_mfma_f32_16x16x32_bf16 v[2:5], v[138:141], v[208:211], v[2:5]
	v_mfma_f32_16x16x32_bf16 v[2:5], v[142:145], v[212:215], v[2:5]
	v_mfma_f32_16x16x32_bf16 v[18:21], v[142:145], v[204:207], v[18:21]
	v_mfma_f32_16x16x32_bf16 v[18:21], v[138:141], v[200:203], v[18:21]
	v_mfma_f32_16x16x32_bf16 v[34:37], v[138:141], v[192:195], v[34:37]
	v_mfma_f32_16x16x32_bf16 v[34:37], v[142:145], v[196:199], v[34:37]
	v_mfma_f32_16x16x32_bf16 v[54:57], v[142:145], v[188:191], v[54:57]
	v_mfma_f32_16x16x32_bf16 v[54:57], v[138:141], v[180:183], v[54:57]
	v_mfma_f32_16x16x32_bf16 v[62:65], v[146:149], v[180:183], v[62:65]
	v_mfma_f32_16x16x32_bf16 v[62:65], v[150:153], v[188:191], v[62:65]
	v_mfma_f32_16x16x32_bf16 v[46:49], v[150:153], v[196:199], v[46:49]
	v_mfma_f32_16x16x32_bf16 v[46:49], v[146:149], v[192:195], v[46:49]
	v_mfma_f32_16x16x32_bf16 v[30:33], v[146:149], v[200:203], v[30:33]
	v_mfma_f32_16x16x32_bf16 v[30:33], v[150:153], v[204:207], v[30:33]
	v_mfma_f32_16x16x32_bf16 v[10:13], v[150:153], v[212:215], v[10:13]
	v_mfma_f32_16x16x32_bf16 v[10:13], v[146:149], v[208:211], v[10:13]
	v_mfma_f32_16x16x32_bf16 v[14:17], v[172:175], v[208:211], v[14:17]
	v_mfma_f32_16x16x32_bf16 v[14:17], v[176:179], v[212:215], v[14:17]
	v_mfma_f32_16x16x32_bf16 v[22:25], v[176:179], v[204:207], v[22:25]
	v_mfma_f32_16x16x32_bf16 v[22:25], v[172:175], v[200:203], v[22:25]
	v_mfma_f32_16x16x32_bf16 v[38:41], v[172:175], v[192:195], v[38:41]
	v_mfma_f32_16x16x32_bf16 v[38:41], v[176:179], v[196:199], v[38:41]
	v_mfma_f32_16x16x32_bf16 v[50:53], v[176:179], v[188:191], v[50:53]
	v_mfma_f32_16x16x32_bf16 v[50:53], v[172:175], v[180:183], v[50:53]
	s_barrier
; #define PG8_STAGE(bufoff, gbase, voff) do { _Pragma("unroll") for (int _i = 0; _i < 2; ++_i) \
;         __builtin_amdgcn_global_load_lds((const unsigned*)((const char*)(gbase) + (voff)[_i]), (PG8_LAS unsigned*)(lds + (bufoff) + ldsw + _i * 8192), 16, 0, 0); } while (0)
; #define PG8_LDA(dst, b, h) do { _Pragma("unroll") for (int m = 0; m < 4; ++m) _Pragma("unroll") for (int k = 0; k < 2; ++k) dst[m][k] = *(const PG8_LAS bf16x8*)(lds + PG8_SA(b, h) + aoff + m * 2048 + k * 1024); } while (0)
; #define PG8_LDB(dst, b, h) do { _Pragma("unroll") for (int n = 0; n < 2; ++n) _Pragma("unroll") for (int k = 0; k < 2; ++k) dst[n][k] = *(const PG8_LAS bf16x8*)(lds + PG8_SB(b, h) + boff + n * 2048 + k * 1024); } while (0)
; #define PG8_MMA(ai, bj, At, Bt) do { __builtin_amdgcn_s_setprio(1); _Pragma("unroll") for (int m = 0; m < 4; ++m) _Pragma("unroll") for (int n = 0; n < 2; ++n) _Pragma("unroll") for (int k = 0; k < 2; ++k) \
;         acc[ai][bj][m][n] = __builtin_amdgcn_mfma_f32_16x16x32_bf16(Bt[n][k], At[m][k], acc[ai][bj][m][n], 0, 0, 0); __builtin_amdgcn_s_setprio(0); } while (0)
; #define PG8_WAIT_V(n) asm volatile("s_waitcnt vmcnt(" #n ")" ::: "memory")
; #define PG8_WAIT_L(n) asm volatile("s_waitcnt lgkmcnt(" #n ")" ::: "memory")
; #define PG8_BAR __builtin_amdgcn_s_barrier()
; template <class Epi, class Sched, bool ALIGN_EPI = false, bool SP2 = false>
; __device__ __forceinline__ void gemm_phase(PG8_LAS unsigned char* lds, const Gemm g, const Sched& S, const Epi& E) {
;     ...
;         for (int t = 0; t < nt; t += 2) {
;             const bool last = (t == nt - 2);
;             const char* a1 = cA + (size_t)(t + 1) * kstep;
;             const char* a2 = last ? nA : cA + (size_t)(t + 2) * kstep; const char* b2 = last ? nB : cB + (size_t)(t + 2) * kstep;
;             const char* a3 = a2 + kstep; const char* b3 = b2 + kstep;
;     ...
;             PG8_LDB(B0, 1, 0); PG8_LDB(B1, 1, 1); PG8_SCHED; PG8_LDA(At, 1, 0); PG8_STAGE(PG8_SA(0, 1), a2 + hstep, voffA);
;             PG8_WAIT_V(8); PG8_WAIT_L(0); PG8_BAR; PG8_MMA(0, 0, At, B0); PG8_MMA(0, 1, At, B1); PG8_BAR; PG8_SCHED;
;             PG8_LDA(At, 1, 1); PG8_STAGE(PG8_SB(1, 0), b3, voffB); PG8_STAGE(PG8_SB(1, 1), b3 + hstep, voffB); PG8_STAGE(PG8_SA(1, 0), a3, voffA);
;             PG8_WAIT_V(8); PG8_WAIT_L(0); PG8_BAR; PG8_MMA(1, 0, At, B0); PG8_MMA(1, 1, At, B1); PG8_BAR; PG8_SCHED;
	s_add_i32 s33, 0, 0x18000
	s_add_i32 s42, 0, 0x1c000
	ds_read_b128 v[130:133], v241 offset:32768
	ds_read_b128 v[134:137], v241 offset:33792
	ds_read_b128 v[138:141], v241 offset:34816
	ds_read_b128 v[142:145], v241 offset:35840
	ds_read_b128 v[146:149], v241 offset:49152
	ds_read_b128 v[150:153], v241 offset:50176
	ds_read_b128 v[172:175], v241 offset:51200
	ds_read_b128 v[176:179], v241 offset:52224
	s_add_u32 s28, s28, 0x100000
	s_addc_u32 s29, s29, 0
	s_mov_b32 m0, s40
	ds_read_b128 v[180:183], v185 offset:32768
	ds_read_b128 v[188:191], v185 offset:33792
	ds_read_b128 v[192:195], v185 offset:34816
	ds_read_b128 v[196:199], v185 offset:35840
	ds_read_b128 v[200:203], v185 offset:36864
	ds_read_b128 v[204:207], v185 offset:37888
	ds_read_b128 v[208:211], v185 offset:38912
	ds_read_b128 v[212:215], v185 offset:39936
	global_load_lds_dwordx4 v154, s[28:29]
	s_mov_b32 m0, s41
	s_nop 0
	global_load_lds_dwordx4 v158, s[28:29]
	s_waitcnt vmcnt(8)
	s_waitcnt lgkmcnt(0)
	s_barrier
	s_waitcnt lgkmcnt(0)
	v_mfma_f32_16x16x32_bf16 v[114:117], v[130:133], v[180:183], v[114:117]
	v_mfma_f32_16x16x32_bf16 v[114:117], v[134:137], v[188:191], v[114:117]
	v_mfma_f32_16x16x32_bf16 v[106:109], v[134:137], v[196:199], v[106:109]
	v_mfma_f32_16x16x32_bf16 v[106:109], v[130:133], v[192:195], v[106:109]
	v_mfma_f32_16x16x32_bf16 v[90:93], v[130:133], v[200:203], v[90:93]
	v_mfma_f32_16x16x32_bf16 v[90:93], v[134:137], v[204:207], v[90:93]
	v_mfma_f32_16x16x32_bf16 v[74:77], v[134:137], v[212:215], v[74:77]
	v_mfma_f32_16x16x32_bf16 v[74:77], v[130:133], v[208:211], v[74:77]
	v_mfma_f32_16x16x32_bf16 v[66:69], v[138:141], v[208:211], v[66:69]
	v_mfma_f32_16x16x32_bf16 v[66:69], v[142:145], v[212:215], v[66:69]
	v_mfma_f32_16x16x32_bf16 v[82:85], v[142:145], v[204:207], v[82:85]
	v_mfma_f32_16x16x32_bf16 v[82:85], v[138:141], v[200:203], v[82:85]
	v_mfma_f32_16x16x32_bf16 v[98:101], v[138:141], v[192:195], v[98:101]
	v_mfma_f32_16x16x32_bf16 v[98:101], v[142:145], v[196:199], v[98:101]
	v_mfma_f32_16x16x32_bf16 v[118:121], v[142:145], v[188:191], v[118:121]
	v_mfma_f32_16x16x32_bf16 v[118:121], v[138:141], v[180:183], v[118:121]
	v_mfma_f32_16x16x32_bf16 v[122:125], v[146:149], v[180:183], v[122:125]
	v_mfma_f32_16x16x32_bf16 v[122:125], v[150:153], v[188:191], v[122:125]
	v_mfma_f32_16x16x32_bf16 v[110:113], v[150:153], v[196:199], v[110:113]
	v_mfma_f32_16x16x32_bf16 v[110:113], v[146:149], v[192:195], v[110:113]
	v_mfma_f32_16x16x32_bf16 v[94:97], v[146:149], v[200:203], v[94:97]
	v_mfma_f32_16x16x32_bf16 v[94:97], v[150:153], v[204:207], v[94:97]
	v_mfma_f32_16x16x32_bf16 v[78:81], v[150:153], v[212:215], v[78:81]
	v_mfma_f32_16x16x32_bf16 v[78:81], v[146:149], v[208:211], v[78:81]
	v_mfma_f32_16x16x32_bf16 v[70:73], v[172:175], v[208:211], v[70:73]
	v_mfma_f32_16x16x32_bf16 v[70:73], v[176:179], v[212:215], v[70:73]
	v_mfma_f32_16x16x32_bf16 v[86:89], v[176:179], v[204:207], v[86:89]
	v_mfma_f32_16x16x32_bf16 v[86:89], v[172:175], v[200:203], v[86:89]
	v_mfma_f32_16x16x32_bf16 v[102:105], v[172:175], v[192:195], v[102:105]
	v_mfma_f32_16x16x32_bf16 v[102:105], v[176:179], v[196:199], v[102:105]
	v_mfma_f32_16x16x32_bf16 v[126:129], v[176:179], v[188:191], v[126:129]
	v_mfma_f32_16x16x32_bf16 v[126:129], v[172:175], v[180:183], v[126:129]
	s_barrier
	s_add_i32 s28, s33, s36
	s_add_i32 m0, s28, 0xffffff80
	ds_read_b128 v[180:183], v185 offset:49152
	ds_read_b128 v[188:191], v185 offset:50176
	ds_read_b128 v[192:195], v185 offset:51200
	ds_read_b128 v[196:199], v185 offset:52224
	ds_read_b128 v[200:203], v185 offset:53248
	ds_read_b128 v[204:207], v185 offset:54272
	ds_read_b128 v[208:211], v185 offset:55296
	ds_read_b128 v[212:215], v185 offset:56320
	global_load_lds_dwordx4 v156, s[24:25] offset:128
	s_add_i32 m0, s28, 0x1f80
	s_add_i32 s28, s42, s36
	global_load_lds_dwordx4 v160, s[24:25] offset:128
	s_add_u32 s24, s24, 0x100080
	s_addc_u32 s25, s25, 0
	s_mov_b32 m0, s28
	s_nop 0
	global_load_lds_dwordx4 v156, s[24:25]
	s_add_i32 m0, s28, 0x2000
	s_nop 0
	global_load_lds_dwordx4 v160, s[24:25]
	s_mov_b32 m0, s44
	s_nop 0
	global_load_lds_dwordx4 v154, s[100:101]
	s_mov_b32 m0, s45
	s_nop 0
	global_load_lds_dwordx4 v158, s[100:101]
	s_waitcnt vmcnt(8)
	s_waitcnt lgkmcnt(0)
	s_barrier
	s_waitcnt lgkmcnt(0)
	v_mfma_f32_16x16x32_bf16 v[58:61], v[130:133], v[180:183], v[58:61]
	v_mfma_f32_16x16x32_bf16 v[58:61], v[134:137], v[188:191], v[58:61]
	v_mfma_f32_16x16x32_bf16 v[42:45], v[134:137], v[196:199], v[42:45]
	v_mfma_f32_16x16x32_bf16 v[42:45], v[130:133], v[192:195], v[42:45]
	v_mfma_f32_16x16x32_bf16 v[26:29], v[130:133], v[200:203], v[26:29]
	v_mfma_f32_16x16x32_bf16 v[26:29], v[134:137], v[204:207], v[26:29]
	v_mfma_f32_16x16x32_bf16 v[6:9], v[134:137], v[212:215], v[6:9]
	v_mfma_f32_16x16x32_bf16 v[6:9], v[130:133], v[208:211], v[6:9]
	v_mfma_f32_16x16x32_bf16 v[2:5], v[138:141], v[208:211], v[2:5]
	v_mfma_f32_16x16x32_bf16 v[2:5], v[142:145], v[212:215], v[2:5]
	v_mfma_f32_16x16x32_bf16 v[18:21], v[142:145], v[204:207], v[18:21]
	v_mfma_f32_16x16x32_bf16 v[18:21], v[138:141], v[200:203], v[18:21]
	v_mfma_f32_16x16x32_bf16 v[34:37], v[138:141], v[192:195], v[34:37]
	v_mfma_f32_16x16x32_bf16 v[34:37], v[142:145], v[196:199], v[34:37]
	v_mfma_f32_16x16x32_bf16 v[54:57], v[142:145], v[188:191], v[54:57]
	v_mfma_f32_16x16x32_bf16 v[54:57], v[138:141], v[180:183], v[54:57]
	v_mfma_f32_16x16x32_bf16 v[62:65], v[146:149], v[180:183], v[62:65]
	v_mfma_f32_16x16x32_bf16 v[62:65], v[150:153], v[188:191], v[62:65]
	v_mfma_f32_16x16x32_bf16 v[46:49], v[150:153], v[196:199], v[46:49]
	v_mfma_f32_16x16x32_bf16 v[46:49], v[146:149], v[192:195], v[46:49]
	v_mfma_f32_16x16x32_bf16 v[30:33], v[146:149], v[200:203], v[30:33]
	v_mfma_f32_16x16x32_bf16 v[30:33], v[150:153], v[204:207], v[30:33]
	v_mfma_f32_16x16x32_bf16 v[10:13], v[150:153], v[212:215], v[10:13]
	v_mfma_f32_16x16x32_bf16 v[10:13], v[146:149], v[208:211], v[10:13]
	v_mfma_f32_16x16x32_bf16 v[14:17], v[172:175], v[208:211], v[14:17]
	v_mfma_f32_16x16x32_bf16 v[14:17], v[176:179], v[212:215], v[14:17]
	v_mfma_f32_16x16x32_bf16 v[22:25], v[176:179], v[204:207], v[22:25]
	v_mfma_f32_16x16x32_bf16 v[22:25], v[172:175], v[200:203], v[22:25]
	v_mfma_f32_16x16x32_bf16 v[38:41], v[172:175], v[192:195], v[38:41]
	v_mfma_f32_16x16x32_bf16 v[38:41], v[176:179], v[196:199], v[38:41]
	v_mfma_f32_16x16x32_bf16 v[50:53], v[176:179], v[188:191], v[50:53]
	v_mfma_f32_16x16x32_bf16 v[50:53], v[172:175], v[180:183], v[50:53]
	s_barrier
	s_add_i32 s62, s62, 2
	s_add_u32 s26, s26, 0x100
	s_addc_u32 s27, s27, 0
	s_add_u32 s52, s52, 0x100
	s_addc_u32 s53, s53, 0
	s_cmp_gt_u32 s62, 61
	s_cbranch_scc0 .LBB0_1595
	s_and_b64 vcc, exec, s[10:11]
	s_cbranch_vccz .LBB0_1598
	s_barrier

; #define PG8_STAGE(bufoff, gbase, voff) do { _Pragma("unroll") for (int _i = 0; _i < 2; ++_i) \
;         __builtin_amdgcn_global_load_lds((const unsigned*)((const char*)(gbase) + (voff)[_i]), (PG8_LAS unsigned*)(lds + (bufoff) + ldsw + _i * 8192), 16, 0, 0); } while (0)
; #define PG8_LDA(dst, b, h) do { _Pragma("unroll") for (int m = 0; m < 4; ++m) _Pragma("unroll") for (int k = 0; k < 2; ++k) dst[m][k] = *(const PG8_LAS bf16x8*)(lds + PG8_SA(b, h) + aoff + m * 2048 + k * 1024); } while (0)
; #define PG8_LDB(dst, b, h) do { _Pragma("unroll") for (int n = 0; n < 2; ++n) _Pragma("unroll") for (int k = 0; k < 2; ++k) dst[n][k] = *(const PG8_LAS bf16x8*)(lds + PG8_SB(b, h) + boff + n * 2048 + k * 1024); } while (0)
; #define PG8_MMA(ai, bj, At, Bt) do { __builtin_amdgcn_s_setprio(1); _Pragma("unroll") for (int m = 0; m < 4; ++m) _Pragma("unroll") for (int n = 0; n < 2; ++n) _Pragma("unroll") for (int k = 0; k < 2; ++k) \
;         acc[ai][bj][m][n] = __builtin_amdgcn_mfma_f32_16x16x32_bf16(Bt[n][k], At[m][k], acc[ai][bj][m][n], 0, 0, 0); __builtin_amdgcn_s_setprio(0); } while (0)
; #define PG8_WAIT_V(n) asm volatile("s_waitcnt vmcnt(" #n ")" ::: "memory")
; #define PG8_WAIT_L(n) asm volatile("s_waitcnt lgkmcnt(" #n ")" ::: "memory")
; #define PG8_BAR __builtin_amdgcn_s_barrier()
; #define PG8_SCHED __builtin_amdgcn_sched_barrier(0)
; template <class Epi, class Sched, bool ALIGN_EPI = false, bool SP2 = false>
; __device__ __forceinline__ void gemm_phase(PG8_LAS unsigned char* lds, const Gemm g, const Sched& S, const Epi& E) {
;     ...
;             PG8_LDB(B0, 0, 0); PG8_LDB(B1, 0, 1); PG8_SCHED; PG8_LDA(At, 0, 0); PG8_STAGE(PG8_SA(1, 1), a1 + hstep, voffA);
;             PG8_WAIT_V(8); PG8_WAIT_L(0); PG8_BAR; PG8_MMA(0, 0, At, B0); PG8_MMA(0, 1, At, B1); PG8_BAR; PG8_SCHED;
;             PG8_LDA(At, 0, 1); PG8_STAGE(PG8_SB(0, 0), b2, voffB); PG8_STAGE(PG8_SB(0, 1), b2 + hstep, voffB); PG8_STAGE(PG8_SA(0, 0), a2, voffA);
;             PG8_WAIT_V(8); PG8_WAIT_L(0); PG8_BAR; PG8_MMA(1, 0, At, B0); PG8_MMA(1, 1, At, B1); PG8_BAR; PG8_SCHED;
.LBB0_1681:
	ds_read_b128 v[160:163], v241 offset:0
	ds_read_b128 v[166:169], v241 offset:1024
	ds_read_b128 v[170:173], v241 offset:2048
	ds_read_b128 v[174:177], v241 offset:3072
	ds_read_b128 v[178:181], v241 offset:16384
	ds_read_b128 v[182:185], v241 offset:17408
	ds_read_b128 v[186:189], v241 offset:18432
	ds_read_b128 v[190:193], v241 offset:19456
	s_add_u32 s22, s24, 0xfff00080
	s_addc_u32 s23, s25, -1
	s_cmp_eq_u32 s52, 60
	s_cselect_b32 s27, s15, s23
	s_cselect_b32 s26, s48, s22
	s_cselect_b32 s23, s13, s51
	s_cselect_b32 s22, s49, s50
	s_add_i32 m0, s21, 0xc000
	ds_read_b128 v[194:197], v155
	ds_read_b128 v[198:201], v155 offset:1024
	ds_read_b128 v[202:205], v155 offset:2048
	ds_read_b128 v[206:209], v155 offset:3072
	ds_read_b128 v[210:213], v155 offset:4096
	ds_read_b128 v[214:217], v155 offset:5120
	ds_read_b128 v[218:221], v155 offset:6144
	ds_read_b128 v[222:225], v155 offset:7168
	global_load_lds_dwordx4 v138, s[24:25]
	s_add_i32 m0, s21, 0xe000
	s_nop 0
	global_load_lds_dwordx4 v140, s[24:25]
	s_waitcnt vmcnt(8)
	s_waitcnt lgkmcnt(0)
	s_barrier
	s_waitcnt lgkmcnt(0)
	v_mfma_f32_16x16x32_bf16 v[122:125], v[160:163], v[194:197], v[122:125]
	v_mfma_f32_16x16x32_bf16 v[122:125], v[166:169], v[198:201], v[122:125]
	v_mfma_f32_16x16x32_bf16 v[106:109], v[166:169], v[206:209], v[106:109]
	v_mfma_f32_16x16x32_bf16 v[106:109], v[160:163], v[202:205], v[106:109]
	v_mfma_f32_16x16x32_bf16 v[90:93], v[160:163], v[210:213], v[90:93]
	v_mfma_f32_16x16x32_bf16 v[90:93], v[166:169], v[214:217], v[90:93]
	v_mfma_f32_16x16x32_bf16 v[74:77], v[166:169], v[222:225], v[74:77]
	v_mfma_f32_16x16x32_bf16 v[74:77], v[160:163], v[218:221], v[74:77]
	v_mfma_f32_16x16x32_bf16 v[62:65], v[170:173], v[218:221], v[62:65]
	v_mfma_f32_16x16x32_bf16 v[62:65], v[174:177], v[222:225], v[62:65]
	v_mfma_f32_16x16x32_bf16 v[82:85], v[174:177], v[214:217], v[82:85]
	v_mfma_f32_16x16x32_bf16 v[82:85], v[170:173], v[210:213], v[82:85]
	v_mfma_f32_16x16x32_bf16 v[98:101], v[170:173], v[202:205], v[98:101]
	v_mfma_f32_16x16x32_bf16 v[98:101], v[174:177], v[206:209], v[98:101]
	v_mfma_f32_16x16x32_bf16 v[114:117], v[174:177], v[198:201], v[114:117]
	v_mfma_f32_16x16x32_bf16 v[114:117], v[170:173], v[194:197], v[114:117]
	v_mfma_f32_16x16x32_bf16 v[126:129], v[178:181], v[194:197], v[126:129]
	v_mfma_f32_16x16x32_bf16 v[126:129], v[182:185], v[198:201], v[126:129]
	v_mfma_f32_16x16x32_bf16 v[110:113], v[182:185], v[206:209], v[110:113]
	v_mfma_f32_16x16x32_bf16 v[110:113], v[178:181], v[202:205], v[110:113]
	v_mfma_f32_16x16x32_bf16 v[94:97], v[178:181], v[210:213], v[94:97]
	v_mfma_f32_16x16x32_bf16 v[94:97], v[182:185], v[214:217], v[94:97]
	v_mfma_f32_16x16x32_bf16 v[78:81], v[182:185], v[222:225], v[78:81]
	v_mfma_f32_16x16x32_bf16 v[78:81], v[178:181], v[218:221], v[78:81]
	v_mfma_f32_16x16x32_bf16 v[70:73], v[186:189], v[218:221], v[70:73]
	v_mfma_f32_16x16x32_bf16 v[70:73], v[190:193], v[222:225], v[70:73]
	v_mfma_f32_16x16x32_bf16 v[86:89], v[190:193], v[214:217], v[86:89]
	v_mfma_f32_16x16x32_bf16 v[86:89], v[186:189], v[210:213], v[86:89]
	v_mfma_f32_16x16x32_bf16 v[102:105], v[186:189], v[202:205], v[102:105]
	v_mfma_f32_16x16x32_bf16 v[102:105], v[190:193], v[206:209], v[102:105]
	v_mfma_f32_16x16x32_bf16 v[118:121], v[190:193], v[198:201], v[118:121]
	v_mfma_f32_16x16x32_bf16 v[118:121], v[186:189], v[194:197], v[118:121]
	s_barrier
	s_add_i32 s33, s44, s29
	s_mov_b32 m0, s33
	ds_read_b128 v[194:197], v155 offset:16384
	ds_read_b128 v[198:201], v155 offset:17408
	ds_read_b128 v[202:205], v155 offset:18432
	ds_read_b128 v[206:209], v155 offset:19456
	ds_read_b128 v[210:213], v155 offset:20480
	ds_read_b128 v[214:217], v155 offset:21504
	ds_read_b128 v[218:221], v155 offset:22528
	ds_read_b128 v[222:225], v155 offset:23552
	global_load_lds_dwordx4 v132, s[22:23]
	s_add_i32 m0, s33, 0x2000
	s_add_u32 s62, s22, 0x100000
	s_addc_u32 s63, s23, 0
	s_add_i32 s33, s45, s29
	global_load_lds_dwordx4 v136, s[22:23]
	s_mov_b32 m0, s33
	s_add_u32 s100, s26, 0x80
	s_addc_u32 s101, s27, 0
	global_load_lds_dwordx4 v132, s[62:63]
	s_add_i32 m0, s33, 0x2000
	s_nop 0
	global_load_lds_dwordx4 v136, s[62:63]
	s_mov_b32 m0, s21
	s_nop 0
	global_load_lds_dwordx4 v130, s[26:27]
	s_mov_b32 m0, s34
	s_nop 0
	global_load_lds_dwordx4 v134, s[26:27]
	s_waitcnt vmcnt(8)
	s_waitcnt lgkmcnt(0)
	s_barrier
	s_waitcnt lgkmcnt(0)
	v_mfma_f32_16x16x32_bf16 v[58:61], v[160:163], v[194:197], v[58:61]
	v_mfma_f32_16x16x32_bf16 v[58:61], v[166:169], v[198:201], v[58:61]
	v_mfma_f32_16x16x32_bf16 v[42:45], v[166:169], v[206:209], v[42:45]
	v_mfma_f32_16x16x32_bf16 v[42:45], v[160:163], v[202:205], v[42:45]
	v_mfma_f32_16x16x32_bf16 v[26:29], v[160:163], v[210:213], v[26:29]
	v_mfma_f32_16x16x32_bf16 v[26:29], v[166:169], v[214:217], v[26:29]
	v_mfma_f32_16x16x32_bf16 v[10:13], v[166:169], v[222:225], v[10:13]
	v_mfma_f32_16x16x32_bf16 v[10:13], v[160:163], v[218:221], v[10:13]
	v_mfma_f32_16x16x32_bf16 v[2:5], v[170:173], v[218:221], v[2:5]
	v_mfma_f32_16x16x32_bf16 v[2:5], v[174:177], v[222:225], v[2:5]
	v_mfma_f32_16x16x32_bf16 v[18:21], v[174:177], v[214:217], v[18:21]
	v_mfma_f32_16x16x32_bf16 v[18:21], v[170:173], v[210:213], v[18:21]
	v_mfma_f32_16x16x32_bf16 v[34:37], v[170:173], v[202:205], v[34:37]
	v_mfma_f32_16x16x32_bf16 v[34:37], v[174:177], v[206:209], v[34:37]
	v_mfma_f32_16x16x32_bf16 v[50:53], v[174:177], v[198:201], v[50:53]
	v_mfma_f32_16x16x32_bf16 v[50:53], v[170:173], v[194:197], v[50:53]
	v_mfma_f32_16x16x32_bf16 v[66:69], v[178:181], v[194:197], v[66:69]
	v_mfma_f32_16x16x32_bf16 v[66:69], v[182:185], v[198:201], v[66:69]
	v_mfma_f32_16x16x32_bf16 v[46:49], v[182:185], v[206:209], v[46:49]
	v_mfma_f32_16x16x32_bf16 v[46:49], v[178:181], v[202:205], v[46:49]
	v_mfma_f32_16x16x32_bf16 v[30:33], v[178:181], v[210:213], v[30:33]
	v_mfma_f32_16x16x32_bf16 v[30:33], v[182:185], v[214:217], v[30:33]
	v_mfma_f32_16x16x32_bf16 v[14:17], v[182:185], v[222:225], v[14:17]
	v_mfma_f32_16x16x32_bf16 v[14:17], v[178:181], v[218:221], v[14:17]
	v_mfma_f32_16x16x32_bf16 v[6:9], v[186:189], v[218:221], v[6:9]
	v_mfma_f32_16x16x32_bf16 v[6:9], v[190:193], v[222:225], v[6:9]
	v_mfma_f32_16x16x32_bf16 v[22:25], v[190:193], v[214:217], v[22:25]
	v_mfma_f32_16x16x32_bf16 v[22:25], v[186:189], v[210:213], v[22:25]
	v_mfma_f32_16x16x32_bf16 v[38:41], v[186:189], v[202:205], v[38:41]
	v_mfma_f32_16x16x32_bf16 v[38:41], v[190:193], v[206:209], v[38:41]
	v_mfma_f32_16x16x32_bf16 v[54:57], v[190:193], v[198:201], v[54:57]
	v_mfma_f32_16x16x32_bf16 v[54:57], v[186:189], v[194:197], v[54:57]
	s_barrier
; #define PG8_STAGE(bufoff, gbase, voff) do { _Pragma("unroll") for (int _i = 0; _i < 2; ++_i) \
;         __builtin_amdgcn_global_load_lds((const unsigned*)((const char*)(gbase) + (voff)[_i]), (PG8_LAS unsigned*)(lds + (bufoff) + ldsw + _i * 8192), 16, 0, 0); } while (0)
; #define PG8_LDA(dst, b, h) do { _Pragma("unroll") for (int m = 0; m < 4; ++m) _Pragma("unroll") for (int k = 0; k < 2; ++k) dst[m][k] = *(const PG8_LAS bf16x8*)(lds + PG8_SA(b, h) + aoff + m * 2048 + k * 1024); } while (0)
; #define PG8_LDB(dst, b, h) do { _Pragma("unroll") for (int n = 0; n < 2; ++n) _Pragma("unroll") for (int k = 0; k < 2; ++k) dst[n][k] = *(const PG8_LAS bf16x8*)(lds + PG8_SB(b, h) + boff + n * 2048 + k * 1024); } while (0)
; #define PG8_MMA(ai, bj, At, Bt) do { __builtin_amdgcn_s_setprio(1); _Pragma("unroll") for (int m = 0; m < 4; ++m) _Pragma("unroll") for (int n = 0; n < 2; ++n) _Pragma("unroll") for (int k = 0; k < 2; ++k) \
;         acc[ai][bj][m][n] = __builtin_amdgcn_mfma_f32_16x16x32_bf16(Bt[n][k], At[m][k], acc[ai][bj][m][n], 0, 0, 0); __builtin_amdgcn_s_setprio(0); } while (0)
; #define PG8_WAIT_V(n) asm volatile("s_waitcnt vmcnt(" #n ")" ::: "memory")
; #define PG8_WAIT_L(n) asm volatile("s_waitcnt lgkmcnt(" #n ")" ::: "memory")
; #define PG8_BAR __builtin_amdgcn_s_barrier()
; template <class Epi, class Sched, bool ALIGN_EPI = false, bool SP2 = false>
; __device__ __forceinline__ void gemm_phase(PG8_LAS unsigned char* lds, const Gemm g, const Sched& S, const Epi& E) {
;     ...
;         for (int t = 0; t < nt; t += 2) {
;             const bool last = (t == nt - 2);
;             const char* a1 = cA + (size_t)(t + 1) * kstep;
;             const char* a2 = last ? nA : cA + (size_t)(t + 2) * kstep; const char* b2 = last ? nB : cB + (size_t)(t + 2) * kstep;
;             const char* a3 = a2 + kstep; const char* b3 = b2 + kstep;
;     ...
;             PG8_LDB(B0, 1, 0); PG8_LDB(B1, 1, 1); PG8_SCHED; PG8_LDA(At, 1, 0); PG8_STAGE(PG8_SA(0, 1), a2 + hstep, voffA);
;             PG8_WAIT_V(8); PG8_WAIT_L(0); PG8_BAR; PG8_MMA(0, 0, At, B0); PG8_MMA(0, 1, At, B1); PG8_BAR; PG8_SCHED;
;             PG8_LDA(At, 1, 1); PG8_STAGE(PG8_SB(1, 0), b3, voffB); PG8_STAGE(PG8_SB(1, 1), b3 + hstep, voffB); PG8_STAGE(PG8_SA(1, 0), a3, voffA);
;             PG8_WAIT_V(8); PG8_WAIT_L(0); PG8_BAR; PG8_MMA(1, 0, At, B0); PG8_MMA(1, 1, At, B1); PG8_BAR; PG8_SCHED;
	s_add_i32 s33, 0, 0x18000
	s_add_i32 s42, 0, 0x1c000
	ds_read_b128 v[160:163], v241 offset:32768
	ds_read_b128 v[166:169], v241 offset:33792
	ds_read_b128 v[170:173], v241 offset:34816
	ds_read_b128 v[174:177], v241 offset:35840
	ds_read_b128 v[178:181], v241 offset:49152
	ds_read_b128 v[182:185], v241 offset:50176
	ds_read_b128 v[186:189], v241 offset:51200
	ds_read_b128 v[190:193], v241 offset:52224
	s_add_u32 s26, s26, 0x100000
	s_addc_u32 s27, s27, 0
	s_mov_b32 m0, s35
	ds_read_b128 v[194:197], v155 offset:32768
	ds_read_b128 v[198:201], v155 offset:33792
	ds_read_b128 v[202:205], v155 offset:34816
	ds_read_b128 v[206:209], v155 offset:35840
	ds_read_b128 v[210:213], v155 offset:36864
	ds_read_b128 v[214:217], v155 offset:37888
	ds_read_b128 v[218:221], v155 offset:38912
	ds_read_b128 v[222:225], v155 offset:39936
	global_load_lds_dwordx4 v130, s[26:27]
	s_mov_b32 m0, s36
	s_nop 0
	global_load_lds_dwordx4 v134, s[26:27]
	s_waitcnt vmcnt(8)
	s_waitcnt lgkmcnt(0)
	s_barrier
	s_waitcnt lgkmcnt(0)
	v_mfma_f32_16x16x32_bf16 v[122:125], v[160:163], v[194:197], v[122:125]
	v_mfma_f32_16x16x32_bf16 v[122:125], v[166:169], v[198:201], v[122:125]
	v_mfma_f32_16x16x32_bf16 v[106:109], v[166:169], v[206:209], v[106:109]
	v_mfma_f32_16x16x32_bf16 v[106:109], v[160:163], v[202:205], v[106:109]
	v_mfma_f32_16x16x32_bf16 v[90:93], v[160:163], v[210:213], v[90:93]
	v_mfma_f32_16x16x32_bf16 v[90:93], v[166:169], v[214:217], v[90:93]
	v_mfma_f32_16x16x32_bf16 v[74:77], v[166:169], v[222:225], v[74:77]
	v_mfma_f32_16x16x32_bf16 v[74:77], v[160:163], v[218:221], v[74:77]
	v_mfma_f32_16x16x32_bf16 v[62:65], v[170:173], v[218:221], v[62:65]
	v_mfma_f32_16x16x32_bf16 v[62:65], v[174:177], v[222:225], v[62:65]
	v_mfma_f32_16x16x32_bf16 v[82:85], v[174:177], v[214:217], v[82:85]
	v_mfma_f32_16x16x32_bf16 v[82:85], v[170:173], v[210:213], v[82:85]
	v_mfma_f32_16x16x32_bf16 v[98:101], v[170:173], v[202:205], v[98:101]
	v_mfma_f32_16x16x32_bf16 v[98:101], v[174:177], v[206:209], v[98:101]
	v_mfma_f32_16x16x32_bf16 v[114:117], v[174:177], v[198:201], v[114:117]
	v_mfma_f32_16x16x32_bf16 v[114:117], v[170:173], v[194:197], v[114:117]
	v_mfma_f32_16x16x32_bf16 v[126:129], v[178:181], v[194:197], v[126:129]
	v_mfma_f32_16x16x32_bf16 v[126:129], v[182:185], v[198:201], v[126:129]
	v_mfma_f32_16x16x32_bf16 v[110:113], v[182:185], v[206:209], v[110:113]
	v_mfma_f32_16x16x32_bf16 v[110:113], v[178:181], v[202:205], v[110:113]
	v_mfma_f32_16x16x32_bf16 v[94:97], v[178:181], v[210:213], v[94:97]
	v_mfma_f32_16x16x32_bf16 v[94:97], v[182:185], v[214:217], v[94:97]
	v_mfma_f32_16x16x32_bf16 v[78:81], v[182:185], v[222:225], v[78:81]
	v_mfma_f32_16x16x32_bf16 v[78:81], v[178:181], v[218:221], v[78:81]
	v_mfma_f32_16x16x32_bf16 v[70:73], v[186:189], v[218:221], v[70:73]
	v_mfma_f32_16x16x32_bf16 v[70:73], v[190:193], v[222:225], v[70:73]
	v_mfma_f32_16x16x32_bf16 v[86:89], v[190:193], v[214:217], v[86:89]
	v_mfma_f32_16x16x32_bf16 v[86:89], v[186:189], v[210:213], v[86:89]
	v_mfma_f32_16x16x32_bf16 v[102:105], v[186:189], v[202:205], v[102:105]
	v_mfma_f32_16x16x32_bf16 v[102:105], v[190:193], v[206:209], v[102:105]
	v_mfma_f32_16x16x32_bf16 v[118:121], v[190:193], v[198:201], v[118:121]
	v_mfma_f32_16x16x32_bf16 v[118:121], v[186:189], v[194:197], v[118:121]
	s_barrier
	s_add_i32 s26, s33, s29
	s_add_i32 m0, s26, 0xffffff80
	ds_read_b128 v[194:197], v155 offset:49152
	ds_read_b128 v[198:201], v155 offset:50176
	ds_read_b128 v[202:205], v155 offset:51200
	ds_read_b128 v[206:209], v155 offset:52224
	ds_read_b128 v[210:213], v155 offset:53248
	ds_read_b128 v[214:217], v155 offset:54272
	ds_read_b128 v[218:221], v155 offset:55296
	ds_read_b128 v[222:225], v155 offset:56320
	global_load_lds_dwordx4 v132, s[22:23] offset:128
	s_add_i32 m0, s26, 0x1f80
	s_add_i32 s26, s42, s29
	global_load_lds_dwordx4 v136, s[22:23] offset:128
	s_add_u32 s22, s22, 0x100080
	s_addc_u32 s23, s23, 0
	s_mov_b32 m0, s26
	s_nop 0
	global_load_lds_dwordx4 v132, s[22:23]
	s_add_i32 m0, s26, 0x2000
	s_nop 0
	global_load_lds_dwordx4 v136, s[22:23]
	s_mov_b32 m0, s41
	s_nop 0
	global_load_lds_dwordx4 v130, s[100:101]
	s_mov_b32 m0, s43
	s_nop 0
	global_load_lds_dwordx4 v134, s[100:101]
	s_waitcnt vmcnt(8)
	s_waitcnt lgkmcnt(0)
	s_barrier
	s_waitcnt lgkmcnt(0)
	v_mfma_f32_16x16x32_bf16 v[58:61], v[160:163], v[194:197], v[58:61]
	v_mfma_f32_16x16x32_bf16 v[58:61], v[166:169], v[198:201], v[58:61]
	v_mfma_f32_16x16x32_bf16 v[42:45], v[166:169], v[206:209], v[42:45]
	v_mfma_f32_16x16x32_bf16 v[42:45], v[160:163], v[202:205], v[42:45]
	v_mfma_f32_16x16x32_bf16 v[26:29], v[160:163], v[210:213], v[26:29]
	v_mfma_f32_16x16x32_bf16 v[26:29], v[166:169], v[214:217], v[26:29]
	v_mfma_f32_16x16x32_bf16 v[10:13], v[166:169], v[222:225], v[10:13]
	v_mfma_f32_16x16x32_bf16 v[10:13], v[160:163], v[218:221], v[10:13]
	v_mfma_f32_16x16x32_bf16 v[2:5], v[170:173], v[218:221], v[2:5]
	v_mfma_f32_16x16x32_bf16 v[2:5], v[174:177], v[222:225], v[2:5]
	v_mfma_f32_16x16x32_bf16 v[18:21], v[174:177], v[214:217], v[18:21]
	v_mfma_f32_16x16x32_bf16 v[18:21], v[170:173], v[210:213], v[18:21]
	v_mfma_f32_16x16x32_bf16 v[34:37], v[170:173], v[202:205], v[34:37]
	v_mfma_f32_16x16x32_bf16 v[34:37], v[174:177], v[206:209], v[34:37]
	v_mfma_f32_16x16x32_bf16 v[50:53], v[174:177], v[198:201], v[50:53]
	v_mfma_f32_16x16x32_bf16 v[50:53], v[170:173], v[194:197], v[50:53]
	v_mfma_f32_16x16x32_bf16 v[66:69], v[178:181], v[194:197], v[66:69]
	v_mfma_f32_16x16x32_bf16 v[66:69], v[182:185], v[198:201], v[66:69]
	v_mfma_f32_16x16x32_bf16 v[46:49], v[182:185], v[206:209], v[46:49]
	v_mfma_f32_16x16x32_bf16 v[46:49], v[178:181], v[202:205], v[46:49]
	v_mfma_f32_16x16x32_bf16 v[30:33], v[178:181], v[210:213], v[30:33]
	v_mfma_f32_16x16x32_bf16 v[30:33], v[182:185], v[214:217], v[30:33]
	v_mfma_f32_16x16x32_bf16 v[14:17], v[182:185], v[222:225], v[14:17]
	v_mfma_f32_16x16x32_bf16 v[14:17], v[178:181], v[218:221], v[14:17]
	v_mfma_f32_16x16x32_bf16 v[6:9], v[186:189], v[218:221], v[6:9]
	v_mfma_f32_16x16x32_bf16 v[6:9], v[190:193], v[222:225], v[6:9]
	v_mfma_f32_16x16x32_bf16 v[22:25], v[190:193], v[214:217], v[22:25]
	v_mfma_f32_16x16x32_bf16 v[22:25], v[186:189], v[210:213], v[22:25]
	v_mfma_f32_16x16x32_bf16 v[38:41], v[186:189], v[202:205], v[38:41]
	v_mfma_f32_16x16x32_bf16 v[38:41], v[190:193], v[206:209], v[38:41]
	v_mfma_f32_16x16x32_bf16 v[54:57], v[190:193], v[198:201], v[54:57]
	v_mfma_f32_16x16x32_bf16 v[54:57], v[186:189], v[194:197], v[54:57]
	s_barrier
	s_add_i32 s52, s52, 2
	s_add_u32 s24, s24, 0x100
	s_addc_u32 s25, s25, 0
	s_add_u32 s50, s50, 0x100
	s_addc_u32 s51, s51, 0
	s_cmp_gt_u32 s52, 61
	s_cbranch_scc0 .LBB0_1681
	s_and_b64 vcc, exec, s[8:9]
	s_cbranch_vccz .LBB0_1684
	s_barrier

; #define PG8_STAGE(bufoff, gbase, voff) do { _Pragma("unroll") for (int _i = 0; _i < 2; ++_i) \
;         __builtin_amdgcn_global_load_lds((const unsigned*)((const char*)(gbase) + (voff)[_i]), (PG8_LAS unsigned*)(lds + (bufoff) + ldsw + _i * 8192), 16, 0, 0); } while (0)
; #define PG8_LDA(dst, b, h) do { _Pragma("unroll") for (int m = 0; m < 4; ++m) _Pragma("unroll") for (int k = 0; k < 2; ++k) dst[m][k] = *(const PG8_LAS bf16x8*)(lds + PG8_SA(b, h) + aoff + m * 2048 + k * 1024); } while (0)
; #define PG8_LDB(dst, b, h) do { _Pragma("unroll") for (int n = 0; n < 2; ++n) _Pragma("unroll") for (int k = 0; k < 2; ++k) dst[n][k] = *(const PG8_LAS bf16x8*)(lds + PG8_SB(b, h) + boff + n * 2048 + k * 1024); } while (0)
; #define PG8_MMA(ai, bj, At, Bt) do { __builtin_amdgcn_s_setprio(1); _Pragma("unroll") for (int m = 0; m < 4; ++m) _Pragma("unroll") for (int n = 0; n < 2; ++n) _Pragma("unroll") for (int k = 0; k < 2; ++k) \
;         acc[ai][bj][m][n] = __builtin_amdgcn_mfma_f32_16x16x32_bf16(Bt[n][k], At[m][k], acc[ai][bj][m][n], 0, 0, 0); __builtin_amdgcn_s_setprio(0); } while (0)
; #define PG8_WAIT_V(n) asm volatile("s_waitcnt vmcnt(" #n ")" ::: "memory")
; #define PG8_WAIT_L(n) asm volatile("s_waitcnt lgkmcnt(" #n ")" ::: "memory")
; #define PG8_BAR __builtin_amdgcn_s_barrier()
; #define PG8_SCHED __builtin_amdgcn_sched_barrier(0)
; template <class Epi, class Sched, bool ALIGN_EPI = false, bool SP2 = false>
; __device__ __forceinline__ void gemm_phase(PG8_LAS unsigned char* lds, const Gemm g, const Sched& S, const Epi& E) {
;     ...
;             PG8_LDB(B0, 0, 0); PG8_LDB(B1, 0, 1); PG8_SCHED; PG8_LDA(At, 0, 0); PG8_STAGE(PG8_SA(1, 1), a1 + hstep, voffA);
;             PG8_WAIT_V(8); PG8_WAIT_L(0); PG8_BAR; PG8_MMA(0, 0, At, B0); PG8_MMA(0, 1, At, B1); PG8_BAR; PG8_SCHED;
;             PG8_LDA(At, 0, 1); PG8_STAGE(PG8_SB(0, 0), b2, voffB); PG8_STAGE(PG8_SB(0, 1), b2 + hstep, voffB); PG8_STAGE(PG8_SA(0, 0), a2, voffA);
;             PG8_WAIT_V(8); PG8_WAIT_L(0); PG8_BAR; PG8_MMA(1, 0, At, B0); PG8_MMA(1, 1, At, B1); PG8_BAR; PG8_SCHED;
.LBB0_1801:
	ds_read_b128 v[130:133], v241 offset:0
	ds_read_b128 v[134:137], v241 offset:1024
	ds_read_b128 v[138:141], v241 offset:2048
	ds_read_b128 v[142:145], v241 offset:3072
	ds_read_b128 v[146:149], v241 offset:16384
	ds_read_b128 v[150:153], v241 offset:17408
	ds_read_b128 v[170:173], v241 offset:18432
	ds_read_b128 v[174:177], v241 offset:19456
	s_add_u32 s16, s18, 0xffd50080
	s_addc_u32 s17, s19, -1
	s_cmpk_eq_i32 s48, 0xa8
	s_cselect_b32 s21, s5, s17
	s_cselect_b32 s20, s4, s16
	s_cselect_b32 s17, s15, s47
	s_cselect_b32 s16, s14, s46
	s_add_i32 m0, s25, 0xc000
	ds_read_b128 v[178:181], v184
	ds_read_b128 v[186:189], v184 offset:1024
	ds_read_b128 v[190:193], v184 offset:2048
	ds_read_b128 v[194:197], v184 offset:3072
	ds_read_b128 v[198:201], v184 offset:4096
	ds_read_b128 v[202:205], v184 offset:5120
	ds_read_b128 v[206:209], v184 offset:6144
	ds_read_b128 v[210:213], v184 offset:7168
	global_load_lds_dwordx4 v0, s[18:19]
	s_add_i32 m0, s25, 0xe000
	s_nop 0
	global_load_lds_dwordx4 v162, s[18:19]
	s_waitcnt vmcnt(8)
	s_waitcnt lgkmcnt(0)
	s_barrier
	s_waitcnt lgkmcnt(0)
	v_mfma_f32_16x16x32_bf16 v[114:117], v[130:133], v[178:181], v[114:117]
	v_mfma_f32_16x16x32_bf16 v[114:117], v[134:137], v[186:189], v[114:117]
	v_mfma_f32_16x16x32_bf16 v[106:109], v[134:137], v[194:197], v[106:109]
	v_mfma_f32_16x16x32_bf16 v[106:109], v[130:133], v[190:193], v[106:109]
	v_mfma_f32_16x16x32_bf16 v[90:93], v[130:133], v[198:201], v[90:93]
	v_mfma_f32_16x16x32_bf16 v[90:93], v[134:137], v[202:205], v[90:93]
	v_mfma_f32_16x16x32_bf16 v[74:77], v[134:137], v[210:213], v[74:77]
	v_mfma_f32_16x16x32_bf16 v[74:77], v[130:133], v[206:209], v[74:77]
	v_mfma_f32_16x16x32_bf16 v[66:69], v[138:141], v[206:209], v[66:69]
	v_mfma_f32_16x16x32_bf16 v[66:69], v[142:145], v[210:213], v[66:69]
	v_mfma_f32_16x16x32_bf16 v[82:85], v[142:145], v[202:205], v[82:85]
	v_mfma_f32_16x16x32_bf16 v[82:85], v[138:141], v[198:201], v[82:85]
	v_mfma_f32_16x16x32_bf16 v[98:101], v[138:141], v[190:193], v[98:101]
	v_mfma_f32_16x16x32_bf16 v[98:101], v[142:145], v[194:197], v[98:101]
	v_mfma_f32_16x16x32_bf16 v[118:121], v[142:145], v[186:189], v[118:121]
	v_mfma_f32_16x16x32_bf16 v[118:121], v[138:141], v[178:181], v[118:121]
	v_mfma_f32_16x16x32_bf16 v[122:125], v[146:149], v[178:181], v[122:125]
	v_mfma_f32_16x16x32_bf16 v[122:125], v[150:153], v[186:189], v[122:125]
	v_mfma_f32_16x16x32_bf16 v[110:113], v[150:153], v[194:197], v[110:113]
	v_mfma_f32_16x16x32_bf16 v[110:113], v[146:149], v[190:193], v[110:113]
	v_mfma_f32_16x16x32_bf16 v[94:97], v[146:149], v[198:201], v[94:97]
	v_mfma_f32_16x16x32_bf16 v[94:97], v[150:153], v[202:205], v[94:97]
	v_mfma_f32_16x16x32_bf16 v[78:81], v[150:153], v[210:213], v[78:81]
	v_mfma_f32_16x16x32_bf16 v[78:81], v[146:149], v[206:209], v[78:81]
	v_mfma_f32_16x16x32_bf16 v[70:73], v[170:173], v[206:209], v[70:73]
	v_mfma_f32_16x16x32_bf16 v[70:73], v[174:177], v[210:213], v[70:73]
	v_mfma_f32_16x16x32_bf16 v[86:89], v[174:177], v[202:205], v[86:89]
	v_mfma_f32_16x16x32_bf16 v[86:89], v[170:173], v[198:201], v[86:89]
	v_mfma_f32_16x16x32_bf16 v[102:105], v[170:173], v[190:193], v[102:105]
	v_mfma_f32_16x16x32_bf16 v[102:105], v[174:177], v[194:197], v[102:105]
	v_mfma_f32_16x16x32_bf16 v[126:129], v[174:177], v[186:189], v[126:129]
	v_mfma_f32_16x16x32_bf16 v[126:129], v[170:173], v[178:181], v[126:129]
	s_barrier
	s_add_i32 s33, s36, s24
	s_mov_b32 m0, s33
	ds_read_b128 v[178:181], v184 offset:16384
	ds_read_b128 v[186:189], v184 offset:17408
	ds_read_b128 v[190:193], v184 offset:18432
	ds_read_b128 v[194:197], v184 offset:19456
	ds_read_b128 v[198:201], v184 offset:20480
	ds_read_b128 v[202:205], v184 offset:21504
	ds_read_b128 v[206:209], v184 offset:22528
	ds_read_b128 v[210:213], v184 offset:23552
	global_load_lds_dwordx4 v156, s[16:17]
	s_add_i32 m0, s33, 0x2000
	s_add_u32 s50, s16, 0x2b0000
	s_addc_u32 s51, s17, 0
	s_add_i32 s33, s37, s24
	global_load_lds_dwordx4 v160, s[16:17]
	s_mov_b32 m0, s33
	s_add_u32 s100, s20, 0x80
	s_addc_u32 s101, s21, 0
	global_load_lds_dwordx4 v156, s[50:51]
	s_add_i32 m0, s33, 0x2000
	s_nop 0
	global_load_lds_dwordx4 v160, s[50:51]
	s_mov_b32 m0, s25
	s_nop 0
	global_load_lds_dwordx4 v154, s[20:21]
	s_mov_b32 m0, s26
	s_nop 0
	global_load_lds_dwordx4 v158, s[20:21]
	s_waitcnt vmcnt(8)
	s_waitcnt lgkmcnt(0)
	s_barrier
	s_waitcnt lgkmcnt(0)
	v_mfma_f32_16x16x32_bf16 v[58:61], v[130:133], v[178:181], v[58:61]
	v_mfma_f32_16x16x32_bf16 v[58:61], v[134:137], v[186:189], v[58:61]
	v_mfma_f32_16x16x32_bf16 v[42:45], v[134:137], v[194:197], v[42:45]
	v_mfma_f32_16x16x32_bf16 v[42:45], v[130:133], v[190:193], v[42:45]
	v_mfma_f32_16x16x32_bf16 v[26:29], v[130:133], v[198:201], v[26:29]
	v_mfma_f32_16x16x32_bf16 v[26:29], v[134:137], v[202:205], v[26:29]
	v_mfma_f32_16x16x32_bf16 v[6:9], v[134:137], v[210:213], v[6:9]
	v_mfma_f32_16x16x32_bf16 v[6:9], v[130:133], v[206:209], v[6:9]
	v_mfma_f32_16x16x32_bf16 v[2:5], v[138:141], v[206:209], v[2:5]
	v_mfma_f32_16x16x32_bf16 v[2:5], v[142:145], v[210:213], v[2:5]
	v_mfma_f32_16x16x32_bf16 v[18:21], v[142:145], v[202:205], v[18:21]
	v_mfma_f32_16x16x32_bf16 v[18:21], v[138:141], v[198:201], v[18:21]
	v_mfma_f32_16x16x32_bf16 v[34:37], v[138:141], v[190:193], v[34:37]
	v_mfma_f32_16x16x32_bf16 v[34:37], v[142:145], v[194:197], v[34:37]
	v_mfma_f32_16x16x32_bf16 v[54:57], v[142:145], v[186:189], v[54:57]
	v_mfma_f32_16x16x32_bf16 v[54:57], v[138:141], v[178:181], v[54:57]
	v_mfma_f32_16x16x32_bf16 v[62:65], v[146:149], v[178:181], v[62:65]
	v_mfma_f32_16x16x32_bf16 v[62:65], v[150:153], v[186:189], v[62:65]
	v_mfma_f32_16x16x32_bf16 v[46:49], v[150:153], v[194:197], v[46:49]
	v_mfma_f32_16x16x32_bf16 v[46:49], v[146:149], v[190:193], v[46:49]
	v_mfma_f32_16x16x32_bf16 v[30:33], v[146:149], v[198:201], v[30:33]
	v_mfma_f32_16x16x32_bf16 v[30:33], v[150:153], v[202:205], v[30:33]
	v_mfma_f32_16x16x32_bf16 v[10:13], v[150:153], v[210:213], v[10:13]
	v_mfma_f32_16x16x32_bf16 v[10:13], v[146:149], v[206:209], v[10:13]
	v_mfma_f32_16x16x32_bf16 v[14:17], v[170:173], v[206:209], v[14:17]
	v_mfma_f32_16x16x32_bf16 v[14:17], v[174:177], v[210:213], v[14:17]
	v_mfma_f32_16x16x32_bf16 v[22:25], v[174:177], v[202:205], v[22:25]
	v_mfma_f32_16x16x32_bf16 v[22:25], v[170:173], v[198:201], v[22:25]
	v_mfma_f32_16x16x32_bf16 v[38:41], v[170:173], v[190:193], v[38:41]
	v_mfma_f32_16x16x32_bf16 v[38:41], v[174:177], v[194:197], v[38:41]
	v_mfma_f32_16x16x32_bf16 v[50:53], v[174:177], v[186:189], v[50:53]
	v_mfma_f32_16x16x32_bf16 v[50:53], v[170:173], v[178:181], v[50:53]
	s_barrier
; #define PG8_STAGE(bufoff, gbase, voff) do { _Pragma("unroll") for (int _i = 0; _i < 2; ++_i) \
;         __builtin_amdgcn_global_load_lds((const unsigned*)((const char*)(gbase) + (voff)[_i]), (PG8_LAS unsigned*)(lds + (bufoff) + ldsw + _i * 8192), 16, 0, 0); } while (0)
; #define PG8_LDA(dst, b, h) do { _Pragma("unroll") for (int m = 0; m < 4; ++m) _Pragma("unroll") for (int k = 0; k < 2; ++k) dst[m][k] = *(const PG8_LAS bf16x8*)(lds + PG8_SA(b, h) + aoff + m * 2048 + k * 1024); } while (0)
; #define PG8_LDB(dst, b, h) do { _Pragma("unroll") for (int n = 0; n < 2; ++n) _Pragma("unroll") for (int k = 0; k < 2; ++k) dst[n][k] = *(const PG8_LAS bf16x8*)(lds + PG8_SB(b, h) + boff + n * 2048 + k * 1024); } while (0)
; #define PG8_MMA(ai, bj, At, Bt) do { __builtin_amdgcn_s_setprio(1); _Pragma("unroll") for (int m = 0; m < 4; ++m) _Pragma("unroll") for (int n = 0; n < 2; ++n) _Pragma("unroll") for (int k = 0; k < 2; ++k) \
;         acc[ai][bj][m][n] = __builtin_amdgcn_mfma_f32_16x16x32_bf16(Bt[n][k], At[m][k], acc[ai][bj][m][n], 0, 0, 0); __builtin_amdgcn_s_setprio(0); } while (0)
; #define PG8_WAIT_V(n) asm volatile("s_waitcnt vmcnt(" #n ")" ::: "memory")
; #define PG8_WAIT_L(n) asm volatile("s_waitcnt lgkmcnt(" #n ")" ::: "memory")
; #define PG8_BAR __builtin_amdgcn_s_barrier()
; template <class Epi, class Sched, bool ALIGN_EPI = false, bool SP2 = false>
; __device__ __forceinline__ void gemm_phase(PG8_LAS unsigned char* lds, const Gemm g, const Sched& S, const Epi& E) {
;     ...
;         for (int t = 0; t < nt; t += 2) {
;             const bool last = (t == nt - 2);
;             const char* a1 = cA + (size_t)(t + 1) * kstep;
;             const char* a2 = last ? nA : cA + (size_t)(t + 2) * kstep; const char* b2 = last ? nB : cB + (size_t)(t + 2) * kstep;
;             const char* a3 = a2 + kstep; const char* b3 = b2 + kstep;
;     ...
;             PG8_LDB(B0, 1, 0); PG8_LDB(B1, 1, 1); PG8_SCHED; PG8_LDA(At, 1, 0); PG8_STAGE(PG8_SA(0, 1), a2 + hstep, voffA);
;             PG8_WAIT_V(8); PG8_WAIT_L(0); PG8_BAR; PG8_MMA(0, 0, At, B0); PG8_MMA(0, 1, At, B1); PG8_BAR; PG8_SCHED;
;             PG8_LDA(At, 1, 1); PG8_STAGE(PG8_SB(1, 0), b3, voffB); PG8_STAGE(PG8_SB(1, 1), b3 + hstep, voffB); PG8_STAGE(PG8_SA(1, 0), a3, voffA);
;             PG8_WAIT_V(8); PG8_WAIT_L(0); PG8_BAR; PG8_MMA(1, 0, At, B0); PG8_MMA(1, 1, At, B1); PG8_BAR; PG8_SCHED;
	s_add_i32 s33, 0, 0x18000
	s_add_i32 s42, 0, 0x1c000
	ds_read_b128 v[130:133], v241 offset:32768
	ds_read_b128 v[134:137], v241 offset:33792
	ds_read_b128 v[138:141], v241 offset:34816
	ds_read_b128 v[142:145], v241 offset:35840
	ds_read_b128 v[146:149], v241 offset:49152
	ds_read_b128 v[150:153], v241 offset:50176
	ds_read_b128 v[170:173], v241 offset:51200
	ds_read_b128 v[174:177], v241 offset:52224
	s_add_u32 s20, s20, 0x2b0000
	s_addc_u32 s21, s21, 0
	s_mov_b32 m0, s27
	ds_read_b128 v[178:181], v184 offset:32768
	ds_read_b128 v[186:189], v184 offset:33792
	ds_read_b128 v[190:193], v184 offset:34816
	ds_read_b128 v[194:197], v184 offset:35840
	ds_read_b128 v[198:201], v184 offset:36864
	ds_read_b128 v[202:205], v184 offset:37888
	ds_read_b128 v[206:209], v184 offset:38912
	ds_read_b128 v[210:213], v184 offset:39936
	global_load_lds_dwordx4 v154, s[20:21]
	s_mov_b32 m0, s28
	s_nop 0
	global_load_lds_dwordx4 v158, s[20:21]
	s_waitcnt vmcnt(8)
	s_waitcnt lgkmcnt(0)
	s_barrier
	s_waitcnt lgkmcnt(0)
	v_mfma_f32_16x16x32_bf16 v[114:117], v[130:133], v[178:181], v[114:117]
	v_mfma_f32_16x16x32_bf16 v[114:117], v[134:137], v[186:189], v[114:117]
	v_mfma_f32_16x16x32_bf16 v[106:109], v[134:137], v[194:197], v[106:109]
	v_mfma_f32_16x16x32_bf16 v[106:109], v[130:133], v[190:193], v[106:109]
	v_mfma_f32_16x16x32_bf16 v[90:93], v[130:133], v[198:201], v[90:93]
	v_mfma_f32_16x16x32_bf16 v[90:93], v[134:137], v[202:205], v[90:93]
	v_mfma_f32_16x16x32_bf16 v[74:77], v[134:137], v[210:213], v[74:77]
	v_mfma_f32_16x16x32_bf16 v[74:77], v[130:133], v[206:209], v[74:77]
	v_mfma_f32_16x16x32_bf16 v[66:69], v[138:141], v[206:209], v[66:69]
	v_mfma_f32_16x16x32_bf16 v[66:69], v[142:145], v[210:213], v[66:69]
	v_mfma_f32_16x16x32_bf16 v[82:85], v[142:145], v[202:205], v[82:85]
	v_mfma_f32_16x16x32_bf16 v[82:85], v[138:141], v[198:201], v[82:85]
	v_mfma_f32_16x16x32_bf16 v[98:101], v[138:141], v[190:193], v[98:101]
	v_mfma_f32_16x16x32_bf16 v[98:101], v[142:145], v[194:197], v[98:101]
	v_mfma_f32_16x16x32_bf16 v[118:121], v[142:145], v[186:189], v[118:121]
	v_mfma_f32_16x16x32_bf16 v[118:121], v[138:141], v[178:181], v[118:121]
	v_mfma_f32_16x16x32_bf16 v[122:125], v[146:149], v[178:181], v[122:125]
	v_mfma_f32_16x16x32_bf16 v[122:125], v[150:153], v[186:189], v[122:125]
	v_mfma_f32_16x16x32_bf16 v[110:113], v[150:153], v[194:197], v[110:113]
	v_mfma_f32_16x16x32_bf16 v[110:113], v[146:149], v[190:193], v[110:113]
	v_mfma_f32_16x16x32_bf16 v[94:97], v[146:149], v[198:201], v[94:97]
	v_mfma_f32_16x16x32_bf16 v[94:97], v[150:153], v[202:205], v[94:97]
	v_mfma_f32_16x16x32_bf16 v[78:81], v[150:153], v[210:213], v[78:81]
	v_mfma_f32_16x16x32_bf16 v[78:81], v[146:149], v[206:209], v[78:81]
	v_mfma_f32_16x16x32_bf16 v[70:73], v[170:173], v[206:209], v[70:73]
	v_mfma_f32_16x16x32_bf16 v[70:73], v[174:177], v[210:213], v[70:73]
	v_mfma_f32_16x16x32_bf16 v[86:89], v[174:177], v[202:205], v[86:89]
	v_mfma_f32_16x16x32_bf16 v[86:89], v[170:173], v[198:201], v[86:89]
	v_mfma_f32_16x16x32_bf16 v[102:105], v[170:173], v[190:193], v[102:105]
	v_mfma_f32_16x16x32_bf16 v[102:105], v[174:177], v[194:197], v[102:105]
	v_mfma_f32_16x16x32_bf16 v[126:129], v[174:177], v[186:189], v[126:129]
	v_mfma_f32_16x16x32_bf16 v[126:129], v[170:173], v[178:181], v[126:129]
	s_barrier
	s_add_i32 s20, s33, s24
	s_add_i32 m0, s20, 0xffffff80
	ds_read_b128 v[178:181], v184 offset:49152
	ds_read_b128 v[186:189], v184 offset:50176
	ds_read_b128 v[190:193], v184 offset:51200
	ds_read_b128 v[194:197], v184 offset:52224
	ds_read_b128 v[198:201], v184 offset:53248
	ds_read_b128 v[202:205], v184 offset:54272
	ds_read_b128 v[206:209], v184 offset:55296
	ds_read_b128 v[210:213], v184 offset:56320
	global_load_lds_dwordx4 v156, s[16:17] offset:128
	s_add_i32 m0, s20, 0x1f80
	s_add_i32 s20, s42, s24
	global_load_lds_dwordx4 v160, s[16:17] offset:128
	s_add_u32 s16, s16, 0x2b0080
	s_addc_u32 s17, s17, 0
	s_mov_b32 m0, s20
	s_nop 0
	global_load_lds_dwordx4 v156, s[16:17]
	s_add_i32 m0, s20, 0x2000
	s_nop 0
	global_load_lds_dwordx4 v160, s[16:17]
	s_mov_b32 m0, s30
	s_nop 0
	global_load_lds_dwordx4 v154, s[100:101]
	s_mov_b32 m0, s31
	s_nop 0
	global_load_lds_dwordx4 v158, s[100:101]
	s_waitcnt vmcnt(8)
	s_waitcnt lgkmcnt(0)
	s_barrier
	s_waitcnt lgkmcnt(0)
	v_mfma_f32_16x16x32_bf16 v[58:61], v[130:133], v[178:181], v[58:61]
	v_mfma_f32_16x16x32_bf16 v[58:61], v[134:137], v[186:189], v[58:61]
	v_mfma_f32_16x16x32_bf16 v[42:45], v[134:137], v[194:197], v[42:45]
	v_mfma_f32_16x16x32_bf16 v[42:45], v[130:133], v[190:193], v[42:45]
	v_mfma_f32_16x16x32_bf16 v[26:29], v[130:133], v[198:201], v[26:29]
	v_mfma_f32_16x16x32_bf16 v[26:29], v[134:137], v[202:205], v[26:29]
	v_mfma_f32_16x16x32_bf16 v[6:9], v[134:137], v[210:213], v[6:9]
	v_mfma_f32_16x16x32_bf16 v[6:9], v[130:133], v[206:209], v[6:9]
	v_mfma_f32_16x16x32_bf16 v[2:5], v[138:141], v[206:209], v[2:5]
	v_mfma_f32_16x16x32_bf16 v[2:5], v[142:145], v[210:213], v[2:5]
	v_mfma_f32_16x16x32_bf16 v[18:21], v[142:145], v[202:205], v[18:21]
	v_mfma_f32_16x16x32_bf16 v[18:21], v[138:141], v[198:201], v[18:21]
	v_mfma_f32_16x16x32_bf16 v[34:37], v[138:141], v[190:193], v[34:37]
	v_mfma_f32_16x16x32_bf16 v[34:37], v[142:145], v[194:197], v[34:37]
	v_mfma_f32_16x16x32_bf16 v[54:57], v[142:145], v[186:189], v[54:57]
	v_mfma_f32_16x16x32_bf16 v[54:57], v[138:141], v[178:181], v[54:57]
	v_mfma_f32_16x16x32_bf16 v[62:65], v[146:149], v[178:181], v[62:65]
	v_mfma_f32_16x16x32_bf16 v[62:65], v[150:153], v[186:189], v[62:65]
	v_mfma_f32_16x16x32_bf16 v[46:49], v[150:153], v[194:197], v[46:49]
	v_mfma_f32_16x16x32_bf16 v[46:49], v[146:149], v[190:193], v[46:49]
	v_mfma_f32_16x16x32_bf16 v[30:33], v[146:149], v[198:201], v[30:33]
	v_mfma_f32_16x16x32_bf16 v[30:33], v[150:153], v[202:205], v[30:33]
	v_mfma_f32_16x16x32_bf16 v[10:13], v[150:153], v[210:213], v[10:13]
	v_mfma_f32_16x16x32_bf16 v[10:13], v[146:149], v[206:209], v[10:13]
	v_mfma_f32_16x16x32_bf16 v[14:17], v[170:173], v[206:209], v[14:17]
	v_mfma_f32_16x16x32_bf16 v[14:17], v[174:177], v[210:213], v[14:17]
	v_mfma_f32_16x16x32_bf16 v[22:25], v[174:177], v[202:205], v[22:25]
	v_mfma_f32_16x16x32_bf16 v[22:25], v[170:173], v[198:201], v[22:25]
	v_mfma_f32_16x16x32_bf16 v[38:41], v[170:173], v[190:193], v[38:41]
	v_mfma_f32_16x16x32_bf16 v[38:41], v[174:177], v[194:197], v[38:41]
	v_mfma_f32_16x16x32_bf16 v[50:53], v[174:177], v[186:189], v[50:53]
	v_mfma_f32_16x16x32_bf16 v[50:53], v[170:173], v[178:181], v[50:53]
	s_barrier
	s_add_i32 s48, s48, 2
	s_add_u32 s18, s18, 0x100
	s_addc_u32 s19, s19, 0
	s_add_u32 s46, s46, 0x100
	s_addc_u32 s47, s47, 0
	s_cmpk_gt_u32 s48, 0xa9
	s_cbranch_scc0 .LBB0_1801
	s_and_b64 vcc, exec, s[12:13]
	s_cbranch_vccz .LBB0_1804
	s_barrier
